# rec scan: same-accumulator MFMA pairs back-to-back with fragment sharing across pairs
# baseline (speedup 1.0000x reference)
.Lrec2_loopA_d0:
	ds_read_b128 v[198:201], v130 offset:0
	ds_read_b128 v[214:217], v130 offset:576
	ds_read_b128 v[202:205], v131 offset:0
	ds_read_b128 v[218:221], v131 offset:576
	ds_read_b128 v[206:209], v130 offset:144
	ds_read_b128 v[222:225], v130 offset:720
	ds_read_b128 v[210:213], v131 offset:144
	s_waitcnt lgkmcnt(14)
	ds_read_b128 v[226:229], v131 offset:720
	s_waitcnt lgkmcnt(4)
	v_mfma_f32_16x16x32_bf16 v[100:103], v[198:201], v[20:23], v[12:15]
	v_mfma_f32_16x16x32_bf16 v[100:103], v[202:205], v[24:27], v[100:103]
	v_mfma_f32_16x16x32_bf16 v[104:107], v[198:201], v[52:55], v[16:19]
	v_mfma_f32_16x16x32_bf16 v[104:107], v[202:205], v[56:59], v[104:107]
	v_mfma_f32_16x16x32_bf16 v[108:111], v[198:201], v[84:87], v[242:245]
	v_mfma_f32_16x16x32_bf16 v[112:115], v[214:217], v[20:23], v[12:15]
	v_mfma_f32_16x16x32_bf16 v[112:115], v[218:221], v[24:27], v[112:115]
	v_mfma_f32_16x16x32_bf16 v[138:141], v[214:217], v[52:55], v[16:19]
	v_mfma_f32_16x16x32_bf16 v[138:141], v[218:221], v[56:59], v[138:141]
	v_mfma_f32_16x16x32_bf16 v[142:145], v[214:217], v[84:87], v[242:245]
	ds_read_b128 v[198:201], v130 offset:288
	ds_read_b128 v[214:217], v130 offset:864
	ds_read_b128 v[202:205], v131 offset:288
	ds_read_b128 v[218:221], v131 offset:864
	s_waitcnt lgkmcnt(4)
	v_mfma_f32_16x16x32_bf16 v[100:103], v[206:209], v[28:31], v[100:103]
	v_mfma_f32_16x16x32_bf16 v[100:103], v[210:213], v[32:35], v[100:103]
	v_mfma_f32_16x16x32_bf16 v[104:107], v[210:213], v[64:67], v[104:107]
	v_mfma_f32_16x16x32_bf16 v[104:107], v[206:209], v[60:63], v[104:107]
	v_mfma_f32_16x16x32_bf16 v[108:111], v[206:209], v[88:91], v[108:111]
	v_mfma_f32_16x16x32_bf16 v[112:115], v[222:225], v[28:31], v[112:115]
	v_mfma_f32_16x16x32_bf16 v[112:115], v[226:229], v[32:35], v[112:115]
	v_mfma_f32_16x16x32_bf16 v[138:141], v[226:229], v[64:67], v[138:141]
	v_mfma_f32_16x16x32_bf16 v[138:141], v[222:225], v[60:63], v[138:141]
	v_mfma_f32_16x16x32_bf16 v[142:145], v[222:225], v[88:91], v[142:145]
	ds_read_b128 v[206:209], v130 offset:432
	ds_read_b128 v[222:225], v130 offset:1008
	ds_read_b128 v[210:213], v131 offset:432
	ds_read_b128 v[226:229], v131 offset:1008
	s_waitcnt lgkmcnt(4)
	v_mfma_f32_16x16x32_bf16 v[100:103], v[198:201], v[36:39], v[100:103]
	v_mfma_f32_16x16x32_bf16 v[100:103], v[202:205], v[40:43], v[100:103]
	v_mfma_f32_16x16x32_bf16 v[104:107], v[202:205], v[72:75], v[104:107]
	v_mfma_f32_16x16x32_bf16 v[104:107], v[198:201], v[68:71], v[104:107]
	v_mfma_f32_16x16x32_bf16 v[108:111], v[198:201], v[92:95], v[108:111]
	v_mfma_f32_16x16x32_bf16 v[112:115], v[214:217], v[36:39], v[112:115]
	v_mfma_f32_16x16x32_bf16 v[112:115], v[218:221], v[40:43], v[112:115]
	v_mfma_f32_16x16x32_bf16 v[138:141], v[218:221], v[72:75], v[138:141]
	v_mfma_f32_16x16x32_bf16 v[138:141], v[214:217], v[68:71], v[138:141]
	v_mfma_f32_16x16x32_bf16 v[142:145], v[214:217], v[92:95], v[142:145]
	s_waitcnt lgkmcnt(0)
	v_mfma_f32_16x16x32_bf16 v[100:103], v[206:209], v[44:47], v[100:103]
	v_mfma_f32_16x16x32_bf16 v[100:103], v[210:213], v[48:51], v[100:103]
	v_mfma_f32_16x16x32_bf16 v[104:107], v[210:213], v[80:83], v[104:107]
	v_mfma_f32_16x16x32_bf16 v[104:107], v[206:209], v[76:79], v[104:107]
	v_mfma_f32_16x16x32_bf16 v[108:111], v[206:209], v[96:99], v[108:111]
	v_mfma_f32_16x16x32_bf16 v[112:115], v[222:225], v[44:47], v[112:115]
	v_mfma_f32_16x16x32_bf16 v[112:115], v[226:229], v[48:51], v[112:115]
	v_mfma_f32_16x16x32_bf16 v[138:141], v[226:229], v[80:83], v[138:141]
	v_mfma_f32_16x16x32_bf16 v[138:141], v[222:225], v[76:79], v[138:141]
	v_mfma_f32_16x16x32_bf16 v[142:145], v[222:225], v[96:99], v[142:145]
	s_waitcnt lgkmcnt(0)
	s_barrier
	s_waitcnt vmcnt(3)
	ds_write_b128 v134, v[146:149]
	ds_write_b128 v134, v[150:153] offset:4608
	ds_write_b128 v135, v[160:163]
	s_add_i32 s52, s4, 3
	s_min_u32 s52, s52, 31
	s_lshl_b32 s52, s52, 13
	s_add_u32 s26, s50, s52
	s_addc_u32 s27, s51, 0
	global_load_dwordx4 v[146:149], v154, s[26:27]
	global_load_dwordx4 v[150:153], v155, s[26:27]
	global_load_dwordx4 v[160:163], v159, s[26:27]
	v_exp_f32_e32 v198, v100
	v_exp_f32_e32 v199, v101
	v_exp_f32_e32 v200, v102
	v_exp_f32_e32 v201, v103
	v_exp_f32_e32 v202, v112
	v_exp_f32_e32 v203, v113
	v_exp_f32_e32 v204, v114
	v_exp_f32_e32 v205, v115
	v_exp_f32_e32 v214, v104
	v_add_f32_e32 v198, 1.0, v198
	v_exp_f32_e32 v215, v105
	v_add_f32_e32 v199, 1.0, v199
	v_exp_f32_e32 v216, v106
	v_add_f32_e32 v200, 1.0, v200
	v_exp_f32_e32 v217, v107
	v_add_f32_e32 v201, 1.0, v201
	v_exp_f32_e32 v218, v138
	v_add_f32_e32 v202, 1.0, v202
	v_exp_f32_e32 v219, v139
	v_add_f32_e32 v203, 1.0, v203
	v_exp_f32_e32 v220, v140
	v_add_f32_e32 v204, 1.0, v204
	v_exp_f32_e32 v221, v141
	v_add_f32_e32 v205, 1.0, v205
	v_rcp_f32_e32 v198, v198
	v_add_f32_e32 v214, 1.0, v214
	v_rcp_f32_e32 v199, v199
	v_add_f32_e32 v215, 1.0, v215
	v_rcp_f32_e32 v200, v200
	v_add_f32_e32 v216, 1.0, v216
	v_rcp_f32_e32 v201, v201
	v_add_f32_e32 v217, 1.0, v217
	v_rcp_f32_e32 v202, v202
	v_add_f32_e32 v218, 1.0, v218
	v_rcp_f32_e32 v203, v203
	v_add_f32_e32 v219, 1.0, v219
	v_rcp_f32_e32 v204, v204
	v_add_f32_e32 v220, 1.0, v220
	v_rcp_f32_e32 v205, v205
	v_add_f32_e32 v221, 1.0, v221
	v_mul_f32_e32 v198, v179, v198
	v_mul_f32_e32 v199, v179, v199
	v_mul_f32_e32 v200, v179, v200
	v_mul_f32_e32 v201, v179, v201
	v_mul_f32_e32 v202, v179, v202
	v_mul_f32_e32 v203, v179, v203
	v_mul_f32_e32 v204, v179, v204
	v_mul_f32_e32 v205, v179, v205
	v_exp_f32_e32 v120, v198
	v_exp_f32_e32 v121, v199
	v_exp_f32_e32 v122, v200
	v_exp_f32_e32 v123, v201
	v_exp_f32_e32 v124, v202
	v_exp_f32_e32 v125, v203
	v_exp_f32_e32 v126, v204
	v_exp_f32_e32 v127, v205
	v_fma_f32 v206, -v120, v120, 1.0
	v_fma_f32 v207, -v121, v121, 1.0
	v_fma_f32 v208, -v122, v122, 1.0
	v_fma_f32 v209, -v123, v123, 1.0
	v_fma_f32 v210, -v124, v124, 1.0
	v_fma_f32 v211, -v125, v125, 1.0
	v_fma_f32 v212, -v126, v126, 1.0
	v_fma_f32 v213, -v127, v127, 1.0
	v_max_f32_e32 v206, 0xda24260, v206
	v_max_f32_e32 v207, 0xda24260, v207
	v_max_f32_e32 v208, 0xda24260, v208
	v_max_f32_e32 v209, 0xda24260, v209
	v_max_f32_e32 v210, 0xda24260, v210
	v_max_f32_e32 v211, 0xda24260, v211
	v_max_f32_e32 v212, 0xda24260, v212
	v_max_f32_e32 v213, 0xda24260, v213
	v_mul_f32_e32 v198, v214, v206
	v_mul_f32_e32 v199, v215, v207
	v_mul_f32_e32 v200, v216, v208
	v_mul_f32_e32 v201, v217, v209
	v_mul_f32_e32 v202, v218, v210
	v_mul_f32_e32 v203, v219, v211
	v_mul_f32_e32 v204, v220, v212
	v_mul_f32_e32 v205, v221, v213
	v_mul_f32_e32 v214, v214, v198
	v_mul_f32_e32 v215, v215, v199
	v_mul_f32_e32 v216, v216, v200
	v_mul_f32_e32 v217, v217, v201
	v_mul_f32_e32 v218, v218, v202
	v_mul_f32_e32 v219, v219, v203
	v_mul_f32_e32 v220, v220, v204
	v_mul_f32_e32 v221, v221, v205
	v_rsq_f32_e32 v214, v214
	v_mul_f32_e32 v222, v108, v206
	v_rsq_f32_e32 v215, v215
	v_mul_f32_e32 v223, v109, v207
	v_rsq_f32_e32 v216, v216
	v_mul_f32_e32 v224, v110, v208
	v_rsq_f32_e32 v217, v217
	v_mul_f32_e32 v225, v111, v209
	v_rsq_f32_e32 v218, v218
	v_mul_f32_e32 v226, v142, v210
	v_rsq_f32_e32 v219, v219
	v_mul_f32_e32 v227, v143, v211
	v_rsq_f32_e32 v220, v220
	v_mul_f32_e32 v228, v144, v212
	v_rsq_f32_e32 v221, v221
	v_mul_f32_e32 v229, v145, v213
	v_mul_f32_e32 v170, v222, v214
	v_mul_f32_e32 v171, v223, v215
	v_mul_f32_e32 v172, v224, v216
	v_mul_f32_e32 v173, v225, v217
	v_mul_f32_e32 v174, v226, v218
	v_mul_f32_e32 v175, v227, v219
	v_mul_f32_e32 v176, v228, v220
	v_mul_f32_e32 v177, v229, v221
	v_mov_b32_e32 v198, v170
	v_mov_b32_e32 v199, v120
	v_fma_f32 v198, v121, v198, v171
	v_mul_f32_e32 v199, v199, v121
	v_fma_f32 v198, v122, v198, v172
	v_mul_f32_e32 v199, v199, v122
	v_fma_f32 v198, v123, v198, v173
	v_mul_f32_e32 v199, v199, v123
	v_fma_f32 v198, v124, v198, v174
	v_mul_f32_e32 v199, v199, v124
	v_fma_f32 v198, v125, v198, v175
	v_mul_f32_e32 v199, v199, v125
	v_fma_f32 v198, v126, v198, v176
	v_mul_f32_e32 v199, v199, v126
	v_fma_f32 v198, v127, v198, v177
	v_mul_f32_e32 v199, v199, v127
	ds_bpermute_b32 v164, v185, v199 offset:0
	ds_bpermute_b32 v246, v185, v198 offset:0
	ds_bpermute_b32 v165, v185, v199 offset:64
	ds_bpermute_b32 v247, v185, v198 offset:64
	ds_bpermute_b32 v166, v185, v199 offset:128
	ds_bpermute_b32 v248, v185, v198 offset:128
	ds_bpermute_b32 v167, v185, v199 offset:192
	ds_bpermute_b32 v249, v185, v198 offset:192
	s_waitcnt lgkmcnt(0)
	v_mov_b32_e32 v251, v246
	v_mov_b32_e32 v250, v164
	v_fma_f32 v251, v251, v165, v247
	v_mul_f32_e32 v250, v250, v165
	v_fma_f32 v251, v251, v166, v248
	v_mul_f32_e32 v250, v250, v166
	v_fma_f32 v251, v251, v167, v249
	v_mul_f32_e32 v250, v250, v167
	s_mov_b64 exec, s[10:11]
	ds_write_b64 v182, v[250:251] offset:0
	s_mov_b64 exec, -1
	s_waitcnt lgkmcnt(0)
	s_barrier
	ds_read2_b64 v[4:7], v183 offset0:0 offset1:16
	s_add_i32 s52, s4, 0
	s_lshl_b32 s52, s52, 12
	v_add_u32_e32 v197, s52, v184
	s_waitcnt lgkmcnt(0)
	v_fma_f32 v198, v180, v4, v5
	v_cndmask_b32_e64 v199, v180, v198, s[24:25]
	v_fma_f32 v180, v198, v6, v7
	v_fma_f32 v200, v199, v164, v246
	v_cndmask_b32_e64 v199, v199, v200, s[16:17]
	v_fma_f32 v200, v199, v165, v247
	v_cndmask_b32_e64 v199, v199, v200, s[20:21]
	v_fma_f32 v200, v199, v166, v248
	v_cndmask_b32_e64 v199, v199, v200, s[22:23]
	v_fma_f32 v214, v120, v199, v170
	v_fma_f32 v215, v121, v214, v171
	v_fma_f32 v216, v122, v215, v172
	v_fma_f32 v217, v123, v216, v173
	v_fma_f32 v218, v124, v217, v174
	v_fma_f32 v219, v125, v218, v175
	v_fma_f32 v220, v126, v219, v176
	v_fma_f32 v221, v127, v220, v177
	v_cvt_pk_bf16_f32 v206, v214, v215
	v_cvt_pk_bf16_f32 v208, v216, v217
	v_cvt_pk_bf16_f32 v210, v218, v219
	v_cvt_pk_bf16_f32 v212, v220, v221
	ds_write_b16 v197, v206 offset:0
	ds_write_b16_d16_hi v197, v206 offset:64
	ds_write_b16 v197, v208 offset:128
	ds_write_b16_d16_hi v197, v208 offset:192
	ds_write_b16 v197, v210 offset:256
	ds_write_b16_d16_hi v197, v210 offset:320
	ds_write_b16 v197, v212 offset:384
	ds_write_b16_d16_hi v197, v212 offset:448
	ds_read_b128 v[198:201], v130 offset:0
	ds_read_b128 v[214:217], v130 offset:576
	ds_read_b128 v[202:205], v131 offset:0
	ds_read_b128 v[218:221], v131 offset:576
	ds_read_b128 v[206:209], v130 offset:144
	ds_read_b128 v[222:225], v130 offset:720
	ds_read_b128 v[210:213], v131 offset:144
	s_waitcnt lgkmcnt(14)
	ds_read_b128 v[226:229], v131 offset:720
	s_waitcnt lgkmcnt(4)
	v_mfma_f32_16x16x32_bf16 v[100:103], v[198:201], v[20:23], v[12:15]
	v_mfma_f32_16x16x32_bf16 v[100:103], v[202:205], v[24:27], v[100:103]
	v_mfma_f32_16x16x32_bf16 v[104:107], v[198:201], v[52:55], v[16:19]
	v_mfma_f32_16x16x32_bf16 v[104:107], v[202:205], v[56:59], v[104:107]
	v_mfma_f32_16x16x32_bf16 v[108:111], v[198:201], v[84:87], v[242:245]
	v_mfma_f32_16x16x32_bf16 v[112:115], v[214:217], v[20:23], v[12:15]
	v_mfma_f32_16x16x32_bf16 v[112:115], v[218:221], v[24:27], v[112:115]
	v_mfma_f32_16x16x32_bf16 v[138:141], v[214:217], v[52:55], v[16:19]
	v_mfma_f32_16x16x32_bf16 v[138:141], v[218:221], v[56:59], v[138:141]
	v_mfma_f32_16x16x32_bf16 v[142:145], v[214:217], v[84:87], v[242:245]
	ds_read_b128 v[198:201], v130 offset:288
	ds_read_b128 v[214:217], v130 offset:864
	ds_read_b128 v[202:205], v131 offset:288
	ds_read_b128 v[218:221], v131 offset:864
	s_waitcnt lgkmcnt(4)
	v_mfma_f32_16x16x32_bf16 v[100:103], v[206:209], v[28:31], v[100:103]
	v_mfma_f32_16x16x32_bf16 v[100:103], v[210:213], v[32:35], v[100:103]
	v_mfma_f32_16x16x32_bf16 v[104:107], v[210:213], v[64:67], v[104:107]
	v_mfma_f32_16x16x32_bf16 v[104:107], v[206:209], v[60:63], v[104:107]
	v_mfma_f32_16x16x32_bf16 v[108:111], v[206:209], v[88:91], v[108:111]
	v_mfma_f32_16x16x32_bf16 v[112:115], v[222:225], v[28:31], v[112:115]
	v_mfma_f32_16x16x32_bf16 v[112:115], v[226:229], v[32:35], v[112:115]
	v_mfma_f32_16x16x32_bf16 v[138:141], v[226:229], v[64:67], v[138:141]
	v_mfma_f32_16x16x32_bf16 v[138:141], v[222:225], v[60:63], v[138:141]
	v_mfma_f32_16x16x32_bf16 v[142:145], v[222:225], v[88:91], v[142:145]
	ds_read_b128 v[206:209], v130 offset:432
	ds_read_b128 v[222:225], v130 offset:1008
	ds_read_b128 v[210:213], v131 offset:432
	ds_read_b128 v[226:229], v131 offset:1008
	s_waitcnt lgkmcnt(4)
	v_mfma_f32_16x16x32_bf16 v[100:103], v[198:201], v[36:39], v[100:103]
	v_mfma_f32_16x16x32_bf16 v[100:103], v[202:205], v[40:43], v[100:103]
	v_mfma_f32_16x16x32_bf16 v[104:107], v[202:205], v[72:75], v[104:107]
	v_mfma_f32_16x16x32_bf16 v[104:107], v[198:201], v[68:71], v[104:107]
	v_mfma_f32_16x16x32_bf16 v[108:111], v[198:201], v[92:95], v[108:111]
	v_mfma_f32_16x16x32_bf16 v[112:115], v[214:217], v[36:39], v[112:115]
	v_mfma_f32_16x16x32_bf16 v[112:115], v[218:221], v[40:43], v[112:115]
	v_mfma_f32_16x16x32_bf16 v[138:141], v[218:221], v[72:75], v[138:141]
	v_mfma_f32_16x16x32_bf16 v[138:141], v[214:217], v[68:71], v[138:141]
	v_mfma_f32_16x16x32_bf16 v[142:145], v[214:217], v[92:95], v[142:145]
	s_waitcnt lgkmcnt(0)
	v_mfma_f32_16x16x32_bf16 v[100:103], v[206:209], v[44:47], v[100:103]
	v_mfma_f32_16x16x32_bf16 v[100:103], v[210:213], v[48:51], v[100:103]
	v_mfma_f32_16x16x32_bf16 v[104:107], v[210:213], v[80:83], v[104:107]
	v_mfma_f32_16x16x32_bf16 v[104:107], v[206:209], v[76:79], v[104:107]
	v_mfma_f32_16x16x32_bf16 v[108:111], v[206:209], v[96:99], v[108:111]
	v_mfma_f32_16x16x32_bf16 v[112:115], v[222:225], v[44:47], v[112:115]
	v_mfma_f32_16x16x32_bf16 v[112:115], v[226:229], v[48:51], v[112:115]
	v_mfma_f32_16x16x32_bf16 v[138:141], v[226:229], v[80:83], v[138:141]
	v_mfma_f32_16x16x32_bf16 v[138:141], v[222:225], v[76:79], v[138:141]
	v_mfma_f32_16x16x32_bf16 v[142:145], v[222:225], v[96:99], v[142:145]
	s_waitcnt lgkmcnt(0)
	s_barrier
	s_waitcnt vmcnt(3)
	ds_write_b128 v134, v[230:233]
	ds_write_b128 v134, v[234:237] offset:4608
	ds_write_b128 v135, v[238:241]
	s_add_i32 s52, s4, 4
	s_min_u32 s52, s52, 31
	s_lshl_b32 s52, s52, 13
	s_add_u32 s26, s50, s52
	s_addc_u32 s27, s51, 0
	global_load_dwordx4 v[230:233], v154, s[26:27]
	global_load_dwordx4 v[234:237], v155, s[26:27]
	global_load_dwordx4 v[238:241], v159, s[26:27]
	v_exp_f32_e32 v198, v100
	v_exp_f32_e32 v199, v101
	v_exp_f32_e32 v200, v102
	v_exp_f32_e32 v201, v103
	v_exp_f32_e32 v202, v112
	v_exp_f32_e32 v203, v113
	v_exp_f32_e32 v204, v114
	v_exp_f32_e32 v205, v115
	v_exp_f32_e32 v214, v104
	v_add_f32_e32 v198, 1.0, v198
	v_exp_f32_e32 v215, v105
	v_add_f32_e32 v199, 1.0, v199
	v_exp_f32_e32 v216, v106
	v_add_f32_e32 v200, 1.0, v200
	v_exp_f32_e32 v217, v107
	v_add_f32_e32 v201, 1.0, v201
	v_exp_f32_e32 v218, v138
	v_add_f32_e32 v202, 1.0, v202
	v_exp_f32_e32 v219, v139
	v_add_f32_e32 v203, 1.0, v203
	v_exp_f32_e32 v220, v140
	v_add_f32_e32 v204, 1.0, v204
	v_exp_f32_e32 v221, v141
	v_add_f32_e32 v205, 1.0, v205
	v_rcp_f32_e32 v198, v198
	v_add_f32_e32 v214, 1.0, v214
	v_rcp_f32_e32 v199, v199
	v_add_f32_e32 v215, 1.0, v215
	v_rcp_f32_e32 v200, v200
	v_add_f32_e32 v216, 1.0, v216
	v_rcp_f32_e32 v201, v201
	v_add_f32_e32 v217, 1.0, v217
	v_rcp_f32_e32 v202, v202
	v_add_f32_e32 v218, 1.0, v218
	v_rcp_f32_e32 v203, v203
	v_add_f32_e32 v219, 1.0, v219
	v_rcp_f32_e32 v204, v204
	v_add_f32_e32 v220, 1.0, v220
	v_rcp_f32_e32 v205, v205
	v_add_f32_e32 v221, 1.0, v221
	v_mul_f32_e32 v198, v179, v198
	v_mul_f32_e32 v199, v179, v199
	v_mul_f32_e32 v200, v179, v200
	v_mul_f32_e32 v201, v179, v201
	v_mul_f32_e32 v202, v179, v202
	v_mul_f32_e32 v203, v179, v203
	v_mul_f32_e32 v204, v179, v204
	v_mul_f32_e32 v205, v179, v205
	v_exp_f32_e32 v120, v198
	v_exp_f32_e32 v121, v199
	v_exp_f32_e32 v122, v200
	v_exp_f32_e32 v123, v201
	v_exp_f32_e32 v124, v202
	v_exp_f32_e32 v125, v203
	v_exp_f32_e32 v126, v204
	v_exp_f32_e32 v127, v205
	v_fma_f32 v206, -v120, v120, 1.0
	v_fma_f32 v207, -v121, v121, 1.0
	v_fma_f32 v208, -v122, v122, 1.0
	v_fma_f32 v209, -v123, v123, 1.0
	v_fma_f32 v210, -v124, v124, 1.0
	v_fma_f32 v211, -v125, v125, 1.0
	v_fma_f32 v212, -v126, v126, 1.0
	v_fma_f32 v213, -v127, v127, 1.0
	v_max_f32_e32 v206, 0xda24260, v206
	v_max_f32_e32 v207, 0xda24260, v207
	v_max_f32_e32 v208, 0xda24260, v208
	v_max_f32_e32 v209, 0xda24260, v209
	v_max_f32_e32 v210, 0xda24260, v210
	v_max_f32_e32 v211, 0xda24260, v211
	v_max_f32_e32 v212, 0xda24260, v212
	v_max_f32_e32 v213, 0xda24260, v213
	v_mul_f32_e32 v198, v214, v206
	v_mul_f32_e32 v199, v215, v207
	v_mul_f32_e32 v200, v216, v208
	v_mul_f32_e32 v201, v217, v209
	v_mul_f32_e32 v202, v218, v210
	v_mul_f32_e32 v203, v219, v211
	v_mul_f32_e32 v204, v220, v212
	v_mul_f32_e32 v205, v221, v213
	v_mul_f32_e32 v214, v214, v198
	v_mul_f32_e32 v215, v215, v199
	v_mul_f32_e32 v216, v216, v200
	v_mul_f32_e32 v217, v217, v201
	v_mul_f32_e32 v218, v218, v202
	v_mul_f32_e32 v219, v219, v203
	v_mul_f32_e32 v220, v220, v204
	v_mul_f32_e32 v221, v221, v205
	v_rsq_f32_e32 v214, v214
	v_mul_f32_e32 v222, v108, v206
	v_rsq_f32_e32 v215, v215
	v_mul_f32_e32 v223, v109, v207
	v_rsq_f32_e32 v216, v216
	v_mul_f32_e32 v224, v110, v208
	v_rsq_f32_e32 v217, v217
	v_mul_f32_e32 v225, v111, v209
	v_rsq_f32_e32 v218, v218
	v_mul_f32_e32 v226, v142, v210
	v_rsq_f32_e32 v219, v219
	v_mul_f32_e32 v227, v143, v211
	v_rsq_f32_e32 v220, v220
	v_mul_f32_e32 v228, v144, v212
	v_rsq_f32_e32 v221, v221
	v_mul_f32_e32 v229, v145, v213
	v_mul_f32_e32 v170, v222, v214
	v_mul_f32_e32 v171, v223, v215
	v_mul_f32_e32 v172, v224, v216
	v_mul_f32_e32 v173, v225, v217
	v_mul_f32_e32 v174, v226, v218
	v_mul_f32_e32 v175, v227, v219
	v_mul_f32_e32 v176, v228, v220
	v_mul_f32_e32 v177, v229, v221
	v_mov_b32_e32 v198, v170
	v_mov_b32_e32 v199, v120
	v_fma_f32 v198, v121, v198, v171
	v_mul_f32_e32 v199, v199, v121
	v_fma_f32 v198, v122, v198, v172
	v_mul_f32_e32 v199, v199, v122
	v_fma_f32 v198, v123, v198, v173
	v_mul_f32_e32 v199, v199, v123
	v_fma_f32 v198, v124, v198, v174
	v_mul_f32_e32 v199, v199, v124
	v_fma_f32 v198, v125, v198, v175
	v_mul_f32_e32 v199, v199, v125
	v_fma_f32 v198, v126, v198, v176
	v_mul_f32_e32 v199, v199, v126
	v_fma_f32 v198, v127, v198, v177
	v_mul_f32_e32 v199, v199, v127
	ds_bpermute_b32 v164, v185, v199 offset:0
	ds_bpermute_b32 v246, v185, v198 offset:0
	ds_bpermute_b32 v165, v185, v199 offset:64
	ds_bpermute_b32 v247, v185, v198 offset:64
	ds_bpermute_b32 v166, v185, v199 offset:128
	ds_bpermute_b32 v248, v185, v198 offset:128
	ds_bpermute_b32 v167, v185, v199 offset:192
	ds_bpermute_b32 v249, v185, v198 offset:192
	s_waitcnt lgkmcnt(0)
	v_mov_b32_e32 v251, v246
	v_mov_b32_e32 v250, v164
	v_fma_f32 v251, v251, v165, v247
	v_mul_f32_e32 v250, v250, v165
	v_fma_f32 v251, v251, v166, v248
	v_mul_f32_e32 v250, v250, v166
	v_fma_f32 v251, v251, v167, v249
	v_mul_f32_e32 v250, v250, v167
	s_mov_b64 exec, s[10:11]
	ds_write_b64 v182, v[250:251] offset:1024
	s_mov_b64 exec, -1
	s_waitcnt lgkmcnt(0)
	s_barrier
	ds_read2_b64 v[4:7], v183 offset0:128 offset1:144
	s_add_i32 s52, s4, 1
	s_lshl_b32 s52, s52, 12
	v_add_u32_e32 v197, s52, v184
	s_waitcnt lgkmcnt(0)
	v_fma_f32 v198, v180, v4, v5
	v_cndmask_b32_e64 v199, v180, v198, s[24:25]
	v_fma_f32 v180, v198, v6, v7
	v_fma_f32 v200, v199, v164, v246
	v_cndmask_b32_e64 v199, v199, v200, s[16:17]
	v_fma_f32 v200, v199, v165, v247
	v_cndmask_b32_e64 v199, v199, v200, s[20:21]
	v_fma_f32 v200, v199, v166, v248
	v_cndmask_b32_e64 v199, v199, v200, s[22:23]
	v_fma_f32 v214, v120, v199, v170
	v_fma_f32 v215, v121, v214, v171
	v_fma_f32 v216, v122, v215, v172
	v_fma_f32 v217, v123, v216, v173
	v_fma_f32 v218, v124, v217, v174
	v_fma_f32 v219, v125, v218, v175
	v_fma_f32 v220, v126, v219, v176
	v_fma_f32 v221, v127, v220, v177
	v_cvt_pk_bf16_f32 v206, v214, v215
	v_cvt_pk_bf16_f32 v208, v216, v217
	v_cvt_pk_bf16_f32 v210, v218, v219
	v_cvt_pk_bf16_f32 v212, v220, v221
	ds_write_b16 v197, v206 offset:0
	ds_write_b16_d16_hi v197, v206 offset:64
	ds_write_b16 v197, v208 offset:128
	ds_write_b16_d16_hi v197, v208 offset:192
	ds_write_b16 v197, v210 offset:256
	ds_write_b16_d16_hi v197, v210 offset:320
	ds_write_b16 v197, v212 offset:384
	ds_write_b16_d16_hi v197, v212 offset:448
	s_add_i32 s4, s4, 2
	s_cmp_lt_u32 s4, 16
	s_cbranch_scc1 .Lrec2_loopA_d0
	ds_read_b128 v[198:201], v130 offset:0
	ds_read_b128 v[214:217], v130 offset:576
	ds_read_b128 v[202:205], v131 offset:0
	ds_read_b128 v[218:221], v131 offset:576
	ds_read_b128 v[206:209], v130 offset:144
	ds_read_b128 v[222:225], v130 offset:720
	ds_read_b128 v[210:213], v131 offset:144
	s_waitcnt lgkmcnt(14)
	ds_read_b128 v[226:229], v131 offset:720
	s_waitcnt lgkmcnt(4)
	v_mfma_f32_16x16x32_bf16 v[100:103], v[198:201], v[20:23], v[12:15]
	v_mfma_f32_16x16x32_bf16 v[100:103], v[202:205], v[24:27], v[100:103]
	v_mfma_f32_16x16x32_bf16 v[104:107], v[198:201], v[52:55], v[16:19]
	v_mfma_f32_16x16x32_bf16 v[104:107], v[202:205], v[56:59], v[104:107]
	v_mfma_f32_16x16x32_bf16 v[108:111], v[198:201], v[84:87], v[242:245]
	v_mfma_f32_16x16x32_bf16 v[112:115], v[214:217], v[20:23], v[12:15]
	v_mfma_f32_16x16x32_bf16 v[112:115], v[218:221], v[24:27], v[112:115]
	v_mfma_f32_16x16x32_bf16 v[138:141], v[214:217], v[52:55], v[16:19]
	v_mfma_f32_16x16x32_bf16 v[138:141], v[218:221], v[56:59], v[138:141]
	v_mfma_f32_16x16x32_bf16 v[142:145], v[214:217], v[84:87], v[242:245]
	ds_read_b128 v[198:201], v130 offset:288
	ds_read_b128 v[214:217], v130 offset:864
	ds_read_b128 v[202:205], v131 offset:288
	ds_read_b128 v[218:221], v131 offset:864
	s_waitcnt lgkmcnt(4)
	v_mfma_f32_16x16x32_bf16 v[100:103], v[206:209], v[28:31], v[100:103]
	v_mfma_f32_16x16x32_bf16 v[100:103], v[210:213], v[32:35], v[100:103]
	v_mfma_f32_16x16x32_bf16 v[104:107], v[210:213], v[64:67], v[104:107]
	v_mfma_f32_16x16x32_bf16 v[104:107], v[206:209], v[60:63], v[104:107]
	v_mfma_f32_16x16x32_bf16 v[108:111], v[206:209], v[88:91], v[108:111]
	v_mfma_f32_16x16x32_bf16 v[112:115], v[222:225], v[28:31], v[112:115]
	v_mfma_f32_16x16x32_bf16 v[112:115], v[226:229], v[32:35], v[112:115]
	v_mfma_f32_16x16x32_bf16 v[138:141], v[226:229], v[64:67], v[138:141]
	v_mfma_f32_16x16x32_bf16 v[138:141], v[222:225], v[60:63], v[138:141]
	v_mfma_f32_16x16x32_bf16 v[142:145], v[222:225], v[88:91], v[142:145]
	ds_read_b128 v[206:209], v130 offset:432
	ds_read_b128 v[222:225], v130 offset:1008
	ds_read_b128 v[210:213], v131 offset:432
	ds_read_b128 v[226:229], v131 offset:1008
	s_waitcnt lgkmcnt(4)
	v_mfma_f32_16x16x32_bf16 v[100:103], v[198:201], v[36:39], v[100:103]
	v_mfma_f32_16x16x32_bf16 v[100:103], v[202:205], v[40:43], v[100:103]
	v_mfma_f32_16x16x32_bf16 v[104:107], v[202:205], v[72:75], v[104:107]
	v_mfma_f32_16x16x32_bf16 v[104:107], v[198:201], v[68:71], v[104:107]
	v_mfma_f32_16x16x32_bf16 v[108:111], v[198:201], v[92:95], v[108:111]
	v_mfma_f32_16x16x32_bf16 v[112:115], v[214:217], v[36:39], v[112:115]
	v_mfma_f32_16x16x32_bf16 v[112:115], v[218:221], v[40:43], v[112:115]
	v_mfma_f32_16x16x32_bf16 v[138:141], v[218:221], v[72:75], v[138:141]
	v_mfma_f32_16x16x32_bf16 v[138:141], v[214:217], v[68:71], v[138:141]
	v_mfma_f32_16x16x32_bf16 v[142:145], v[214:217], v[92:95], v[142:145]
	s_waitcnt lgkmcnt(0)
	v_mfma_f32_16x16x32_bf16 v[100:103], v[206:209], v[44:47], v[100:103]
	v_mfma_f32_16x16x32_bf16 v[100:103], v[210:213], v[48:51], v[100:103]
	v_mfma_f32_16x16x32_bf16 v[104:107], v[210:213], v[80:83], v[104:107]
	v_mfma_f32_16x16x32_bf16 v[104:107], v[206:209], v[76:79], v[104:107]
	v_mfma_f32_16x16x32_bf16 v[108:111], v[206:209], v[96:99], v[108:111]
	v_mfma_f32_16x16x32_bf16 v[112:115], v[222:225], v[44:47], v[112:115]
	v_mfma_f32_16x16x32_bf16 v[112:115], v[226:229], v[48:51], v[112:115]
	v_mfma_f32_16x16x32_bf16 v[138:141], v[226:229], v[80:83], v[138:141]
	v_mfma_f32_16x16x32_bf16 v[138:141], v[222:225], v[76:79], v[138:141]
	v_mfma_f32_16x16x32_bf16 v[142:145], v[222:225], v[96:99], v[142:145]
	s_waitcnt lgkmcnt(0)
	s_barrier
	s_waitcnt vmcnt(3)
	ds_write_b128 v134, v[146:149]
	ds_write_b128 v134, v[150:153] offset:4608
	ds_write_b128 v135, v[160:163]
	s_add_i32 s64, s4, 0
	s_mul_i32 s71, s64, 0x30000
	s_add_u32 s38, s60, s71
	s_addc_u32 s39, s61, 0
	s_lshl_b32 s64, s64, 12
	global_load_dwordx4 v[8:11], v255, s[38:39]
	s_add_i32 s52, s4, 3
	s_min_u32 s52, s52, 31
	s_lshl_b32 s52, s52, 13
	s_add_u32 s26, s50, s52
	s_addc_u32 s27, s51, 0
	global_load_dwordx4 v[146:149], v154, s[26:27]
	global_load_dwordx4 v[150:153], v155, s[26:27]
	global_load_dwordx4 v[160:163], v159, s[26:27]
	v_exp_f32_e32 v198, v100
	v_exp_f32_e32 v199, v101
	v_exp_f32_e32 v200, v102
	v_exp_f32_e32 v201, v103
	v_exp_f32_e32 v202, v112
	v_exp_f32_e32 v203, v113
	v_exp_f32_e32 v204, v114
	v_exp_f32_e32 v205, v115
	v_exp_f32_e32 v214, v104
	v_add_f32_e32 v198, 1.0, v198
	v_exp_f32_e32 v215, v105
	v_add_f32_e32 v199, 1.0, v199
	v_exp_f32_e32 v216, v106
	v_add_f32_e32 v200, 1.0, v200
	v_exp_f32_e32 v217, v107
	v_add_f32_e32 v201, 1.0, v201
	v_exp_f32_e32 v218, v138
	v_add_f32_e32 v202, 1.0, v202
	v_exp_f32_e32 v219, v139
	v_add_f32_e32 v203, 1.0, v203
	v_exp_f32_e32 v220, v140
	v_add_f32_e32 v204, 1.0, v204
	v_exp_f32_e32 v221, v141
	v_add_f32_e32 v205, 1.0, v205
	v_rcp_f32_e32 v198, v198
	v_add_f32_e32 v214, 1.0, v214
	v_rcp_f32_e32 v199, v199
	v_add_f32_e32 v215, 1.0, v215
	v_rcp_f32_e32 v200, v200
	v_add_f32_e32 v216, 1.0, v216
	v_rcp_f32_e32 v201, v201
	v_add_f32_e32 v217, 1.0, v217
	v_rcp_f32_e32 v202, v202
	v_add_f32_e32 v218, 1.0, v218
	v_rcp_f32_e32 v203, v203
	v_add_f32_e32 v219, 1.0, v219
	v_rcp_f32_e32 v204, v204
	v_add_f32_e32 v220, 1.0, v220
	v_rcp_f32_e32 v205, v205
	v_add_f32_e32 v221, 1.0, v221
	v_mul_f32_e32 v198, v179, v198
	v_mul_f32_e32 v199, v179, v199
	v_mul_f32_e32 v200, v179, v200
	v_mul_f32_e32 v201, v179, v201
	v_mul_f32_e32 v202, v179, v202
	v_mul_f32_e32 v203, v179, v203
	v_mul_f32_e32 v204, v179, v204
	v_mul_f32_e32 v205, v179, v205
	v_exp_f32_e32 v120, v198
	v_exp_f32_e32 v121, v199
	v_exp_f32_e32 v122, v200
	v_exp_f32_e32 v123, v201
	v_exp_f32_e32 v124, v202
	v_exp_f32_e32 v125, v203
	v_exp_f32_e32 v126, v204
	v_exp_f32_e32 v127, v205
	v_fma_f32 v206, -v120, v120, 1.0
	v_fma_f32 v207, -v121, v121, 1.0
	v_fma_f32 v208, -v122, v122, 1.0
	v_fma_f32 v209, -v123, v123, 1.0
	v_fma_f32 v210, -v124, v124, 1.0
	v_fma_f32 v211, -v125, v125, 1.0
	v_fma_f32 v212, -v126, v126, 1.0
	v_fma_f32 v213, -v127, v127, 1.0
	v_max_f32_e32 v206, 0xda24260, v206
	v_max_f32_e32 v207, 0xda24260, v207
	v_max_f32_e32 v208, 0xda24260, v208
	v_max_f32_e32 v209, 0xda24260, v209
	v_max_f32_e32 v210, 0xda24260, v210
	v_max_f32_e32 v211, 0xda24260, v211
	v_max_f32_e32 v212, 0xda24260, v212
	v_max_f32_e32 v213, 0xda24260, v213
	v_mul_f32_e32 v198, v214, v206
	v_mul_f32_e32 v199, v215, v207
	v_mul_f32_e32 v200, v216, v208
	v_mul_f32_e32 v201, v217, v209
	v_mul_f32_e32 v202, v218, v210
	v_mul_f32_e32 v203, v219, v211
	v_mul_f32_e32 v204, v220, v212
	v_mul_f32_e32 v205, v221, v213
	v_mul_f32_e32 v214, v214, v198
	v_mul_f32_e32 v215, v215, v199
	v_mul_f32_e32 v216, v216, v200
	v_mul_f32_e32 v217, v217, v201
	v_mul_f32_e32 v218, v218, v202
	v_mul_f32_e32 v219, v219, v203
	v_mul_f32_e32 v220, v220, v204
	v_mul_f32_e32 v221, v221, v205
	v_rsq_f32_e32 v214, v214
	v_mul_f32_e32 v222, v108, v206
	v_rsq_f32_e32 v215, v215
	v_mul_f32_e32 v223, v109, v207
	v_rsq_f32_e32 v216, v216
	v_mul_f32_e32 v224, v110, v208
	v_rsq_f32_e32 v217, v217
	v_mul_f32_e32 v225, v111, v209
	v_rsq_f32_e32 v218, v218
	v_mul_f32_e32 v226, v142, v210
	v_rsq_f32_e32 v219, v219
	v_mul_f32_e32 v227, v143, v211
	v_rsq_f32_e32 v220, v220
	v_mul_f32_e32 v228, v144, v212
	v_rsq_f32_e32 v221, v221
	v_mul_f32_e32 v229, v145, v213
	v_mul_f32_e32 v170, v222, v214
	v_mul_f32_e32 v171, v223, v215
	v_mul_f32_e32 v172, v224, v216
	v_mul_f32_e32 v173, v225, v217
	v_mul_f32_e32 v174, v226, v218
	v_mul_f32_e32 v175, v227, v219
	v_mul_f32_e32 v176, v228, v220
	v_mul_f32_e32 v177, v229, v221
	v_mov_b32_e32 v198, v170
	v_mov_b32_e32 v199, v120
	v_fma_f32 v198, v121, v198, v171
	v_mul_f32_e32 v199, v199, v121
	v_fma_f32 v198, v122, v198, v172
	v_mul_f32_e32 v199, v199, v122
	v_fma_f32 v198, v123, v198, v173
	v_mul_f32_e32 v199, v199, v123
	v_fma_f32 v198, v124, v198, v174
	v_mul_f32_e32 v199, v199, v124
	v_fma_f32 v198, v125, v198, v175
	v_mul_f32_e32 v199, v199, v125
	v_fma_f32 v198, v126, v198, v176
	v_mul_f32_e32 v199, v199, v126
	v_fma_f32 v198, v127, v198, v177
	v_mul_f32_e32 v199, v199, v127
	ds_bpermute_b32 v164, v185, v199 offset:0
	ds_bpermute_b32 v246, v185, v198 offset:0
	ds_bpermute_b32 v165, v185, v199 offset:64
	ds_bpermute_b32 v247, v185, v198 offset:64
	ds_bpermute_b32 v166, v185, v199 offset:128
	ds_bpermute_b32 v248, v185, v198 offset:128
	ds_bpermute_b32 v167, v185, v199 offset:192
	ds_bpermute_b32 v249, v185, v198 offset:192
	s_waitcnt lgkmcnt(0)
	v_mov_b32_e32 v251, v246
	v_mov_b32_e32 v250, v164
	v_fma_f32 v251, v251, v165, v247
	v_mul_f32_e32 v250, v250, v165
	v_fma_f32 v251, v251, v166, v248
	v_mul_f32_e32 v250, v250, v166
	v_fma_f32 v251, v251, v167, v249
	v_mul_f32_e32 v250, v250, v167
	s_mov_b64 exec, s[10:11]
	ds_write_b64 v182, v[250:251] offset:0
	s_mov_b64 exec, -1
	s_waitcnt lgkmcnt(0)
	s_barrier
	ds_read2_b64 v[4:7], v183 offset0:0 offset1:16
	s_add_i32 s52, s4, 0
	s_lshl_b32 s52, s52, 12
	v_add_u32_e32 v197, s52, v184
	s_waitcnt lgkmcnt(0)
	v_fma_f32 v198, v180, v4, v5
	v_cndmask_b32_e64 v199, v180, v198, s[24:25]
	v_fma_f32 v180, v198, v6, v7
	v_fma_f32 v200, v199, v164, v246
	v_cndmask_b32_e64 v199, v199, v200, s[16:17]
	v_fma_f32 v200, v199, v165, v247
	v_cndmask_b32_e64 v199, v199, v200, s[20:21]
	v_fma_f32 v200, v199, v166, v248
	v_cndmask_b32_e64 v199, v199, v200, s[22:23]
	v_fma_f32 v214, v120, v199, v170
	v_fma_f32 v215, v121, v214, v171
	v_fma_f32 v216, v122, v215, v172
	v_fma_f32 v217, v123, v216, v173
	v_fma_f32 v218, v124, v217, v174
	v_fma_f32 v219, v125, v218, v175
	v_fma_f32 v220, v126, v219, v176
	v_fma_f32 v221, v127, v220, v177
	ds_read_u16 v206, v197 offset:0
	ds_read_u16 v207, v197 offset:64
	ds_read_u16 v208, v197 offset:128
	ds_read_u16 v209, v197 offset:192
	ds_read_u16 v210, v197 offset:256
	ds_read_u16 v211, v197 offset:320
	ds_read_u16 v212, v197 offset:384
	ds_read_u16 v213, v197 offset:448
	s_waitcnt lgkmcnt(0)
	v_lshlrev_b32_e32 v206, 16, v206
	v_lshlrev_b32_e32 v207, 16, v207
	v_lshlrev_b32_e32 v208, 16, v208
	v_lshlrev_b32_e32 v209, 16, v209
	v_lshlrev_b32_e32 v210, 16, v210
	v_lshlrev_b32_e32 v211, 16, v211
	v_lshlrev_b32_e32 v212, 16, v212
	v_lshlrev_b32_e32 v213, 16, v213
	v_add_f32_e32 v214, v214, v206
	v_add_f32_e32 v215, v215, v207
	v_add_f32_e32 v216, v216, v208
	v_add_f32_e32 v217, v217, v209
	v_add_f32_e32 v218, v218, v210
	v_add_f32_e32 v219, v219, v211
	v_add_f32_e32 v220, v220, v212
	v_add_f32_e32 v221, v221, v213
	v_cvt_pk_bf16_f32 v206, v214, v215
	v_cvt_pk_bf16_f32 v208, v216, v217
	v_cvt_pk_bf16_f32 v210, v218, v219
	v_cvt_pk_bf16_f32 v212, v220, v221
	ds_write_b16 v197, v206 offset:0
	ds_write_b16_d16_hi v197, v206 offset:64
	ds_write_b16 v197, v208 offset:128
	ds_write_b16_d16_hi v197, v208 offset:192
	ds_write_b16 v197, v210 offset:256
	ds_write_b16_d16_hi v197, v210 offset:320
	ds_write_b16 v197, v212 offset:384
	ds_write_b16_d16_hi v197, v212 offset:448
	ds_read_b128 v[198:201], v130 offset:0
	ds_read_b128 v[214:217], v130 offset:576
	ds_read_b128 v[202:205], v131 offset:0
	ds_read_b128 v[218:221], v131 offset:576
	ds_read_b128 v[206:209], v130 offset:144
	ds_read_b128 v[222:225], v130 offset:720
	ds_read_b128 v[210:213], v131 offset:144
	s_waitcnt lgkmcnt(14)
	ds_read_b128 v[226:229], v131 offset:720
	s_waitcnt lgkmcnt(4)
	v_mfma_f32_16x16x32_bf16 v[100:103], v[198:201], v[20:23], v[12:15]
	v_mfma_f32_16x16x32_bf16 v[100:103], v[202:205], v[24:27], v[100:103]
	v_mfma_f32_16x16x32_bf16 v[104:107], v[198:201], v[52:55], v[16:19]
	v_mfma_f32_16x16x32_bf16 v[104:107], v[202:205], v[56:59], v[104:107]
	v_mfma_f32_16x16x32_bf16 v[108:111], v[198:201], v[84:87], v[242:245]
	v_mfma_f32_16x16x32_bf16 v[112:115], v[214:217], v[20:23], v[12:15]
	v_mfma_f32_16x16x32_bf16 v[112:115], v[218:221], v[24:27], v[112:115]
	v_mfma_f32_16x16x32_bf16 v[138:141], v[214:217], v[52:55], v[16:19]
	v_mfma_f32_16x16x32_bf16 v[138:141], v[218:221], v[56:59], v[138:141]
	v_mfma_f32_16x16x32_bf16 v[142:145], v[214:217], v[84:87], v[242:245]
	ds_read_b128 v[198:201], v130 offset:288
	ds_read_b128 v[214:217], v130 offset:864
	ds_read_b128 v[202:205], v131 offset:288
	ds_read_b128 v[218:221], v131 offset:864
	s_waitcnt lgkmcnt(4)
	v_mfma_f32_16x16x32_bf16 v[100:103], v[206:209], v[28:31], v[100:103]
	v_mfma_f32_16x16x32_bf16 v[100:103], v[210:213], v[32:35], v[100:103]
	v_mfma_f32_16x16x32_bf16 v[104:107], v[210:213], v[64:67], v[104:107]
	v_mfma_f32_16x16x32_bf16 v[104:107], v[206:209], v[60:63], v[104:107]
	v_mfma_f32_16x16x32_bf16 v[108:111], v[206:209], v[88:91], v[108:111]
	v_mfma_f32_16x16x32_bf16 v[112:115], v[222:225], v[28:31], v[112:115]
	v_mfma_f32_16x16x32_bf16 v[112:115], v[226:229], v[32:35], v[112:115]
	v_mfma_f32_16x16x32_bf16 v[138:141], v[226:229], v[64:67], v[138:141]
	v_mfma_f32_16x16x32_bf16 v[138:141], v[222:225], v[60:63], v[138:141]
	v_mfma_f32_16x16x32_bf16 v[142:145], v[222:225], v[88:91], v[142:145]
	ds_read_b128 v[206:209], v130 offset:432
	ds_read_b128 v[222:225], v130 offset:1008
	ds_read_b128 v[210:213], v131 offset:432
	ds_read_b128 v[226:229], v131 offset:1008
	s_waitcnt lgkmcnt(4)
	v_mfma_f32_16x16x32_bf16 v[100:103], v[198:201], v[36:39], v[100:103]
	v_mfma_f32_16x16x32_bf16 v[100:103], v[202:205], v[40:43], v[100:103]
	v_mfma_f32_16x16x32_bf16 v[104:107], v[202:205], v[72:75], v[104:107]
	v_mfma_f32_16x16x32_bf16 v[104:107], v[198:201], v[68:71], v[104:107]
	v_mfma_f32_16x16x32_bf16 v[108:111], v[198:201], v[92:95], v[108:111]
	v_mfma_f32_16x16x32_bf16 v[112:115], v[214:217], v[36:39], v[112:115]
	v_mfma_f32_16x16x32_bf16 v[112:115], v[218:221], v[40:43], v[112:115]
	v_mfma_f32_16x16x32_bf16 v[138:141], v[218:221], v[72:75], v[138:141]
	v_mfma_f32_16x16x32_bf16 v[138:141], v[214:217], v[68:71], v[138:141]
	v_mfma_f32_16x16x32_bf16 v[142:145], v[214:217], v[92:95], v[142:145]
	s_waitcnt lgkmcnt(0)
	v_mfma_f32_16x16x32_bf16 v[100:103], v[206:209], v[44:47], v[100:103]
	v_mfma_f32_16x16x32_bf16 v[100:103], v[210:213], v[48:51], v[100:103]
	v_mfma_f32_16x16x32_bf16 v[104:107], v[210:213], v[80:83], v[104:107]
	v_mfma_f32_16x16x32_bf16 v[104:107], v[206:209], v[76:79], v[104:107]
	v_mfma_f32_16x16x32_bf16 v[108:111], v[206:209], v[96:99], v[108:111]
	v_mfma_f32_16x16x32_bf16 v[112:115], v[222:225], v[44:47], v[112:115]
	v_mfma_f32_16x16x32_bf16 v[112:115], v[226:229], v[48:51], v[112:115]
	v_mfma_f32_16x16x32_bf16 v[138:141], v[226:229], v[80:83], v[138:141]
	v_mfma_f32_16x16x32_bf16 v[138:141], v[222:225], v[76:79], v[138:141]
	v_mfma_f32_16x16x32_bf16 v[142:145], v[222:225], v[96:99], v[142:145]
	s_waitcnt lgkmcnt(0)
	s_barrier
	s_waitcnt vmcnt(4)
	ds_write_b128 v134, v[230:233]
	ds_write_b128 v134, v[234:237] offset:4608
	ds_write_b128 v135, v[238:241]
	s_add_i32 s64, s4, 0
	s_mul_i32 s71, s64, 0x30000
	s_add_u32 s38, s60, s71
	s_addc_u32 s39, s61, 0
	s_lshl_b32 s64, s64, 12
	v_add_u32_e32 v136, s64, v195
	ds_read_b128 v[116:119], v136
	s_waitcnt vmcnt(3)
	s_waitcnt lgkmcnt(0)
	v_lshlrev_b32_e32 v136, 16, v116
	v_lshlrev_b32_e32 v137, 16, v8
	v_and_b32_e32 v168, 0xffff0000, v116
	v_and_b32_e32 v169, 0xffff0000, v8
	v_mul_f32_e32 v136, v136, v137
	v_mul_f32_e32 v168, v168, v169
	v_cvt_pk_bf16_f32 v116, v136, v168
	v_lshlrev_b32_e32 v136, 16, v117
	v_lshlrev_b32_e32 v137, 16, v9
	v_and_b32_e32 v168, 0xffff0000, v117
	v_and_b32_e32 v169, 0xffff0000, v9
	v_mul_f32_e32 v136, v136, v137
	v_mul_f32_e32 v168, v168, v169
	v_cvt_pk_bf16_f32 v117, v136, v168
	v_lshlrev_b32_e32 v136, 16, v118
	v_lshlrev_b32_e32 v137, 16, v10
	v_and_b32_e32 v168, 0xffff0000, v118
	v_and_b32_e32 v169, 0xffff0000, v10
	v_mul_f32_e32 v136, v136, v137
	v_mul_f32_e32 v168, v168, v169
	v_cvt_pk_bf16_f32 v118, v136, v168
	v_lshlrev_b32_e32 v136, 16, v119
	v_lshlrev_b32_e32 v137, 16, v11
	v_and_b32_e32 v168, 0xffff0000, v119
	v_and_b32_e32 v169, 0xffff0000, v11
	v_mul_f32_e32 v136, v136, v137
	v_mul_f32_e32 v168, v168, v169
	v_cvt_pk_bf16_f32 v119, v136, v168
	global_store_dwordx4 v255, v[116:119], s[38:39]
	s_add_i32 s64, s4, 1
	s_mul_i32 s71, s64, 0x30000
	s_add_u32 s38, s60, s71
	s_addc_u32 s39, s61, 0
	s_lshl_b32 s64, s64, 12
	global_load_dwordx4 v[8:11], v255, s[38:39]
	s_add_i32 s52, s4, 4
	s_min_u32 s52, s52, 31
	s_lshl_b32 s52, s52, 13
	s_add_u32 s26, s50, s52
	s_addc_u32 s27, s51, 0
	global_load_dwordx4 v[230:233], v154, s[26:27]
	global_load_dwordx4 v[234:237], v155, s[26:27]
	global_load_dwordx4 v[238:241], v159, s[26:27]
	v_exp_f32_e32 v198, v100
	v_exp_f32_e32 v199, v101
	v_exp_f32_e32 v200, v102
	v_exp_f32_e32 v201, v103
	v_exp_f32_e32 v202, v112
	v_exp_f32_e32 v203, v113
	v_exp_f32_e32 v204, v114
	v_exp_f32_e32 v205, v115
	v_exp_f32_e32 v214, v104
	v_add_f32_e32 v198, 1.0, v198
	v_exp_f32_e32 v215, v105
	v_add_f32_e32 v199, 1.0, v199
	v_exp_f32_e32 v216, v106
	v_add_f32_e32 v200, 1.0, v200
	v_exp_f32_e32 v217, v107
	v_add_f32_e32 v201, 1.0, v201
	v_exp_f32_e32 v218, v138
	v_add_f32_e32 v202, 1.0, v202
	v_exp_f32_e32 v219, v139
	v_add_f32_e32 v203, 1.0, v203
	v_exp_f32_e32 v220, v140
	v_add_f32_e32 v204, 1.0, v204
	v_exp_f32_e32 v221, v141
	v_add_f32_e32 v205, 1.0, v205
	v_rcp_f32_e32 v198, v198
	v_add_f32_e32 v214, 1.0, v214
	v_rcp_f32_e32 v199, v199
	v_add_f32_e32 v215, 1.0, v215
	v_rcp_f32_e32 v200, v200
	v_add_f32_e32 v216, 1.0, v216
	v_rcp_f32_e32 v201, v201
	v_add_f32_e32 v217, 1.0, v217
	v_rcp_f32_e32 v202, v202
	v_add_f32_e32 v218, 1.0, v218
	v_rcp_f32_e32 v203, v203
	v_add_f32_e32 v219, 1.0, v219
	v_rcp_f32_e32 v204, v204
	v_add_f32_e32 v220, 1.0, v220
	v_rcp_f32_e32 v205, v205
	v_add_f32_e32 v221, 1.0, v221
	v_mul_f32_e32 v198, v179, v198
	v_mul_f32_e32 v199, v179, v199
	v_mul_f32_e32 v200, v179, v200
	v_mul_f32_e32 v201, v179, v201
	v_mul_f32_e32 v202, v179, v202
	v_mul_f32_e32 v203, v179, v203
	v_mul_f32_e32 v204, v179, v204
	v_mul_f32_e32 v205, v179, v205
	v_exp_f32_e32 v120, v198
	v_exp_f32_e32 v121, v199
	v_exp_f32_e32 v122, v200
	v_exp_f32_e32 v123, v201
	v_exp_f32_e32 v124, v202
	v_exp_f32_e32 v125, v203
	v_exp_f32_e32 v126, v204
	v_exp_f32_e32 v127, v205
	v_fma_f32 v206, -v120, v120, 1.0
	v_fma_f32 v207, -v121, v121, 1.0
	v_fma_f32 v208, -v122, v122, 1.0
	v_fma_f32 v209, -v123, v123, 1.0
	v_fma_f32 v210, -v124, v124, 1.0
	v_fma_f32 v211, -v125, v125, 1.0
	v_fma_f32 v212, -v126, v126, 1.0
	v_fma_f32 v213, -v127, v127, 1.0
	v_max_f32_e32 v206, 0xda24260, v206
	v_max_f32_e32 v207, 0xda24260, v207
	v_max_f32_e32 v208, 0xda24260, v208
	v_max_f32_e32 v209, 0xda24260, v209
	v_max_f32_e32 v210, 0xda24260, v210
	v_max_f32_e32 v211, 0xda24260, v211
	v_max_f32_e32 v212, 0xda24260, v212
	v_max_f32_e32 v213, 0xda24260, v213
	v_mul_f32_e32 v198, v214, v206
	v_mul_f32_e32 v199, v215, v207
	v_mul_f32_e32 v200, v216, v208
	v_mul_f32_e32 v201, v217, v209
	v_mul_f32_e32 v202, v218, v210
	v_mul_f32_e32 v203, v219, v211
	v_mul_f32_e32 v204, v220, v212
	v_mul_f32_e32 v205, v221, v213
	v_mul_f32_e32 v214, v214, v198
	v_mul_f32_e32 v215, v215, v199
	v_mul_f32_e32 v216, v216, v200
	v_mul_f32_e32 v217, v217, v201
	v_mul_f32_e32 v218, v218, v202
	v_mul_f32_e32 v219, v219, v203
	v_mul_f32_e32 v220, v220, v204
	v_mul_f32_e32 v221, v221, v205
	v_rsq_f32_e32 v214, v214
	v_mul_f32_e32 v222, v108, v206
	v_rsq_f32_e32 v215, v215
	v_mul_f32_e32 v223, v109, v207
	v_rsq_f32_e32 v216, v216
	v_mul_f32_e32 v224, v110, v208
	v_rsq_f32_e32 v217, v217
	v_mul_f32_e32 v225, v111, v209
	v_rsq_f32_e32 v218, v218
	v_mul_f32_e32 v226, v142, v210
	v_rsq_f32_e32 v219, v219
	v_mul_f32_e32 v227, v143, v211
	v_rsq_f32_e32 v220, v220
	v_mul_f32_e32 v228, v144, v212
	v_rsq_f32_e32 v221, v221
	v_mul_f32_e32 v229, v145, v213
	v_mul_f32_e32 v170, v222, v214
	v_mul_f32_e32 v171, v223, v215
	v_mul_f32_e32 v172, v224, v216
	v_mul_f32_e32 v173, v225, v217
	v_mul_f32_e32 v174, v226, v218
	v_mul_f32_e32 v175, v227, v219
	v_mul_f32_e32 v176, v228, v220
	v_mul_f32_e32 v177, v229, v221
	v_mov_b32_e32 v198, v170
	v_mov_b32_e32 v199, v120
	v_fma_f32 v198, v121, v198, v171
	v_mul_f32_e32 v199, v199, v121
	v_fma_f32 v198, v122, v198, v172
	v_mul_f32_e32 v199, v199, v122
	v_fma_f32 v198, v123, v198, v173
	v_mul_f32_e32 v199, v199, v123
	v_fma_f32 v198, v124, v198, v174
	v_mul_f32_e32 v199, v199, v124
	v_fma_f32 v198, v125, v198, v175
	v_mul_f32_e32 v199, v199, v125
	v_fma_f32 v198, v126, v198, v176
	v_mul_f32_e32 v199, v199, v126
	v_fma_f32 v198, v127, v198, v177
	v_mul_f32_e32 v199, v199, v127
	ds_bpermute_b32 v164, v185, v199 offset:0
	ds_bpermute_b32 v246, v185, v198 offset:0
	ds_bpermute_b32 v165, v185, v199 offset:64
	ds_bpermute_b32 v247, v185, v198 offset:64
	ds_bpermute_b32 v166, v185, v199 offset:128
	ds_bpermute_b32 v248, v185, v198 offset:128
	ds_bpermute_b32 v167, v185, v199 offset:192
	ds_bpermute_b32 v249, v185, v198 offset:192
	s_waitcnt lgkmcnt(0)
	v_mov_b32_e32 v251, v246
	v_mov_b32_e32 v250, v164
	v_fma_f32 v251, v251, v165, v247
	v_mul_f32_e32 v250, v250, v165
	v_fma_f32 v251, v251, v166, v248
	v_mul_f32_e32 v250, v250, v166
	v_fma_f32 v251, v251, v167, v249
	v_mul_f32_e32 v250, v250, v167
	s_mov_b64 exec, s[10:11]
	ds_write_b64 v182, v[250:251] offset:1024
	s_mov_b64 exec, -1
	s_waitcnt lgkmcnt(0)
	s_barrier
	ds_read2_b64 v[4:7], v183 offset0:128 offset1:144
	s_add_i32 s52, s4, 1
	s_lshl_b32 s52, s52, 12
	v_add_u32_e32 v197, s52, v184
	s_waitcnt lgkmcnt(0)
	v_fma_f32 v198, v180, v4, v5
	v_cndmask_b32_e64 v199, v180, v198, s[24:25]
	v_fma_f32 v180, v198, v6, v7
	v_fma_f32 v200, v199, v164, v246
	v_cndmask_b32_e64 v199, v199, v200, s[16:17]
	v_fma_f32 v200, v199, v165, v247
	v_cndmask_b32_e64 v199, v199, v200, s[20:21]
	v_fma_f32 v200, v199, v166, v248
	v_cndmask_b32_e64 v199, v199, v200, s[22:23]
	v_fma_f32 v214, v120, v199, v170
	v_fma_f32 v215, v121, v214, v171
	v_fma_f32 v216, v122, v215, v172
	v_fma_f32 v217, v123, v216, v173
	v_fma_f32 v218, v124, v217, v174
	v_fma_f32 v219, v125, v218, v175
	v_fma_f32 v220, v126, v219, v176
	v_fma_f32 v221, v127, v220, v177
	ds_read_u16 v206, v197 offset:0
	ds_read_u16 v207, v197 offset:64
	ds_read_u16 v208, v197 offset:128
	ds_read_u16 v209, v197 offset:192
	ds_read_u16 v210, v197 offset:256
	ds_read_u16 v211, v197 offset:320
	ds_read_u16 v212, v197 offset:384
	ds_read_u16 v213, v197 offset:448
	s_waitcnt lgkmcnt(0)
	v_lshlrev_b32_e32 v206, 16, v206
	v_lshlrev_b32_e32 v207, 16, v207
	v_lshlrev_b32_e32 v208, 16, v208
	v_lshlrev_b32_e32 v209, 16, v209
	v_lshlrev_b32_e32 v210, 16, v210
	v_lshlrev_b32_e32 v211, 16, v211
	v_lshlrev_b32_e32 v212, 16, v212
	v_lshlrev_b32_e32 v213, 16, v213
	v_add_f32_e32 v214, v214, v206
	v_add_f32_e32 v215, v215, v207
	v_add_f32_e32 v216, v216, v208
	v_add_f32_e32 v217, v217, v209
	v_add_f32_e32 v218, v218, v210
	v_add_f32_e32 v219, v219, v211
	v_add_f32_e32 v220, v220, v212
	v_add_f32_e32 v221, v221, v213
	v_cvt_pk_bf16_f32 v206, v214, v215
	v_cvt_pk_bf16_f32 v208, v216, v217
	v_cvt_pk_bf16_f32 v210, v218, v219
	v_cvt_pk_bf16_f32 v212, v220, v221
	ds_write_b16 v197, v206 offset:0
	ds_write_b16_d16_hi v197, v206 offset:64
	ds_write_b16 v197, v208 offset:128
	ds_write_b16_d16_hi v197, v208 offset:192
	ds_write_b16 v197, v210 offset:256
	ds_write_b16_d16_hi v197, v210 offset:320
	ds_write_b16 v197, v212 offset:384
	ds_write_b16_d16_hi v197, v212 offset:448
	s_add_i32 s4, s4, 2
.Lrec2_loopB_d0:
	ds_read_b128 v[198:201], v130 offset:0
	ds_read_b128 v[214:217], v130 offset:576
	ds_read_b128 v[202:205], v131 offset:0
	ds_read_b128 v[218:221], v131 offset:576
	ds_read_b128 v[206:209], v130 offset:144
	ds_read_b128 v[222:225], v130 offset:720
	ds_read_b128 v[210:213], v131 offset:144
	s_waitcnt lgkmcnt(14)
	ds_read_b128 v[226:229], v131 offset:720
	s_waitcnt lgkmcnt(4)
	v_mfma_f32_16x16x32_bf16 v[100:103], v[198:201], v[20:23], v[12:15]
	v_mfma_f32_16x16x32_bf16 v[100:103], v[202:205], v[24:27], v[100:103]
	v_mfma_f32_16x16x32_bf16 v[104:107], v[198:201], v[52:55], v[16:19]
	v_mfma_f32_16x16x32_bf16 v[104:107], v[202:205], v[56:59], v[104:107]
	v_mfma_f32_16x16x32_bf16 v[108:111], v[198:201], v[84:87], v[242:245]
	v_mfma_f32_16x16x32_bf16 v[112:115], v[214:217], v[20:23], v[12:15]
	v_mfma_f32_16x16x32_bf16 v[112:115], v[218:221], v[24:27], v[112:115]
	v_mfma_f32_16x16x32_bf16 v[138:141], v[214:217], v[52:55], v[16:19]
	v_mfma_f32_16x16x32_bf16 v[138:141], v[218:221], v[56:59], v[138:141]
	v_mfma_f32_16x16x32_bf16 v[142:145], v[214:217], v[84:87], v[242:245]
	ds_read_b128 v[198:201], v130 offset:288
	ds_read_b128 v[214:217], v130 offset:864
	ds_read_b128 v[202:205], v131 offset:288
	ds_read_b128 v[218:221], v131 offset:864
	s_waitcnt lgkmcnt(4)
	v_mfma_f32_16x16x32_bf16 v[100:103], v[206:209], v[28:31], v[100:103]
	v_mfma_f32_16x16x32_bf16 v[100:103], v[210:213], v[32:35], v[100:103]
	v_mfma_f32_16x16x32_bf16 v[104:107], v[210:213], v[64:67], v[104:107]
	v_mfma_f32_16x16x32_bf16 v[104:107], v[206:209], v[60:63], v[104:107]
	v_mfma_f32_16x16x32_bf16 v[108:111], v[206:209], v[88:91], v[108:111]
	v_mfma_f32_16x16x32_bf16 v[112:115], v[222:225], v[28:31], v[112:115]
	v_mfma_f32_16x16x32_bf16 v[112:115], v[226:229], v[32:35], v[112:115]
	v_mfma_f32_16x16x32_bf16 v[138:141], v[226:229], v[64:67], v[138:141]
	v_mfma_f32_16x16x32_bf16 v[138:141], v[222:225], v[60:63], v[138:141]
	v_mfma_f32_16x16x32_bf16 v[142:145], v[222:225], v[88:91], v[142:145]
	ds_read_b128 v[206:209], v130 offset:432
	ds_read_b128 v[222:225], v130 offset:1008
	ds_read_b128 v[210:213], v131 offset:432
	ds_read_b128 v[226:229], v131 offset:1008
	s_waitcnt lgkmcnt(4)
	v_mfma_f32_16x16x32_bf16 v[100:103], v[198:201], v[36:39], v[100:103]
	v_mfma_f32_16x16x32_bf16 v[100:103], v[202:205], v[40:43], v[100:103]
	v_mfma_f32_16x16x32_bf16 v[104:107], v[202:205], v[72:75], v[104:107]
	v_mfma_f32_16x16x32_bf16 v[104:107], v[198:201], v[68:71], v[104:107]
	v_mfma_f32_16x16x32_bf16 v[108:111], v[198:201], v[92:95], v[108:111]
	v_mfma_f32_16x16x32_bf16 v[112:115], v[214:217], v[36:39], v[112:115]
	v_mfma_f32_16x16x32_bf16 v[112:115], v[218:221], v[40:43], v[112:115]
	v_mfma_f32_16x16x32_bf16 v[138:141], v[218:221], v[72:75], v[138:141]
	v_mfma_f32_16x16x32_bf16 v[138:141], v[214:217], v[68:71], v[138:141]
	v_mfma_f32_16x16x32_bf16 v[142:145], v[214:217], v[92:95], v[142:145]
	s_waitcnt lgkmcnt(0)
	v_mfma_f32_16x16x32_bf16 v[100:103], v[206:209], v[44:47], v[100:103]
	v_mfma_f32_16x16x32_bf16 v[100:103], v[210:213], v[48:51], v[100:103]
	v_mfma_f32_16x16x32_bf16 v[104:107], v[210:213], v[80:83], v[104:107]
	v_mfma_f32_16x16x32_bf16 v[104:107], v[206:209], v[76:79], v[104:107]
	v_mfma_f32_16x16x32_bf16 v[108:111], v[206:209], v[96:99], v[108:111]
	v_mfma_f32_16x16x32_bf16 v[112:115], v[222:225], v[44:47], v[112:115]
	v_mfma_f32_16x16x32_bf16 v[112:115], v[226:229], v[48:51], v[112:115]
	v_mfma_f32_16x16x32_bf16 v[138:141], v[226:229], v[80:83], v[138:141]
	v_mfma_f32_16x16x32_bf16 v[138:141], v[222:225], v[76:79], v[138:141]
	v_mfma_f32_16x16x32_bf16 v[142:145], v[222:225], v[96:99], v[142:145]
	s_waitcnt lgkmcnt(0)
	s_barrier
	s_waitcnt vmcnt(5)
	ds_write_b128 v134, v[146:149]
	ds_write_b128 v134, v[150:153] offset:4608
	ds_write_b128 v135, v[160:163]
	s_add_i32 s64, s4, -1
	s_mul_i32 s71, s64, 0x30000
	s_add_u32 s38, s60, s71
	s_addc_u32 s39, s61, 0
	s_lshl_b32 s64, s64, 12
	v_add_u32_e32 v136, s64, v195
	ds_read_b128 v[116:119], v136
	s_waitcnt vmcnt(3)
	s_waitcnt lgkmcnt(0)
	v_lshlrev_b32_e32 v136, 16, v116
	v_lshlrev_b32_e32 v137, 16, v8
	v_and_b32_e32 v168, 0xffff0000, v116
	v_and_b32_e32 v169, 0xffff0000, v8
	v_mul_f32_e32 v136, v136, v137
	v_mul_f32_e32 v168, v168, v169
	v_cvt_pk_bf16_f32 v116, v136, v168
	v_lshlrev_b32_e32 v136, 16, v117
	v_lshlrev_b32_e32 v137, 16, v9
	v_and_b32_e32 v168, 0xffff0000, v117
	v_and_b32_e32 v169, 0xffff0000, v9
	v_mul_f32_e32 v136, v136, v137
	v_mul_f32_e32 v168, v168, v169
	v_cvt_pk_bf16_f32 v117, v136, v168
	v_lshlrev_b32_e32 v136, 16, v118
	v_lshlrev_b32_e32 v137, 16, v10
	v_and_b32_e32 v168, 0xffff0000, v118
	v_and_b32_e32 v169, 0xffff0000, v10
	v_mul_f32_e32 v136, v136, v137
	v_mul_f32_e32 v168, v168, v169
	v_cvt_pk_bf16_f32 v118, v136, v168
	v_lshlrev_b32_e32 v136, 16, v119
	v_lshlrev_b32_e32 v137, 16, v11
	v_and_b32_e32 v168, 0xffff0000, v119
	v_and_b32_e32 v169, 0xffff0000, v11
	v_mul_f32_e32 v136, v136, v137
	v_mul_f32_e32 v168, v168, v169
	v_cvt_pk_bf16_f32 v119, v136, v168
	global_store_dwordx4 v255, v[116:119], s[38:39]
	s_add_i32 s64, s4, 0
	s_mul_i32 s71, s64, 0x30000
	s_add_u32 s38, s60, s71
	s_addc_u32 s39, s61, 0
	s_lshl_b32 s64, s64, 12
	global_load_dwordx4 v[8:11], v255, s[38:39]
	s_add_i32 s52, s4, 3
	s_min_u32 s52, s52, 31
	s_lshl_b32 s52, s52, 13
	s_add_u32 s26, s50, s52
	s_addc_u32 s27, s51, 0
	global_load_dwordx4 v[146:149], v154, s[26:27]
	global_load_dwordx4 v[150:153], v155, s[26:27]
	global_load_dwordx4 v[160:163], v159, s[26:27]
	v_exp_f32_e32 v198, v100
	v_exp_f32_e32 v199, v101
	v_exp_f32_e32 v200, v102
	v_exp_f32_e32 v201, v103
	v_exp_f32_e32 v202, v112
	v_exp_f32_e32 v203, v113
	v_exp_f32_e32 v204, v114
	v_exp_f32_e32 v205, v115
	v_exp_f32_e32 v214, v104
	v_add_f32_e32 v198, 1.0, v198
	v_exp_f32_e32 v215, v105
	v_add_f32_e32 v199, 1.0, v199
	v_exp_f32_e32 v216, v106
	v_add_f32_e32 v200, 1.0, v200
	v_exp_f32_e32 v217, v107
	v_add_f32_e32 v201, 1.0, v201
	v_exp_f32_e32 v218, v138
	v_add_f32_e32 v202, 1.0, v202
	v_exp_f32_e32 v219, v139
	v_add_f32_e32 v203, 1.0, v203
	v_exp_f32_e32 v220, v140
	v_add_f32_e32 v204, 1.0, v204
	v_exp_f32_e32 v221, v141
	v_add_f32_e32 v205, 1.0, v205
	v_rcp_f32_e32 v198, v198
	v_add_f32_e32 v214, 1.0, v214
	v_rcp_f32_e32 v199, v199
	v_add_f32_e32 v215, 1.0, v215
	v_rcp_f32_e32 v200, v200
	v_add_f32_e32 v216, 1.0, v216
	v_rcp_f32_e32 v201, v201
	v_add_f32_e32 v217, 1.0, v217
	v_rcp_f32_e32 v202, v202
	v_add_f32_e32 v218, 1.0, v218
	v_rcp_f32_e32 v203, v203
	v_add_f32_e32 v219, 1.0, v219
	v_rcp_f32_e32 v204, v204
	v_add_f32_e32 v220, 1.0, v220
	v_rcp_f32_e32 v205, v205
	v_add_f32_e32 v221, 1.0, v221
	v_mul_f32_e32 v198, v179, v198
	v_mul_f32_e32 v199, v179, v199
	v_mul_f32_e32 v200, v179, v200
	v_mul_f32_e32 v201, v179, v201
	v_mul_f32_e32 v202, v179, v202
	v_mul_f32_e32 v203, v179, v203
	v_mul_f32_e32 v204, v179, v204
	v_mul_f32_e32 v205, v179, v205
	v_exp_f32_e32 v120, v198
	v_exp_f32_e32 v121, v199
	v_exp_f32_e32 v122, v200
	v_exp_f32_e32 v123, v201
	v_exp_f32_e32 v124, v202
	v_exp_f32_e32 v125, v203
	v_exp_f32_e32 v126, v204
	v_exp_f32_e32 v127, v205
	v_fma_f32 v206, -v120, v120, 1.0
	v_fma_f32 v207, -v121, v121, 1.0
	v_fma_f32 v208, -v122, v122, 1.0
	v_fma_f32 v209, -v123, v123, 1.0
	v_fma_f32 v210, -v124, v124, 1.0
	v_fma_f32 v211, -v125, v125, 1.0
	v_fma_f32 v212, -v126, v126, 1.0
	v_fma_f32 v213, -v127, v127, 1.0
	v_max_f32_e32 v206, 0xda24260, v206
	v_max_f32_e32 v207, 0xda24260, v207
	v_max_f32_e32 v208, 0xda24260, v208
	v_max_f32_e32 v209, 0xda24260, v209
	v_max_f32_e32 v210, 0xda24260, v210
	v_max_f32_e32 v211, 0xda24260, v211
	v_max_f32_e32 v212, 0xda24260, v212
	v_max_f32_e32 v213, 0xda24260, v213
	v_mul_f32_e32 v198, v214, v206
	v_mul_f32_e32 v199, v215, v207
	v_mul_f32_e32 v200, v216, v208
	v_mul_f32_e32 v201, v217, v209
	v_mul_f32_e32 v202, v218, v210
	v_mul_f32_e32 v203, v219, v211
	v_mul_f32_e32 v204, v220, v212
	v_mul_f32_e32 v205, v221, v213
	v_mul_f32_e32 v214, v214, v198
	v_mul_f32_e32 v215, v215, v199
	v_mul_f32_e32 v216, v216, v200
	v_mul_f32_e32 v217, v217, v201
	v_mul_f32_e32 v218, v218, v202
	v_mul_f32_e32 v219, v219, v203
	v_mul_f32_e32 v220, v220, v204
	v_mul_f32_e32 v221, v221, v205
	v_rsq_f32_e32 v214, v214
	v_mul_f32_e32 v222, v108, v206
	v_rsq_f32_e32 v215, v215
	v_mul_f32_e32 v223, v109, v207
	v_rsq_f32_e32 v216, v216
	v_mul_f32_e32 v224, v110, v208
	v_rsq_f32_e32 v217, v217
	v_mul_f32_e32 v225, v111, v209
	v_rsq_f32_e32 v218, v218
	v_mul_f32_e32 v226, v142, v210
	v_rsq_f32_e32 v219, v219
	v_mul_f32_e32 v227, v143, v211
	v_rsq_f32_e32 v220, v220
	v_mul_f32_e32 v228, v144, v212
	v_rsq_f32_e32 v221, v221
	v_mul_f32_e32 v229, v145, v213
	v_mul_f32_e32 v170, v222, v214
	v_mul_f32_e32 v171, v223, v215
	v_mul_f32_e32 v172, v224, v216
	v_mul_f32_e32 v173, v225, v217
	v_mul_f32_e32 v174, v226, v218
	v_mul_f32_e32 v175, v227, v219
	v_mul_f32_e32 v176, v228, v220
	v_mul_f32_e32 v177, v229, v221
	v_mov_b32_e32 v198, v170
	v_mov_b32_e32 v199, v120
	v_fma_f32 v198, v121, v198, v171
	v_mul_f32_e32 v199, v199, v121
	v_fma_f32 v198, v122, v198, v172
	v_mul_f32_e32 v199, v199, v122
	v_fma_f32 v198, v123, v198, v173
	v_mul_f32_e32 v199, v199, v123
	v_fma_f32 v198, v124, v198, v174
	v_mul_f32_e32 v199, v199, v124
	v_fma_f32 v198, v125, v198, v175
	v_mul_f32_e32 v199, v199, v125
	v_fma_f32 v198, v126, v198, v176
	v_mul_f32_e32 v199, v199, v126
	v_fma_f32 v198, v127, v198, v177
	v_mul_f32_e32 v199, v199, v127
	ds_bpermute_b32 v164, v185, v199 offset:0
	ds_bpermute_b32 v246, v185, v198 offset:0
	ds_bpermute_b32 v165, v185, v199 offset:64
	ds_bpermute_b32 v247, v185, v198 offset:64
	ds_bpermute_b32 v166, v185, v199 offset:128
	ds_bpermute_b32 v248, v185, v198 offset:128
	ds_bpermute_b32 v167, v185, v199 offset:192
	ds_bpermute_b32 v249, v185, v198 offset:192
	s_waitcnt lgkmcnt(0)
	v_mov_b32_e32 v251, v246
	v_mov_b32_e32 v250, v164
	v_fma_f32 v251, v251, v165, v247
	v_mul_f32_e32 v250, v250, v165
	v_fma_f32 v251, v251, v166, v248
	v_mul_f32_e32 v250, v250, v166
	v_fma_f32 v251, v251, v167, v249
	v_mul_f32_e32 v250, v250, v167
	s_mov_b64 exec, s[10:11]
	ds_write_b64 v182, v[250:251] offset:0
	s_mov_b64 exec, -1
	s_waitcnt lgkmcnt(0)
	s_barrier
	ds_read2_b64 v[4:7], v183 offset0:0 offset1:16
	s_add_i32 s52, s4, 0
	s_lshl_b32 s52, s52, 12
	v_add_u32_e32 v197, s52, v184
	s_waitcnt lgkmcnt(0)
	v_fma_f32 v198, v180, v4, v5
	v_cndmask_b32_e64 v199, v180, v198, s[24:25]
	v_fma_f32 v180, v198, v6, v7
	v_fma_f32 v200, v199, v164, v246
	v_cndmask_b32_e64 v199, v199, v200, s[16:17]
	v_fma_f32 v200, v199, v165, v247
	v_cndmask_b32_e64 v199, v199, v200, s[20:21]
	v_fma_f32 v200, v199, v166, v248
	v_cndmask_b32_e64 v199, v199, v200, s[22:23]
	v_fma_f32 v214, v120, v199, v170
	v_fma_f32 v215, v121, v214, v171
	v_fma_f32 v216, v122, v215, v172
	v_fma_f32 v217, v123, v216, v173
	v_fma_f32 v218, v124, v217, v174
	v_fma_f32 v219, v125, v218, v175
	v_fma_f32 v220, v126, v219, v176
	v_fma_f32 v221, v127, v220, v177
	ds_read_u16 v206, v197 offset:0
	ds_read_u16 v207, v197 offset:64
	ds_read_u16 v208, v197 offset:128
	ds_read_u16 v209, v197 offset:192
	ds_read_u16 v210, v197 offset:256
	ds_read_u16 v211, v197 offset:320
	ds_read_u16 v212, v197 offset:384
	ds_read_u16 v213, v197 offset:448
	s_waitcnt lgkmcnt(0)
	v_lshlrev_b32_e32 v206, 16, v206
	v_lshlrev_b32_e32 v207, 16, v207
	v_lshlrev_b32_e32 v208, 16, v208
	v_lshlrev_b32_e32 v209, 16, v209
	v_lshlrev_b32_e32 v210, 16, v210
	v_lshlrev_b32_e32 v211, 16, v211
	v_lshlrev_b32_e32 v212, 16, v212
	v_lshlrev_b32_e32 v213, 16, v213
	v_add_f32_e32 v214, v214, v206
	v_add_f32_e32 v215, v215, v207
	v_add_f32_e32 v216, v216, v208
	v_add_f32_e32 v217, v217, v209
	v_add_f32_e32 v218, v218, v210
	v_add_f32_e32 v219, v219, v211
	v_add_f32_e32 v220, v220, v212
	v_add_f32_e32 v221, v221, v213
	v_cvt_pk_bf16_f32 v206, v214, v215
	v_cvt_pk_bf16_f32 v208, v216, v217
	v_cvt_pk_bf16_f32 v210, v218, v219
	v_cvt_pk_bf16_f32 v212, v220, v221
	ds_write_b16 v197, v206 offset:0
	ds_write_b16_d16_hi v197, v206 offset:64
	ds_write_b16 v197, v208 offset:128
	ds_write_b16_d16_hi v197, v208 offset:192
	ds_write_b16 v197, v210 offset:256
	ds_write_b16_d16_hi v197, v210 offset:320
	ds_write_b16 v197, v212 offset:384
	ds_write_b16_d16_hi v197, v212 offset:448
	ds_read_b128 v[198:201], v130 offset:0
	ds_read_b128 v[214:217], v130 offset:576
	ds_read_b128 v[202:205], v131 offset:0
	ds_read_b128 v[218:221], v131 offset:576
	ds_read_b128 v[206:209], v130 offset:144
	ds_read_b128 v[222:225], v130 offset:720
	ds_read_b128 v[210:213], v131 offset:144
	s_waitcnt lgkmcnt(14)
	ds_read_b128 v[226:229], v131 offset:720
	s_waitcnt lgkmcnt(4)
	v_mfma_f32_16x16x32_bf16 v[100:103], v[198:201], v[20:23], v[12:15]
	v_mfma_f32_16x16x32_bf16 v[100:103], v[202:205], v[24:27], v[100:103]
	v_mfma_f32_16x16x32_bf16 v[104:107], v[198:201], v[52:55], v[16:19]
	v_mfma_f32_16x16x32_bf16 v[104:107], v[202:205], v[56:59], v[104:107]
	v_mfma_f32_16x16x32_bf16 v[108:111], v[198:201], v[84:87], v[242:245]
	v_mfma_f32_16x16x32_bf16 v[112:115], v[214:217], v[20:23], v[12:15]
	v_mfma_f32_16x16x32_bf16 v[112:115], v[218:221], v[24:27], v[112:115]
	v_mfma_f32_16x16x32_bf16 v[138:141], v[214:217], v[52:55], v[16:19]
	v_mfma_f32_16x16x32_bf16 v[138:141], v[218:221], v[56:59], v[138:141]
	v_mfma_f32_16x16x32_bf16 v[142:145], v[214:217], v[84:87], v[242:245]
	ds_read_b128 v[198:201], v130 offset:288
	ds_read_b128 v[214:217], v130 offset:864
	ds_read_b128 v[202:205], v131 offset:288
	ds_read_b128 v[218:221], v131 offset:864
	s_waitcnt lgkmcnt(4)
	v_mfma_f32_16x16x32_bf16 v[100:103], v[206:209], v[28:31], v[100:103]
	v_mfma_f32_16x16x32_bf16 v[100:103], v[210:213], v[32:35], v[100:103]
	v_mfma_f32_16x16x32_bf16 v[104:107], v[210:213], v[64:67], v[104:107]
	v_mfma_f32_16x16x32_bf16 v[104:107], v[206:209], v[60:63], v[104:107]
	v_mfma_f32_16x16x32_bf16 v[108:111], v[206:209], v[88:91], v[108:111]
	v_mfma_f32_16x16x32_bf16 v[112:115], v[222:225], v[28:31], v[112:115]
	v_mfma_f32_16x16x32_bf16 v[112:115], v[226:229], v[32:35], v[112:115]
	v_mfma_f32_16x16x32_bf16 v[138:141], v[226:229], v[64:67], v[138:141]
	v_mfma_f32_16x16x32_bf16 v[138:141], v[222:225], v[60:63], v[138:141]
	v_mfma_f32_16x16x32_bf16 v[142:145], v[222:225], v[88:91], v[142:145]
	ds_read_b128 v[206:209], v130 offset:432
	ds_read_b128 v[222:225], v130 offset:1008
	ds_read_b128 v[210:213], v131 offset:432
	ds_read_b128 v[226:229], v131 offset:1008
	s_waitcnt lgkmcnt(4)
	v_mfma_f32_16x16x32_bf16 v[100:103], v[198:201], v[36:39], v[100:103]
	v_mfma_f32_16x16x32_bf16 v[100:103], v[202:205], v[40:43], v[100:103]
	v_mfma_f32_16x16x32_bf16 v[104:107], v[202:205], v[72:75], v[104:107]
	v_mfma_f32_16x16x32_bf16 v[104:107], v[198:201], v[68:71], v[104:107]
	v_mfma_f32_16x16x32_bf16 v[108:111], v[198:201], v[92:95], v[108:111]
	v_mfma_f32_16x16x32_bf16 v[112:115], v[214:217], v[36:39], v[112:115]
	v_mfma_f32_16x16x32_bf16 v[112:115], v[218:221], v[40:43], v[112:115]
	v_mfma_f32_16x16x32_bf16 v[138:141], v[218:221], v[72:75], v[138:141]
	v_mfma_f32_16x16x32_bf16 v[138:141], v[214:217], v[68:71], v[138:141]
	v_mfma_f32_16x16x32_bf16 v[142:145], v[214:217], v[92:95], v[142:145]
	s_waitcnt lgkmcnt(0)
	v_mfma_f32_16x16x32_bf16 v[100:103], v[206:209], v[44:47], v[100:103]
	v_mfma_f32_16x16x32_bf16 v[100:103], v[210:213], v[48:51], v[100:103]
	v_mfma_f32_16x16x32_bf16 v[104:107], v[210:213], v[80:83], v[104:107]
	v_mfma_f32_16x16x32_bf16 v[104:107], v[206:209], v[76:79], v[104:107]
	v_mfma_f32_16x16x32_bf16 v[108:111], v[206:209], v[96:99], v[108:111]
	v_mfma_f32_16x16x32_bf16 v[112:115], v[222:225], v[44:47], v[112:115]
	v_mfma_f32_16x16x32_bf16 v[112:115], v[226:229], v[48:51], v[112:115]
	v_mfma_f32_16x16x32_bf16 v[138:141], v[226:229], v[80:83], v[138:141]
	v_mfma_f32_16x16x32_bf16 v[138:141], v[222:225], v[76:79], v[138:141]
	v_mfma_f32_16x16x32_bf16 v[142:145], v[222:225], v[96:99], v[142:145]
	s_waitcnt lgkmcnt(0)
	s_barrier
	s_waitcnt vmcnt(5)
	ds_write_b128 v134, v[230:233]
	ds_write_b128 v134, v[234:237] offset:4608
	ds_write_b128 v135, v[238:241]
	s_add_i32 s64, s4, 0
	s_mul_i32 s71, s64, 0x30000
	s_add_u32 s38, s60, s71
	s_addc_u32 s39, s61, 0
	s_lshl_b32 s64, s64, 12
	v_add_u32_e32 v136, s64, v195
	ds_read_b128 v[116:119], v136
	s_waitcnt vmcnt(3)
	s_waitcnt lgkmcnt(0)
	v_lshlrev_b32_e32 v136, 16, v116
	v_lshlrev_b32_e32 v137, 16, v8
	v_and_b32_e32 v168, 0xffff0000, v116
	v_and_b32_e32 v169, 0xffff0000, v8
	v_mul_f32_e32 v136, v136, v137
	v_mul_f32_e32 v168, v168, v169
	v_cvt_pk_bf16_f32 v116, v136, v168
	v_lshlrev_b32_e32 v136, 16, v117
	v_lshlrev_b32_e32 v137, 16, v9
	v_and_b32_e32 v168, 0xffff0000, v117
	v_and_b32_e32 v169, 0xffff0000, v9
	v_mul_f32_e32 v136, v136, v137
	v_mul_f32_e32 v168, v168, v169
	v_cvt_pk_bf16_f32 v117, v136, v168
	v_lshlrev_b32_e32 v136, 16, v118
	v_lshlrev_b32_e32 v137, 16, v10
	v_and_b32_e32 v168, 0xffff0000, v118
	v_and_b32_e32 v169, 0xffff0000, v10
	v_mul_f32_e32 v136, v136, v137
	v_mul_f32_e32 v168, v168, v169
	v_cvt_pk_bf16_f32 v118, v136, v168
	v_lshlrev_b32_e32 v136, 16, v119
	v_lshlrev_b32_e32 v137, 16, v11
	v_and_b32_e32 v168, 0xffff0000, v119
	v_and_b32_e32 v169, 0xffff0000, v11
	v_mul_f32_e32 v136, v136, v137
	v_mul_f32_e32 v168, v168, v169
	v_cvt_pk_bf16_f32 v119, v136, v168
	global_store_dwordx4 v255, v[116:119], s[38:39]
	s_add_i32 s64, s4, 1
	s_mul_i32 s71, s64, 0x30000
	s_add_u32 s38, s60, s71
	s_addc_u32 s39, s61, 0
	s_lshl_b32 s64, s64, 12
	global_load_dwordx4 v[8:11], v255, s[38:39]
	s_add_i32 s52, s4, 4
	s_min_u32 s52, s52, 31
	s_lshl_b32 s52, s52, 13
	s_add_u32 s26, s50, s52
	s_addc_u32 s27, s51, 0
	global_load_dwordx4 v[230:233], v154, s[26:27]
	global_load_dwordx4 v[234:237], v155, s[26:27]
	global_load_dwordx4 v[238:241], v159, s[26:27]
	v_exp_f32_e32 v198, v100
	v_exp_f32_e32 v199, v101
	v_exp_f32_e32 v200, v102
	v_exp_f32_e32 v201, v103
	v_exp_f32_e32 v202, v112
	v_exp_f32_e32 v203, v113
	v_exp_f32_e32 v204, v114
	v_exp_f32_e32 v205, v115
	v_exp_f32_e32 v214, v104
	v_add_f32_e32 v198, 1.0, v198
	v_exp_f32_e32 v215, v105
	v_add_f32_e32 v199, 1.0, v199
	v_exp_f32_e32 v216, v106
	v_add_f32_e32 v200, 1.0, v200
	v_exp_f32_e32 v217, v107
	v_add_f32_e32 v201, 1.0, v201
	v_exp_f32_e32 v218, v138
	v_add_f32_e32 v202, 1.0, v202
	v_exp_f32_e32 v219, v139
	v_add_f32_e32 v203, 1.0, v203
	v_exp_f32_e32 v220, v140
	v_add_f32_e32 v204, 1.0, v204
	v_exp_f32_e32 v221, v141
	v_add_f32_e32 v205, 1.0, v205
	v_rcp_f32_e32 v198, v198
	v_add_f32_e32 v214, 1.0, v214
	v_rcp_f32_e32 v199, v199
	v_add_f32_e32 v215, 1.0, v215
	v_rcp_f32_e32 v200, v200
	v_add_f32_e32 v216, 1.0, v216
	v_rcp_f32_e32 v201, v201
	v_add_f32_e32 v217, 1.0, v217
	v_rcp_f32_e32 v202, v202
	v_add_f32_e32 v218, 1.0, v218
	v_rcp_f32_e32 v203, v203
	v_add_f32_e32 v219, 1.0, v219
	v_rcp_f32_e32 v204, v204
	v_add_f32_e32 v220, 1.0, v220
	v_rcp_f32_e32 v205, v205
	v_add_f32_e32 v221, 1.0, v221
	v_mul_f32_e32 v198, v179, v198
	v_mul_f32_e32 v199, v179, v199
	v_mul_f32_e32 v200, v179, v200
	v_mul_f32_e32 v201, v179, v201
	v_mul_f32_e32 v202, v179, v202
	v_mul_f32_e32 v203, v179, v203
	v_mul_f32_e32 v204, v179, v204
	v_mul_f32_e32 v205, v179, v205
	v_exp_f32_e32 v120, v198
	v_exp_f32_e32 v121, v199
	v_exp_f32_e32 v122, v200
	v_exp_f32_e32 v123, v201
	v_exp_f32_e32 v124, v202
	v_exp_f32_e32 v125, v203
	v_exp_f32_e32 v126, v204
	v_exp_f32_e32 v127, v205
	v_fma_f32 v206, -v120, v120, 1.0
	v_fma_f32 v207, -v121, v121, 1.0
	v_fma_f32 v208, -v122, v122, 1.0
	v_fma_f32 v209, -v123, v123, 1.0
	v_fma_f32 v210, -v124, v124, 1.0
	v_fma_f32 v211, -v125, v125, 1.0
	v_fma_f32 v212, -v126, v126, 1.0
	v_fma_f32 v213, -v127, v127, 1.0
	v_max_f32_e32 v206, 0xda24260, v206
	v_max_f32_e32 v207, 0xda24260, v207
	v_max_f32_e32 v208, 0xda24260, v208
	v_max_f32_e32 v209, 0xda24260, v209
	v_max_f32_e32 v210, 0xda24260, v210
	v_max_f32_e32 v211, 0xda24260, v211
	v_max_f32_e32 v212, 0xda24260, v212
	v_max_f32_e32 v213, 0xda24260, v213
	v_mul_f32_e32 v198, v214, v206
	v_mul_f32_e32 v199, v215, v207
	v_mul_f32_e32 v200, v216, v208
	v_mul_f32_e32 v201, v217, v209
	v_mul_f32_e32 v202, v218, v210
	v_mul_f32_e32 v203, v219, v211
	v_mul_f32_e32 v204, v220, v212
	v_mul_f32_e32 v205, v221, v213
	v_mul_f32_e32 v214, v214, v198
	v_mul_f32_e32 v215, v215, v199
	v_mul_f32_e32 v216, v216, v200
	v_mul_f32_e32 v217, v217, v201
	v_mul_f32_e32 v218, v218, v202
	v_mul_f32_e32 v219, v219, v203
	v_mul_f32_e32 v220, v220, v204
	v_mul_f32_e32 v221, v221, v205
	v_rsq_f32_e32 v214, v214
	v_mul_f32_e32 v222, v108, v206
	v_rsq_f32_e32 v215, v215
	v_mul_f32_e32 v223, v109, v207
	v_rsq_f32_e32 v216, v216
	v_mul_f32_e32 v224, v110, v208
	v_rsq_f32_e32 v217, v217
	v_mul_f32_e32 v225, v111, v209
	v_rsq_f32_e32 v218, v218
	v_mul_f32_e32 v226, v142, v210
	v_rsq_f32_e32 v219, v219
	v_mul_f32_e32 v227, v143, v211
	v_rsq_f32_e32 v220, v220
	v_mul_f32_e32 v228, v144, v212
	v_rsq_f32_e32 v221, v221
	v_mul_f32_e32 v229, v145, v213
	v_mul_f32_e32 v170, v222, v214
	v_mul_f32_e32 v171, v223, v215
	v_mul_f32_e32 v172, v224, v216
	v_mul_f32_e32 v173, v225, v217
	v_mul_f32_e32 v174, v226, v218
	v_mul_f32_e32 v175, v227, v219
	v_mul_f32_e32 v176, v228, v220
	v_mul_f32_e32 v177, v229, v221
	v_mov_b32_e32 v198, v170
	v_mov_b32_e32 v199, v120
	v_fma_f32 v198, v121, v198, v171
	v_mul_f32_e32 v199, v199, v121
	v_fma_f32 v198, v122, v198, v172
	v_mul_f32_e32 v199, v199, v122
	v_fma_f32 v198, v123, v198, v173
	v_mul_f32_e32 v199, v199, v123
	v_fma_f32 v198, v124, v198, v174
	v_mul_f32_e32 v199, v199, v124
	v_fma_f32 v198, v125, v198, v175
	v_mul_f32_e32 v199, v199, v125
	v_fma_f32 v198, v126, v198, v176
	v_mul_f32_e32 v199, v199, v126
	v_fma_f32 v198, v127, v198, v177
	v_mul_f32_e32 v199, v199, v127
	ds_bpermute_b32 v164, v185, v199 offset:0
	ds_bpermute_b32 v246, v185, v198 offset:0
	ds_bpermute_b32 v165, v185, v199 offset:64
	ds_bpermute_b32 v247, v185, v198 offset:64
	ds_bpermute_b32 v166, v185, v199 offset:128
	ds_bpermute_b32 v248, v185, v198 offset:128
	ds_bpermute_b32 v167, v185, v199 offset:192
	ds_bpermute_b32 v249, v185, v198 offset:192
	s_waitcnt lgkmcnt(0)
	v_mov_b32_e32 v251, v246
	v_mov_b32_e32 v250, v164
	v_fma_f32 v251, v251, v165, v247
	v_mul_f32_e32 v250, v250, v165
	v_fma_f32 v251, v251, v166, v248
	v_mul_f32_e32 v250, v250, v166
	v_fma_f32 v251, v251, v167, v249
	v_mul_f32_e32 v250, v250, v167
	s_mov_b64 exec, s[10:11]
	ds_write_b64 v182, v[250:251] offset:1024
	s_mov_b64 exec, -1
	s_waitcnt lgkmcnt(0)
	s_barrier
	ds_read2_b64 v[4:7], v183 offset0:128 offset1:144
	s_add_i32 s52, s4, 1
	s_lshl_b32 s52, s52, 12
	v_add_u32_e32 v197, s52, v184
	s_waitcnt lgkmcnt(0)
	v_fma_f32 v198, v180, v4, v5
	v_cndmask_b32_e64 v199, v180, v198, s[24:25]
	v_fma_f32 v180, v198, v6, v7
	v_fma_f32 v200, v199, v164, v246
	v_cndmask_b32_e64 v199, v199, v200, s[16:17]
	v_fma_f32 v200, v199, v165, v247
	v_cndmask_b32_e64 v199, v199, v200, s[20:21]
	v_fma_f32 v200, v199, v166, v248
	v_cndmask_b32_e64 v199, v199, v200, s[22:23]
	v_fma_f32 v214, v120, v199, v170
	v_fma_f32 v215, v121, v214, v171
	v_fma_f32 v216, v122, v215, v172
	v_fma_f32 v217, v123, v216, v173
	v_fma_f32 v218, v124, v217, v174
	v_fma_f32 v219, v125, v218, v175
	v_fma_f32 v220, v126, v219, v176
	v_fma_f32 v221, v127, v220, v177
	ds_read_u16 v206, v197 offset:0
	ds_read_u16 v207, v197 offset:64
	ds_read_u16 v208, v197 offset:128
	ds_read_u16 v209, v197 offset:192
	ds_read_u16 v210, v197 offset:256
	ds_read_u16 v211, v197 offset:320
	ds_read_u16 v212, v197 offset:384
	ds_read_u16 v213, v197 offset:448
	s_waitcnt lgkmcnt(0)
	v_lshlrev_b32_e32 v206, 16, v206
	v_lshlrev_b32_e32 v207, 16, v207
	v_lshlrev_b32_e32 v208, 16, v208
	v_lshlrev_b32_e32 v209, 16, v209
	v_lshlrev_b32_e32 v210, 16, v210
	v_lshlrev_b32_e32 v211, 16, v211
	v_lshlrev_b32_e32 v212, 16, v212
	v_lshlrev_b32_e32 v213, 16, v213
	v_add_f32_e32 v214, v214, v206
	v_add_f32_e32 v215, v215, v207
	v_add_f32_e32 v216, v216, v208
	v_add_f32_e32 v217, v217, v209
	v_add_f32_e32 v218, v218, v210
	v_add_f32_e32 v219, v219, v211
	v_add_f32_e32 v220, v220, v212
	v_add_f32_e32 v221, v221, v213
	v_cvt_pk_bf16_f32 v206, v214, v215
	v_cvt_pk_bf16_f32 v208, v216, v217
	v_cvt_pk_bf16_f32 v210, v218, v219
	v_cvt_pk_bf16_f32 v212, v220, v221
	ds_write_b16 v197, v206 offset:0
	ds_write_b16_d16_hi v197, v206 offset:64
	ds_write_b16 v197, v208 offset:128
	ds_write_b16_d16_hi v197, v208 offset:192
	ds_write_b16 v197, v210 offset:256
	ds_write_b16_d16_hi v197, v210 offset:320
	ds_write_b16 v197, v212 offset:384
	ds_write_b16_d16_hi v197, v212 offset:448
	s_add_i32 s4, s4, 2
	s_cmp_lt_u32 s4, 32
	s_cbranch_scc1 .Lrec2_loopB_d0
	s_waitcnt lgkmcnt(0)
	s_barrier
	s_add_i32 s64, s4, -1
	s_mul_i32 s71, s64, 0x30000
	s_add_u32 s38, s60, s71
	s_addc_u32 s39, s61, 0
	s_lshl_b32 s64, s64, 12
	v_add_u32_e32 v136, s64, v195
	ds_read_b128 v[116:119], v136
	s_waitcnt vmcnt(3)
	s_waitcnt lgkmcnt(0)
	v_lshlrev_b32_e32 v136, 16, v116
	v_lshlrev_b32_e32 v137, 16, v8
	v_and_b32_e32 v168, 0xffff0000, v116
	v_and_b32_e32 v169, 0xffff0000, v8
	v_mul_f32_e32 v136, v136, v137
	v_mul_f32_e32 v168, v168, v169
	v_cvt_pk_bf16_f32 v116, v136, v168
	v_lshlrev_b32_e32 v136, 16, v117
	v_lshlrev_b32_e32 v137, 16, v9
	v_and_b32_e32 v168, 0xffff0000, v117
	v_and_b32_e32 v169, 0xffff0000, v9
	v_mul_f32_e32 v136, v136, v137
	v_mul_f32_e32 v168, v168, v169
	v_cvt_pk_bf16_f32 v117, v136, v168
	v_lshlrev_b32_e32 v136, 16, v118
	v_lshlrev_b32_e32 v137, 16, v10
	v_and_b32_e32 v168, 0xffff0000, v118
	v_and_b32_e32 v169, 0xffff0000, v10
	v_mul_f32_e32 v136, v136, v137
	v_mul_f32_e32 v168, v168, v169
	v_cvt_pk_bf16_f32 v118, v136, v168
	v_lshlrev_b32_e32 v136, 16, v119
	v_lshlrev_b32_e32 v137, 16, v11
	v_and_b32_e32 v168, 0xffff0000, v119
	v_and_b32_e32 v169, 0xffff0000, v11
	v_mul_f32_e32 v136, v136, v137
	v_mul_f32_e32 v168, v168, v169
	v_cvt_pk_bf16_f32 v119, v136, v168
	global_store_dwordx4 v255, v[116:119], s[38:39]
	s_barrier
	s_branch .Lrec2_done

.Lrec2_loopA_d1:
	ds_read_b128 v[198:201], v130 offset:0
	ds_read_b128 v[214:217], v130 offset:576
	ds_read_b128 v[202:205], v131 offset:0
	ds_read_b128 v[218:221], v131 offset:576
	ds_read_b128 v[206:209], v130 offset:144
	ds_read_b128 v[222:225], v130 offset:720
	ds_read_b128 v[210:213], v131 offset:144
	s_waitcnt lgkmcnt(14)
	ds_read_b128 v[226:229], v131 offset:720
	s_waitcnt lgkmcnt(4)
	v_mfma_f32_16x16x32_bf16 v[100:103], v[198:201], v[20:23], v[12:15]
	v_mfma_f32_16x16x32_bf16 v[100:103], v[202:205], v[24:27], v[100:103]
	v_mfma_f32_16x16x32_bf16 v[104:107], v[198:201], v[52:55], v[16:19]
	v_mfma_f32_16x16x32_bf16 v[104:107], v[202:205], v[56:59], v[104:107]
	v_mfma_f32_16x16x32_bf16 v[108:111], v[198:201], v[84:87], v[242:245]
	v_mfma_f32_16x16x32_bf16 v[112:115], v[214:217], v[20:23], v[12:15]
	v_mfma_f32_16x16x32_bf16 v[112:115], v[218:221], v[24:27], v[112:115]
	v_mfma_f32_16x16x32_bf16 v[138:141], v[214:217], v[52:55], v[16:19]
	v_mfma_f32_16x16x32_bf16 v[138:141], v[218:221], v[56:59], v[138:141]
	v_mfma_f32_16x16x32_bf16 v[142:145], v[214:217], v[84:87], v[242:245]
	ds_read_b128 v[198:201], v130 offset:288
	ds_read_b128 v[214:217], v130 offset:864
	ds_read_b128 v[202:205], v131 offset:288
	ds_read_b128 v[218:221], v131 offset:864
	s_waitcnt lgkmcnt(4)
	v_mfma_f32_16x16x32_bf16 v[100:103], v[206:209], v[28:31], v[100:103]
	v_mfma_f32_16x16x32_bf16 v[100:103], v[210:213], v[32:35], v[100:103]
	v_mfma_f32_16x16x32_bf16 v[104:107], v[210:213], v[64:67], v[104:107]
	v_mfma_f32_16x16x32_bf16 v[104:107], v[206:209], v[60:63], v[104:107]
	v_mfma_f32_16x16x32_bf16 v[108:111], v[206:209], v[88:91], v[108:111]
	v_mfma_f32_16x16x32_bf16 v[112:115], v[222:225], v[28:31], v[112:115]
	v_mfma_f32_16x16x32_bf16 v[112:115], v[226:229], v[32:35], v[112:115]
	v_mfma_f32_16x16x32_bf16 v[138:141], v[226:229], v[64:67], v[138:141]
	v_mfma_f32_16x16x32_bf16 v[138:141], v[222:225], v[60:63], v[138:141]
	v_mfma_f32_16x16x32_bf16 v[142:145], v[222:225], v[88:91], v[142:145]
	ds_read_b128 v[206:209], v130 offset:432
	ds_read_b128 v[222:225], v130 offset:1008
	ds_read_b128 v[210:213], v131 offset:432
	ds_read_b128 v[226:229], v131 offset:1008
	s_waitcnt lgkmcnt(4)
	v_mfma_f32_16x16x32_bf16 v[100:103], v[198:201], v[36:39], v[100:103]
	v_mfma_f32_16x16x32_bf16 v[100:103], v[202:205], v[40:43], v[100:103]
	v_mfma_f32_16x16x32_bf16 v[104:107], v[202:205], v[72:75], v[104:107]
	v_mfma_f32_16x16x32_bf16 v[104:107], v[198:201], v[68:71], v[104:107]
	v_mfma_f32_16x16x32_bf16 v[108:111], v[198:201], v[92:95], v[108:111]
	v_mfma_f32_16x16x32_bf16 v[112:115], v[214:217], v[36:39], v[112:115]
	v_mfma_f32_16x16x32_bf16 v[112:115], v[218:221], v[40:43], v[112:115]
	v_mfma_f32_16x16x32_bf16 v[138:141], v[218:221], v[72:75], v[138:141]
	v_mfma_f32_16x16x32_bf16 v[138:141], v[214:217], v[68:71], v[138:141]
	v_mfma_f32_16x16x32_bf16 v[142:145], v[214:217], v[92:95], v[142:145]
	s_waitcnt lgkmcnt(0)
	v_mfma_f32_16x16x32_bf16 v[100:103], v[206:209], v[44:47], v[100:103]
	v_mfma_f32_16x16x32_bf16 v[100:103], v[210:213], v[48:51], v[100:103]
	v_mfma_f32_16x16x32_bf16 v[104:107], v[210:213], v[80:83], v[104:107]
	v_mfma_f32_16x16x32_bf16 v[104:107], v[206:209], v[76:79], v[104:107]
	v_mfma_f32_16x16x32_bf16 v[108:111], v[206:209], v[96:99], v[108:111]
	v_mfma_f32_16x16x32_bf16 v[112:115], v[222:225], v[44:47], v[112:115]
	v_mfma_f32_16x16x32_bf16 v[112:115], v[226:229], v[48:51], v[112:115]
	v_mfma_f32_16x16x32_bf16 v[138:141], v[226:229], v[80:83], v[138:141]
	v_mfma_f32_16x16x32_bf16 v[138:141], v[222:225], v[76:79], v[138:141]
	v_mfma_f32_16x16x32_bf16 v[142:145], v[222:225], v[96:99], v[142:145]
	s_waitcnt lgkmcnt(0)
	s_barrier
	s_waitcnt vmcnt(3)
	ds_write_b128 v134, v[146:149]
	ds_write_b128 v134, v[150:153] offset:4608
	ds_write_b128 v135, v[160:163]
	s_add_i32 s52, s4, 3
	s_min_u32 s52, s52, 31
	s_sub_i32 s52, 31, s52
	s_lshl_b32 s52, s52, 13
	s_add_u32 s26, s50, s52
	s_addc_u32 s27, s51, 0
	global_load_dwordx4 v[146:149], v154, s[26:27]
	global_load_dwordx4 v[150:153], v155, s[26:27]
	global_load_dwordx4 v[160:163], v159, s[26:27]
	v_exp_f32_e32 v198, v100
	v_exp_f32_e32 v199, v101
	v_exp_f32_e32 v200, v102
	v_exp_f32_e32 v201, v103
	v_exp_f32_e32 v202, v112
	v_exp_f32_e32 v203, v113
	v_exp_f32_e32 v204, v114
	v_exp_f32_e32 v205, v115
	v_exp_f32_e32 v214, v104
	v_add_f32_e32 v198, 1.0, v198
	v_exp_f32_e32 v215, v105
	v_add_f32_e32 v199, 1.0, v199
	v_exp_f32_e32 v216, v106
	v_add_f32_e32 v200, 1.0, v200
	v_exp_f32_e32 v217, v107
	v_add_f32_e32 v201, 1.0, v201
	v_exp_f32_e32 v218, v138
	v_add_f32_e32 v202, 1.0, v202
	v_exp_f32_e32 v219, v139
	v_add_f32_e32 v203, 1.0, v203
	v_exp_f32_e32 v220, v140
	v_add_f32_e32 v204, 1.0, v204
	v_exp_f32_e32 v221, v141
	v_add_f32_e32 v205, 1.0, v205
	v_rcp_f32_e32 v198, v198
	v_add_f32_e32 v214, 1.0, v214
	v_rcp_f32_e32 v199, v199
	v_add_f32_e32 v215, 1.0, v215
	v_rcp_f32_e32 v200, v200
	v_add_f32_e32 v216, 1.0, v216
	v_rcp_f32_e32 v201, v201
	v_add_f32_e32 v217, 1.0, v217
	v_rcp_f32_e32 v202, v202
	v_add_f32_e32 v218, 1.0, v218
	v_rcp_f32_e32 v203, v203
	v_add_f32_e32 v219, 1.0, v219
	v_rcp_f32_e32 v204, v204
	v_add_f32_e32 v220, 1.0, v220
	v_rcp_f32_e32 v205, v205
	v_add_f32_e32 v221, 1.0, v221
	v_mul_f32_e32 v198, v179, v198
	v_mul_f32_e32 v199, v179, v199
	v_mul_f32_e32 v200, v179, v200
	v_mul_f32_e32 v201, v179, v201
	v_mul_f32_e32 v202, v179, v202
	v_mul_f32_e32 v203, v179, v203
	v_mul_f32_e32 v204, v179, v204
	v_mul_f32_e32 v205, v179, v205
	v_exp_f32_e32 v120, v198
	v_exp_f32_e32 v121, v199
	v_exp_f32_e32 v122, v200
	v_exp_f32_e32 v123, v201
	v_exp_f32_e32 v124, v202
	v_exp_f32_e32 v125, v203
	v_exp_f32_e32 v126, v204
	v_exp_f32_e32 v127, v205
	v_fma_f32 v206, -v120, v120, 1.0
	v_fma_f32 v207, -v121, v121, 1.0
	v_fma_f32 v208, -v122, v122, 1.0
	v_fma_f32 v209, -v123, v123, 1.0
	v_fma_f32 v210, -v124, v124, 1.0
	v_fma_f32 v211, -v125, v125, 1.0
	v_fma_f32 v212, -v126, v126, 1.0
	v_fma_f32 v213, -v127, v127, 1.0
	v_max_f32_e32 v206, 0xda24260, v206
	v_max_f32_e32 v207, 0xda24260, v207
	v_max_f32_e32 v208, 0xda24260, v208
	v_max_f32_e32 v209, 0xda24260, v209
	v_max_f32_e32 v210, 0xda24260, v210
	v_max_f32_e32 v211, 0xda24260, v211
	v_max_f32_e32 v212, 0xda24260, v212
	v_max_f32_e32 v213, 0xda24260, v213
	v_mul_f32_e32 v198, v214, v206
	v_mul_f32_e32 v199, v215, v207
	v_mul_f32_e32 v200, v216, v208
	v_mul_f32_e32 v201, v217, v209
	v_mul_f32_e32 v202, v218, v210
	v_mul_f32_e32 v203, v219, v211
	v_mul_f32_e32 v204, v220, v212
	v_mul_f32_e32 v205, v221, v213
	v_mul_f32_e32 v214, v214, v198
	v_mul_f32_e32 v215, v215, v199
	v_mul_f32_e32 v216, v216, v200
	v_mul_f32_e32 v217, v217, v201
	v_mul_f32_e32 v218, v218, v202
	v_mul_f32_e32 v219, v219, v203
	v_mul_f32_e32 v220, v220, v204
	v_mul_f32_e32 v221, v221, v205
	v_rsq_f32_e32 v214, v214
	v_mul_f32_e32 v222, v108, v206
	v_rsq_f32_e32 v215, v215
	v_mul_f32_e32 v223, v109, v207
	v_rsq_f32_e32 v216, v216
	v_mul_f32_e32 v224, v110, v208
	v_rsq_f32_e32 v217, v217
	v_mul_f32_e32 v225, v111, v209
	v_rsq_f32_e32 v218, v218
	v_mul_f32_e32 v226, v142, v210
	v_rsq_f32_e32 v219, v219
	v_mul_f32_e32 v227, v143, v211
	v_rsq_f32_e32 v220, v220
	v_mul_f32_e32 v228, v144, v212
	v_rsq_f32_e32 v221, v221
	v_mul_f32_e32 v229, v145, v213
	v_mul_f32_e32 v170, v222, v214
	v_mul_f32_e32 v171, v223, v215
	v_mul_f32_e32 v172, v224, v216
	v_mul_f32_e32 v173, v225, v217
	v_mul_f32_e32 v174, v226, v218
	v_mul_f32_e32 v175, v227, v219
	v_mul_f32_e32 v176, v228, v220
	v_mul_f32_e32 v177, v229, v221
	v_mov_b32_e32 v198, v177
	v_mov_b32_e32 v199, v127
	v_fma_f32 v198, v126, v198, v176
	v_mul_f32_e32 v199, v199, v126
	v_fma_f32 v198, v125, v198, v175
	v_mul_f32_e32 v199, v199, v125
	v_fma_f32 v198, v124, v198, v174
	v_mul_f32_e32 v199, v199, v124
	v_fma_f32 v198, v123, v198, v173
	v_mul_f32_e32 v199, v199, v123
	v_fma_f32 v198, v122, v198, v172
	v_mul_f32_e32 v199, v199, v122
	v_fma_f32 v198, v121, v198, v171
	v_mul_f32_e32 v199, v199, v121
	v_fma_f32 v198, v120, v198, v170
	v_mul_f32_e32 v199, v199, v120
	ds_bpermute_b32 v164, v185, v199 offset:0
	ds_bpermute_b32 v246, v185, v198 offset:0
	ds_bpermute_b32 v165, v185, v199 offset:64
	ds_bpermute_b32 v247, v185, v198 offset:64
	ds_bpermute_b32 v166, v185, v199 offset:128
	ds_bpermute_b32 v248, v185, v198 offset:128
	ds_bpermute_b32 v167, v185, v199 offset:192
	ds_bpermute_b32 v249, v185, v198 offset:192
	s_waitcnt lgkmcnt(0)
	v_mov_b32_e32 v251, v249
	v_mov_b32_e32 v250, v167
	v_fma_f32 v251, v251, v166, v248
	v_mul_f32_e32 v250, v250, v166
	v_fma_f32 v251, v251, v165, v247
	v_mul_f32_e32 v250, v250, v165
	v_fma_f32 v251, v251, v164, v246
	v_mul_f32_e32 v250, v250, v164
	s_mov_b64 exec, s[10:11]
	ds_write_b64 v182, v[250:251] offset:0
	s_mov_b64 exec, -1
	s_waitcnt lgkmcnt(0)
	s_barrier
	ds_read2_b64 v[4:7], v183 offset0:0 offset1:16
	s_add_i32 s52, s4, 0
	s_sub_i32 s52, 31, s52
	s_lshl_b32 s52, s52, 12
	v_add_u32_e32 v197, s52, v184
	s_waitcnt lgkmcnt(0)
	v_fma_f32 v198, v180, v6, v7
	v_cndmask_b32_e64 v199, v180, v198, s[24:25]
	v_fma_f32 v180, v198, v4, v5
	v_fma_f32 v200, v199, v167, v249
	v_cndmask_b32_e64 v199, v199, v200, s[16:17]
	v_fma_f32 v200, v199, v166, v248
	v_cndmask_b32_e64 v199, v199, v200, s[20:21]
	v_fma_f32 v200, v199, v165, v247
	v_cndmask_b32_e64 v199, v199, v200, s[22:23]
	v_fma_f32 v221, v127, v199, v177
	v_fma_f32 v220, v126, v221, v176
	v_fma_f32 v219, v125, v220, v175
	v_fma_f32 v218, v124, v219, v174
	v_fma_f32 v217, v123, v218, v173
	v_fma_f32 v216, v122, v217, v172
	v_fma_f32 v215, v121, v216, v171
	v_fma_f32 v214, v120, v215, v170
	v_cvt_pk_bf16_f32 v206, v214, v215
	v_cvt_pk_bf16_f32 v208, v216, v217
	v_cvt_pk_bf16_f32 v210, v218, v219
	v_cvt_pk_bf16_f32 v212, v220, v221
	ds_write_b16 v197, v206 offset:0
	ds_write_b16_d16_hi v197, v206 offset:64
	ds_write_b16 v197, v208 offset:128
	ds_write_b16_d16_hi v197, v208 offset:192
	ds_write_b16 v197, v210 offset:256
	ds_write_b16_d16_hi v197, v210 offset:320
	ds_write_b16 v197, v212 offset:384
	ds_write_b16_d16_hi v197, v212 offset:448
	ds_read_b128 v[198:201], v130 offset:0
	ds_read_b128 v[214:217], v130 offset:576
	ds_read_b128 v[202:205], v131 offset:0
	ds_read_b128 v[218:221], v131 offset:576
	ds_read_b128 v[206:209], v130 offset:144
	ds_read_b128 v[222:225], v130 offset:720
	ds_read_b128 v[210:213], v131 offset:144
	s_waitcnt lgkmcnt(14)
	ds_read_b128 v[226:229], v131 offset:720
	s_waitcnt lgkmcnt(4)
	v_mfma_f32_16x16x32_bf16 v[100:103], v[198:201], v[20:23], v[12:15]
	v_mfma_f32_16x16x32_bf16 v[100:103], v[202:205], v[24:27], v[100:103]
	v_mfma_f32_16x16x32_bf16 v[104:107], v[198:201], v[52:55], v[16:19]
	v_mfma_f32_16x16x32_bf16 v[104:107], v[202:205], v[56:59], v[104:107]
	v_mfma_f32_16x16x32_bf16 v[108:111], v[198:201], v[84:87], v[242:245]
	v_mfma_f32_16x16x32_bf16 v[112:115], v[214:217], v[20:23], v[12:15]
	v_mfma_f32_16x16x32_bf16 v[112:115], v[218:221], v[24:27], v[112:115]
	v_mfma_f32_16x16x32_bf16 v[138:141], v[214:217], v[52:55], v[16:19]
	v_mfma_f32_16x16x32_bf16 v[138:141], v[218:221], v[56:59], v[138:141]
	v_mfma_f32_16x16x32_bf16 v[142:145], v[214:217], v[84:87], v[242:245]
	ds_read_b128 v[198:201], v130 offset:288
	ds_read_b128 v[214:217], v130 offset:864
	ds_read_b128 v[202:205], v131 offset:288
	ds_read_b128 v[218:221], v131 offset:864
	s_waitcnt lgkmcnt(4)
	v_mfma_f32_16x16x32_bf16 v[100:103], v[206:209], v[28:31], v[100:103]
	v_mfma_f32_16x16x32_bf16 v[100:103], v[210:213], v[32:35], v[100:103]
	v_mfma_f32_16x16x32_bf16 v[104:107], v[210:213], v[64:67], v[104:107]
	v_mfma_f32_16x16x32_bf16 v[104:107], v[206:209], v[60:63], v[104:107]
	v_mfma_f32_16x16x32_bf16 v[108:111], v[206:209], v[88:91], v[108:111]
	v_mfma_f32_16x16x32_bf16 v[112:115], v[222:225], v[28:31], v[112:115]
	v_mfma_f32_16x16x32_bf16 v[112:115], v[226:229], v[32:35], v[112:115]
	v_mfma_f32_16x16x32_bf16 v[138:141], v[226:229], v[64:67], v[138:141]
	v_mfma_f32_16x16x32_bf16 v[138:141], v[222:225], v[60:63], v[138:141]
	v_mfma_f32_16x16x32_bf16 v[142:145], v[222:225], v[88:91], v[142:145]
	ds_read_b128 v[206:209], v130 offset:432
	ds_read_b128 v[222:225], v130 offset:1008
	ds_read_b128 v[210:213], v131 offset:432
	ds_read_b128 v[226:229], v131 offset:1008
	s_waitcnt lgkmcnt(4)
	v_mfma_f32_16x16x32_bf16 v[100:103], v[198:201], v[36:39], v[100:103]
	v_mfma_f32_16x16x32_bf16 v[100:103], v[202:205], v[40:43], v[100:103]
	v_mfma_f32_16x16x32_bf16 v[104:107], v[202:205], v[72:75], v[104:107]
	v_mfma_f32_16x16x32_bf16 v[104:107], v[198:201], v[68:71], v[104:107]
	v_mfma_f32_16x16x32_bf16 v[108:111], v[198:201], v[92:95], v[108:111]
	v_mfma_f32_16x16x32_bf16 v[112:115], v[214:217], v[36:39], v[112:115]
	v_mfma_f32_16x16x32_bf16 v[112:115], v[218:221], v[40:43], v[112:115]
	v_mfma_f32_16x16x32_bf16 v[138:141], v[218:221], v[72:75], v[138:141]
	v_mfma_f32_16x16x32_bf16 v[138:141], v[214:217], v[68:71], v[138:141]
	v_mfma_f32_16x16x32_bf16 v[142:145], v[214:217], v[92:95], v[142:145]
	s_waitcnt lgkmcnt(0)
	v_mfma_f32_16x16x32_bf16 v[100:103], v[206:209], v[44:47], v[100:103]
	v_mfma_f32_16x16x32_bf16 v[100:103], v[210:213], v[48:51], v[100:103]
	v_mfma_f32_16x16x32_bf16 v[104:107], v[210:213], v[80:83], v[104:107]
	v_mfma_f32_16x16x32_bf16 v[104:107], v[206:209], v[76:79], v[104:107]
	v_mfma_f32_16x16x32_bf16 v[108:111], v[206:209], v[96:99], v[108:111]
	v_mfma_f32_16x16x32_bf16 v[112:115], v[222:225], v[44:47], v[112:115]
	v_mfma_f32_16x16x32_bf16 v[112:115], v[226:229], v[48:51], v[112:115]
	v_mfma_f32_16x16x32_bf16 v[138:141], v[226:229], v[80:83], v[138:141]
	v_mfma_f32_16x16x32_bf16 v[138:141], v[222:225], v[76:79], v[138:141]
	v_mfma_f32_16x16x32_bf16 v[142:145], v[222:225], v[96:99], v[142:145]
	s_waitcnt lgkmcnt(0)
	s_barrier
	s_waitcnt vmcnt(3)
	ds_write_b128 v134, v[230:233]
	ds_write_b128 v134, v[234:237] offset:4608
	ds_write_b128 v135, v[238:241]
	s_add_i32 s52, s4, 4
	s_min_u32 s52, s52, 31
	s_sub_i32 s52, 31, s52
	s_lshl_b32 s52, s52, 13
	s_add_u32 s26, s50, s52
	s_addc_u32 s27, s51, 0
	global_load_dwordx4 v[230:233], v154, s[26:27]
	global_load_dwordx4 v[234:237], v155, s[26:27]
	global_load_dwordx4 v[238:241], v159, s[26:27]
	v_exp_f32_e32 v198, v100
	v_exp_f32_e32 v199, v101
	v_exp_f32_e32 v200, v102
	v_exp_f32_e32 v201, v103
	v_exp_f32_e32 v202, v112
	v_exp_f32_e32 v203, v113
	v_exp_f32_e32 v204, v114
	v_exp_f32_e32 v205, v115
	v_exp_f32_e32 v214, v104
	v_add_f32_e32 v198, 1.0, v198
	v_exp_f32_e32 v215, v105
	v_add_f32_e32 v199, 1.0, v199
	v_exp_f32_e32 v216, v106
	v_add_f32_e32 v200, 1.0, v200
	v_exp_f32_e32 v217, v107
	v_add_f32_e32 v201, 1.0, v201
	v_exp_f32_e32 v218, v138
	v_add_f32_e32 v202, 1.0, v202
	v_exp_f32_e32 v219, v139
	v_add_f32_e32 v203, 1.0, v203
	v_exp_f32_e32 v220, v140
	v_add_f32_e32 v204, 1.0, v204
	v_exp_f32_e32 v221, v141
	v_add_f32_e32 v205, 1.0, v205
	v_rcp_f32_e32 v198, v198
	v_add_f32_e32 v214, 1.0, v214
	v_rcp_f32_e32 v199, v199
	v_add_f32_e32 v215, 1.0, v215
	v_rcp_f32_e32 v200, v200
	v_add_f32_e32 v216, 1.0, v216
	v_rcp_f32_e32 v201, v201
	v_add_f32_e32 v217, 1.0, v217
	v_rcp_f32_e32 v202, v202
	v_add_f32_e32 v218, 1.0, v218
	v_rcp_f32_e32 v203, v203
	v_add_f32_e32 v219, 1.0, v219
	v_rcp_f32_e32 v204, v204
	v_add_f32_e32 v220, 1.0, v220
	v_rcp_f32_e32 v205, v205
	v_add_f32_e32 v221, 1.0, v221
	v_mul_f32_e32 v198, v179, v198
	v_mul_f32_e32 v199, v179, v199
	v_mul_f32_e32 v200, v179, v200
	v_mul_f32_e32 v201, v179, v201
	v_mul_f32_e32 v202, v179, v202
	v_mul_f32_e32 v203, v179, v203
	v_mul_f32_e32 v204, v179, v204
	v_mul_f32_e32 v205, v179, v205
	v_exp_f32_e32 v120, v198
	v_exp_f32_e32 v121, v199
	v_exp_f32_e32 v122, v200
	v_exp_f32_e32 v123, v201
	v_exp_f32_e32 v124, v202
	v_exp_f32_e32 v125, v203
	v_exp_f32_e32 v126, v204
	v_exp_f32_e32 v127, v205
	v_fma_f32 v206, -v120, v120, 1.0
	v_fma_f32 v207, -v121, v121, 1.0
	v_fma_f32 v208, -v122, v122, 1.0
	v_fma_f32 v209, -v123, v123, 1.0
	v_fma_f32 v210, -v124, v124, 1.0
	v_fma_f32 v211, -v125, v125, 1.0
	v_fma_f32 v212, -v126, v126, 1.0
	v_fma_f32 v213, -v127, v127, 1.0
	v_max_f32_e32 v206, 0xda24260, v206
	v_max_f32_e32 v207, 0xda24260, v207
	v_max_f32_e32 v208, 0xda24260, v208
	v_max_f32_e32 v209, 0xda24260, v209
	v_max_f32_e32 v210, 0xda24260, v210
	v_max_f32_e32 v211, 0xda24260, v211
	v_max_f32_e32 v212, 0xda24260, v212
	v_max_f32_e32 v213, 0xda24260, v213
	v_mul_f32_e32 v198, v214, v206
	v_mul_f32_e32 v199, v215, v207
	v_mul_f32_e32 v200, v216, v208
	v_mul_f32_e32 v201, v217, v209
	v_mul_f32_e32 v202, v218, v210
	v_mul_f32_e32 v203, v219, v211
	v_mul_f32_e32 v204, v220, v212
	v_mul_f32_e32 v205, v221, v213
	v_mul_f32_e32 v214, v214, v198
	v_mul_f32_e32 v215, v215, v199
	v_mul_f32_e32 v216, v216, v200
	v_mul_f32_e32 v217, v217, v201
	v_mul_f32_e32 v218, v218, v202
	v_mul_f32_e32 v219, v219, v203
	v_mul_f32_e32 v220, v220, v204
	v_mul_f32_e32 v221, v221, v205
	v_rsq_f32_e32 v214, v214
	v_mul_f32_e32 v222, v108, v206
	v_rsq_f32_e32 v215, v215
	v_mul_f32_e32 v223, v109, v207
	v_rsq_f32_e32 v216, v216
	v_mul_f32_e32 v224, v110, v208
	v_rsq_f32_e32 v217, v217
	v_mul_f32_e32 v225, v111, v209
	v_rsq_f32_e32 v218, v218
	v_mul_f32_e32 v226, v142, v210
	v_rsq_f32_e32 v219, v219
	v_mul_f32_e32 v227, v143, v211
	v_rsq_f32_e32 v220, v220
	v_mul_f32_e32 v228, v144, v212
	v_rsq_f32_e32 v221, v221
	v_mul_f32_e32 v229, v145, v213
	v_mul_f32_e32 v170, v222, v214
	v_mul_f32_e32 v171, v223, v215
	v_mul_f32_e32 v172, v224, v216
	v_mul_f32_e32 v173, v225, v217
	v_mul_f32_e32 v174, v226, v218
	v_mul_f32_e32 v175, v227, v219
	v_mul_f32_e32 v176, v228, v220
	v_mul_f32_e32 v177, v229, v221
	v_mov_b32_e32 v198, v177
	v_mov_b32_e32 v199, v127
	v_fma_f32 v198, v126, v198, v176
	v_mul_f32_e32 v199, v199, v126
	v_fma_f32 v198, v125, v198, v175
	v_mul_f32_e32 v199, v199, v125
	v_fma_f32 v198, v124, v198, v174
	v_mul_f32_e32 v199, v199, v124
	v_fma_f32 v198, v123, v198, v173
	v_mul_f32_e32 v199, v199, v123
	v_fma_f32 v198, v122, v198, v172
	v_mul_f32_e32 v199, v199, v122
	v_fma_f32 v198, v121, v198, v171
	v_mul_f32_e32 v199, v199, v121
	v_fma_f32 v198, v120, v198, v170
	v_mul_f32_e32 v199, v199, v120
	ds_bpermute_b32 v164, v185, v199 offset:0
	ds_bpermute_b32 v246, v185, v198 offset:0
	ds_bpermute_b32 v165, v185, v199 offset:64
	ds_bpermute_b32 v247, v185, v198 offset:64
	ds_bpermute_b32 v166, v185, v199 offset:128
	ds_bpermute_b32 v248, v185, v198 offset:128
	ds_bpermute_b32 v167, v185, v199 offset:192
	ds_bpermute_b32 v249, v185, v198 offset:192
	s_waitcnt lgkmcnt(0)
	v_mov_b32_e32 v251, v249
	v_mov_b32_e32 v250, v167
	v_fma_f32 v251, v251, v166, v248
	v_mul_f32_e32 v250, v250, v166
	v_fma_f32 v251, v251, v165, v247
	v_mul_f32_e32 v250, v250, v165
	v_fma_f32 v251, v251, v164, v246
	v_mul_f32_e32 v250, v250, v164
	s_mov_b64 exec, s[10:11]
	ds_write_b64 v182, v[250:251] offset:1024
	s_mov_b64 exec, -1
	s_waitcnt lgkmcnt(0)
	s_barrier
	ds_read2_b64 v[4:7], v183 offset0:128 offset1:144
	s_add_i32 s52, s4, 1
	s_sub_i32 s52, 31, s52
	s_lshl_b32 s52, s52, 12
	v_add_u32_e32 v197, s52, v184
	s_waitcnt lgkmcnt(0)
	v_fma_f32 v198, v180, v6, v7
	v_cndmask_b32_e64 v199, v180, v198, s[24:25]
	v_fma_f32 v180, v198, v4, v5
	v_fma_f32 v200, v199, v167, v249
	v_cndmask_b32_e64 v199, v199, v200, s[16:17]
	v_fma_f32 v200, v199, v166, v248
	v_cndmask_b32_e64 v199, v199, v200, s[20:21]
	v_fma_f32 v200, v199, v165, v247
	v_cndmask_b32_e64 v199, v199, v200, s[22:23]
	v_fma_f32 v221, v127, v199, v177
	v_fma_f32 v220, v126, v221, v176
	v_fma_f32 v219, v125, v220, v175
	v_fma_f32 v218, v124, v219, v174
	v_fma_f32 v217, v123, v218, v173
	v_fma_f32 v216, v122, v217, v172
	v_fma_f32 v215, v121, v216, v171
	v_fma_f32 v214, v120, v215, v170
	v_cvt_pk_bf16_f32 v206, v214, v215
	v_cvt_pk_bf16_f32 v208, v216, v217
	v_cvt_pk_bf16_f32 v210, v218, v219
	v_cvt_pk_bf16_f32 v212, v220, v221
	ds_write_b16 v197, v206 offset:0
	ds_write_b16_d16_hi v197, v206 offset:64
	ds_write_b16 v197, v208 offset:128
	ds_write_b16_d16_hi v197, v208 offset:192
	ds_write_b16 v197, v210 offset:256
	ds_write_b16_d16_hi v197, v210 offset:320
	ds_write_b16 v197, v212 offset:384
	ds_write_b16_d16_hi v197, v212 offset:448
	s_add_i32 s4, s4, 2
	s_cmp_lt_u32 s4, 16
	s_cbranch_scc1 .Lrec2_loopA_d1
	ds_read_b128 v[198:201], v130 offset:0
	ds_read_b128 v[214:217], v130 offset:576
	ds_read_b128 v[202:205], v131 offset:0
	ds_read_b128 v[218:221], v131 offset:576
	ds_read_b128 v[206:209], v130 offset:144
	ds_read_b128 v[222:225], v130 offset:720
	ds_read_b128 v[210:213], v131 offset:144
	s_waitcnt lgkmcnt(14)
	ds_read_b128 v[226:229], v131 offset:720
	s_waitcnt lgkmcnt(4)
	v_mfma_f32_16x16x32_bf16 v[100:103], v[198:201], v[20:23], v[12:15]
	v_mfma_f32_16x16x32_bf16 v[100:103], v[202:205], v[24:27], v[100:103]
	v_mfma_f32_16x16x32_bf16 v[104:107], v[198:201], v[52:55], v[16:19]
	v_mfma_f32_16x16x32_bf16 v[104:107], v[202:205], v[56:59], v[104:107]
	v_mfma_f32_16x16x32_bf16 v[108:111], v[198:201], v[84:87], v[242:245]
	v_mfma_f32_16x16x32_bf16 v[112:115], v[214:217], v[20:23], v[12:15]
	v_mfma_f32_16x16x32_bf16 v[112:115], v[218:221], v[24:27], v[112:115]
	v_mfma_f32_16x16x32_bf16 v[138:141], v[214:217], v[52:55], v[16:19]
	v_mfma_f32_16x16x32_bf16 v[138:141], v[218:221], v[56:59], v[138:141]
	v_mfma_f32_16x16x32_bf16 v[142:145], v[214:217], v[84:87], v[242:245]
	ds_read_b128 v[198:201], v130 offset:288
	ds_read_b128 v[214:217], v130 offset:864
	ds_read_b128 v[202:205], v131 offset:288
	ds_read_b128 v[218:221], v131 offset:864
	s_waitcnt lgkmcnt(4)
	v_mfma_f32_16x16x32_bf16 v[100:103], v[206:209], v[28:31], v[100:103]
	v_mfma_f32_16x16x32_bf16 v[100:103], v[210:213], v[32:35], v[100:103]
	v_mfma_f32_16x16x32_bf16 v[104:107], v[210:213], v[64:67], v[104:107]
	v_mfma_f32_16x16x32_bf16 v[104:107], v[206:209], v[60:63], v[104:107]
	v_mfma_f32_16x16x32_bf16 v[108:111], v[206:209], v[88:91], v[108:111]
	v_mfma_f32_16x16x32_bf16 v[112:115], v[222:225], v[28:31], v[112:115]
	v_mfma_f32_16x16x32_bf16 v[112:115], v[226:229], v[32:35], v[112:115]
	v_mfma_f32_16x16x32_bf16 v[138:141], v[226:229], v[64:67], v[138:141]
	v_mfma_f32_16x16x32_bf16 v[138:141], v[222:225], v[60:63], v[138:141]
	v_mfma_f32_16x16x32_bf16 v[142:145], v[222:225], v[88:91], v[142:145]
	ds_read_b128 v[206:209], v130 offset:432
	ds_read_b128 v[222:225], v130 offset:1008
	ds_read_b128 v[210:213], v131 offset:432
	ds_read_b128 v[226:229], v131 offset:1008
	s_waitcnt lgkmcnt(4)
	v_mfma_f32_16x16x32_bf16 v[100:103], v[198:201], v[36:39], v[100:103]
	v_mfma_f32_16x16x32_bf16 v[100:103], v[202:205], v[40:43], v[100:103]
	v_mfma_f32_16x16x32_bf16 v[104:107], v[202:205], v[72:75], v[104:107]
	v_mfma_f32_16x16x32_bf16 v[104:107], v[198:201], v[68:71], v[104:107]
	v_mfma_f32_16x16x32_bf16 v[108:111], v[198:201], v[92:95], v[108:111]
	v_mfma_f32_16x16x32_bf16 v[112:115], v[214:217], v[36:39], v[112:115]
	v_mfma_f32_16x16x32_bf16 v[112:115], v[218:221], v[40:43], v[112:115]
	v_mfma_f32_16x16x32_bf16 v[138:141], v[218:221], v[72:75], v[138:141]
	v_mfma_f32_16x16x32_bf16 v[138:141], v[214:217], v[68:71], v[138:141]
	v_mfma_f32_16x16x32_bf16 v[142:145], v[214:217], v[92:95], v[142:145]
	s_waitcnt lgkmcnt(0)
	v_mfma_f32_16x16x32_bf16 v[100:103], v[206:209], v[44:47], v[100:103]
	v_mfma_f32_16x16x32_bf16 v[100:103], v[210:213], v[48:51], v[100:103]
	v_mfma_f32_16x16x32_bf16 v[104:107], v[210:213], v[80:83], v[104:107]
	v_mfma_f32_16x16x32_bf16 v[104:107], v[206:209], v[76:79], v[104:107]
	v_mfma_f32_16x16x32_bf16 v[108:111], v[206:209], v[96:99], v[108:111]
	v_mfma_f32_16x16x32_bf16 v[112:115], v[222:225], v[44:47], v[112:115]
	v_mfma_f32_16x16x32_bf16 v[112:115], v[226:229], v[48:51], v[112:115]
	v_mfma_f32_16x16x32_bf16 v[138:141], v[226:229], v[80:83], v[138:141]
	v_mfma_f32_16x16x32_bf16 v[138:141], v[222:225], v[76:79], v[138:141]
	v_mfma_f32_16x16x32_bf16 v[142:145], v[222:225], v[96:99], v[142:145]
	s_waitcnt lgkmcnt(0)
	s_barrier
	s_waitcnt vmcnt(3)
	ds_write_b128 v134, v[146:149]
	ds_write_b128 v134, v[150:153] offset:4608
	ds_write_b128 v135, v[160:163]
	s_add_i32 s64, s4, 0
	s_sub_i32 s64, 31, s64
	s_mul_i32 s71, s64, 0x30000
	s_add_u32 s38, s60, s71
	s_addc_u32 s39, s61, 0
	s_lshl_b32 s64, s64, 12
	global_load_dwordx4 v[8:11], v255, s[38:39]
	s_add_i32 s52, s4, 3
	s_min_u32 s52, s52, 31
	s_sub_i32 s52, 31, s52
	s_lshl_b32 s52, s52, 13
	s_add_u32 s26, s50, s52
	s_addc_u32 s27, s51, 0
	global_load_dwordx4 v[146:149], v154, s[26:27]
	global_load_dwordx4 v[150:153], v155, s[26:27]
	global_load_dwordx4 v[160:163], v159, s[26:27]
	v_exp_f32_e32 v198, v100
	v_exp_f32_e32 v199, v101
	v_exp_f32_e32 v200, v102
	v_exp_f32_e32 v201, v103
	v_exp_f32_e32 v202, v112
	v_exp_f32_e32 v203, v113
	v_exp_f32_e32 v204, v114
	v_exp_f32_e32 v205, v115
	v_exp_f32_e32 v214, v104
	v_add_f32_e32 v198, 1.0, v198
	v_exp_f32_e32 v215, v105
	v_add_f32_e32 v199, 1.0, v199
	v_exp_f32_e32 v216, v106
	v_add_f32_e32 v200, 1.0, v200
	v_exp_f32_e32 v217, v107
	v_add_f32_e32 v201, 1.0, v201
	v_exp_f32_e32 v218, v138
	v_add_f32_e32 v202, 1.0, v202
	v_exp_f32_e32 v219, v139
	v_add_f32_e32 v203, 1.0, v203
	v_exp_f32_e32 v220, v140
	v_add_f32_e32 v204, 1.0, v204
	v_exp_f32_e32 v221, v141
	v_add_f32_e32 v205, 1.0, v205
	v_rcp_f32_e32 v198, v198
	v_add_f32_e32 v214, 1.0, v214
	v_rcp_f32_e32 v199, v199
	v_add_f32_e32 v215, 1.0, v215
	v_rcp_f32_e32 v200, v200
	v_add_f32_e32 v216, 1.0, v216
	v_rcp_f32_e32 v201, v201
	v_add_f32_e32 v217, 1.0, v217
	v_rcp_f32_e32 v202, v202
	v_add_f32_e32 v218, 1.0, v218
	v_rcp_f32_e32 v203, v203
	v_add_f32_e32 v219, 1.0, v219
	v_rcp_f32_e32 v204, v204
	v_add_f32_e32 v220, 1.0, v220
	v_rcp_f32_e32 v205, v205
	v_add_f32_e32 v221, 1.0, v221
	v_mul_f32_e32 v198, v179, v198
	v_mul_f32_e32 v199, v179, v199
	v_mul_f32_e32 v200, v179, v200
	v_mul_f32_e32 v201, v179, v201
	v_mul_f32_e32 v202, v179, v202
	v_mul_f32_e32 v203, v179, v203
	v_mul_f32_e32 v204, v179, v204
	v_mul_f32_e32 v205, v179, v205
	v_exp_f32_e32 v120, v198
	v_exp_f32_e32 v121, v199
	v_exp_f32_e32 v122, v200
	v_exp_f32_e32 v123, v201
	v_exp_f32_e32 v124, v202
	v_exp_f32_e32 v125, v203
	v_exp_f32_e32 v126, v204
	v_exp_f32_e32 v127, v205
	v_fma_f32 v206, -v120, v120, 1.0
	v_fma_f32 v207, -v121, v121, 1.0
	v_fma_f32 v208, -v122, v122, 1.0
	v_fma_f32 v209, -v123, v123, 1.0
	v_fma_f32 v210, -v124, v124, 1.0
	v_fma_f32 v211, -v125, v125, 1.0
	v_fma_f32 v212, -v126, v126, 1.0
	v_fma_f32 v213, -v127, v127, 1.0
	v_max_f32_e32 v206, 0xda24260, v206
	v_max_f32_e32 v207, 0xda24260, v207
	v_max_f32_e32 v208, 0xda24260, v208
	v_max_f32_e32 v209, 0xda24260, v209
	v_max_f32_e32 v210, 0xda24260, v210
	v_max_f32_e32 v211, 0xda24260, v211
	v_max_f32_e32 v212, 0xda24260, v212
	v_max_f32_e32 v213, 0xda24260, v213
	v_mul_f32_e32 v198, v214, v206
	v_mul_f32_e32 v199, v215, v207
	v_mul_f32_e32 v200, v216, v208
	v_mul_f32_e32 v201, v217, v209
	v_mul_f32_e32 v202, v218, v210
	v_mul_f32_e32 v203, v219, v211
	v_mul_f32_e32 v204, v220, v212
	v_mul_f32_e32 v205, v221, v213
	v_mul_f32_e32 v214, v214, v198
	v_mul_f32_e32 v215, v215, v199
	v_mul_f32_e32 v216, v216, v200
	v_mul_f32_e32 v217, v217, v201
	v_mul_f32_e32 v218, v218, v202
	v_mul_f32_e32 v219, v219, v203
	v_mul_f32_e32 v220, v220, v204
	v_mul_f32_e32 v221, v221, v205
	v_rsq_f32_e32 v214, v214
	v_mul_f32_e32 v222, v108, v206
	v_rsq_f32_e32 v215, v215
	v_mul_f32_e32 v223, v109, v207
	v_rsq_f32_e32 v216, v216
	v_mul_f32_e32 v224, v110, v208
	v_rsq_f32_e32 v217, v217
	v_mul_f32_e32 v225, v111, v209
	v_rsq_f32_e32 v218, v218
	v_mul_f32_e32 v226, v142, v210
	v_rsq_f32_e32 v219, v219
	v_mul_f32_e32 v227, v143, v211
	v_rsq_f32_e32 v220, v220
	v_mul_f32_e32 v228, v144, v212
	v_rsq_f32_e32 v221, v221
	v_mul_f32_e32 v229, v145, v213
	v_mul_f32_e32 v170, v222, v214
	v_mul_f32_e32 v171, v223, v215
	v_mul_f32_e32 v172, v224, v216
	v_mul_f32_e32 v173, v225, v217
	v_mul_f32_e32 v174, v226, v218
	v_mul_f32_e32 v175, v227, v219
	v_mul_f32_e32 v176, v228, v220
	v_mul_f32_e32 v177, v229, v221
	v_mov_b32_e32 v198, v177
	v_mov_b32_e32 v199, v127
	v_fma_f32 v198, v126, v198, v176
	v_mul_f32_e32 v199, v199, v126
	v_fma_f32 v198, v125, v198, v175
	v_mul_f32_e32 v199, v199, v125
	v_fma_f32 v198, v124, v198, v174
	v_mul_f32_e32 v199, v199, v124
	v_fma_f32 v198, v123, v198, v173
	v_mul_f32_e32 v199, v199, v123
	v_fma_f32 v198, v122, v198, v172
	v_mul_f32_e32 v199, v199, v122
	v_fma_f32 v198, v121, v198, v171
	v_mul_f32_e32 v199, v199, v121
	v_fma_f32 v198, v120, v198, v170
	v_mul_f32_e32 v199, v199, v120
	ds_bpermute_b32 v164, v185, v199 offset:0
	ds_bpermute_b32 v246, v185, v198 offset:0
	ds_bpermute_b32 v165, v185, v199 offset:64
	ds_bpermute_b32 v247, v185, v198 offset:64
	ds_bpermute_b32 v166, v185, v199 offset:128
	ds_bpermute_b32 v248, v185, v198 offset:128
	ds_bpermute_b32 v167, v185, v199 offset:192
	ds_bpermute_b32 v249, v185, v198 offset:192
	s_waitcnt lgkmcnt(0)
	v_mov_b32_e32 v251, v249
	v_mov_b32_e32 v250, v167
	v_fma_f32 v251, v251, v166, v248
	v_mul_f32_e32 v250, v250, v166
	v_fma_f32 v251, v251, v165, v247
	v_mul_f32_e32 v250, v250, v165
	v_fma_f32 v251, v251, v164, v246
	v_mul_f32_e32 v250, v250, v164
	s_mov_b64 exec, s[10:11]
	ds_write_b64 v182, v[250:251] offset:0
	s_mov_b64 exec, -1
	s_waitcnt lgkmcnt(0)
	s_barrier
	ds_read2_b64 v[4:7], v183 offset0:0 offset1:16
	s_add_i32 s52, s4, 0
	s_sub_i32 s52, 31, s52
	s_lshl_b32 s52, s52, 12
	v_add_u32_e32 v197, s52, v184
	s_waitcnt lgkmcnt(0)
	v_fma_f32 v198, v180, v6, v7
	v_cndmask_b32_e64 v199, v180, v198, s[24:25]
	v_fma_f32 v180, v198, v4, v5
	v_fma_f32 v200, v199, v167, v249
	v_cndmask_b32_e64 v199, v199, v200, s[16:17]
	v_fma_f32 v200, v199, v166, v248
	v_cndmask_b32_e64 v199, v199, v200, s[20:21]
	v_fma_f32 v200, v199, v165, v247
	v_cndmask_b32_e64 v199, v199, v200, s[22:23]
	v_fma_f32 v221, v127, v199, v177
	v_fma_f32 v220, v126, v221, v176
	v_fma_f32 v219, v125, v220, v175
	v_fma_f32 v218, v124, v219, v174
	v_fma_f32 v217, v123, v218, v173
	v_fma_f32 v216, v122, v217, v172
	v_fma_f32 v215, v121, v216, v171
	v_fma_f32 v214, v120, v215, v170
	ds_read_u16 v206, v197 offset:0
	ds_read_u16 v207, v197 offset:64
	ds_read_u16 v208, v197 offset:128
	ds_read_u16 v209, v197 offset:192
	ds_read_u16 v210, v197 offset:256
	ds_read_u16 v211, v197 offset:320
	ds_read_u16 v212, v197 offset:384
	ds_read_u16 v213, v197 offset:448
	s_waitcnt lgkmcnt(0)
	v_lshlrev_b32_e32 v206, 16, v206
	v_lshlrev_b32_e32 v207, 16, v207
	v_lshlrev_b32_e32 v208, 16, v208
	v_lshlrev_b32_e32 v209, 16, v209
	v_lshlrev_b32_e32 v210, 16, v210
	v_lshlrev_b32_e32 v211, 16, v211
	v_lshlrev_b32_e32 v212, 16, v212
	v_lshlrev_b32_e32 v213, 16, v213
	v_add_f32_e32 v214, v214, v206
	v_add_f32_e32 v215, v215, v207
	v_add_f32_e32 v216, v216, v208
	v_add_f32_e32 v217, v217, v209
	v_add_f32_e32 v218, v218, v210
	v_add_f32_e32 v219, v219, v211
	v_add_f32_e32 v220, v220, v212
	v_add_f32_e32 v221, v221, v213
	v_cvt_pk_bf16_f32 v206, v214, v215
	v_cvt_pk_bf16_f32 v208, v216, v217
	v_cvt_pk_bf16_f32 v210, v218, v219
	v_cvt_pk_bf16_f32 v212, v220, v221
	ds_write_b16 v197, v206 offset:0
	ds_write_b16_d16_hi v197, v206 offset:64
	ds_write_b16 v197, v208 offset:128
	ds_write_b16_d16_hi v197, v208 offset:192
	ds_write_b16 v197, v210 offset:256
	ds_write_b16_d16_hi v197, v210 offset:320
	ds_write_b16 v197, v212 offset:384
	ds_write_b16_d16_hi v197, v212 offset:448
	ds_read_b128 v[198:201], v130 offset:0
	ds_read_b128 v[214:217], v130 offset:576
	ds_read_b128 v[202:205], v131 offset:0
	ds_read_b128 v[218:221], v131 offset:576
	ds_read_b128 v[206:209], v130 offset:144
	ds_read_b128 v[222:225], v130 offset:720
	ds_read_b128 v[210:213], v131 offset:144
	s_waitcnt lgkmcnt(14)
	ds_read_b128 v[226:229], v131 offset:720
	s_waitcnt lgkmcnt(4)
	v_mfma_f32_16x16x32_bf16 v[100:103], v[198:201], v[20:23], v[12:15]
	v_mfma_f32_16x16x32_bf16 v[100:103], v[202:205], v[24:27], v[100:103]
	v_mfma_f32_16x16x32_bf16 v[104:107], v[198:201], v[52:55], v[16:19]
	v_mfma_f32_16x16x32_bf16 v[104:107], v[202:205], v[56:59], v[104:107]
	v_mfma_f32_16x16x32_bf16 v[108:111], v[198:201], v[84:87], v[242:245]
	v_mfma_f32_16x16x32_bf16 v[112:115], v[214:217], v[20:23], v[12:15]
	v_mfma_f32_16x16x32_bf16 v[112:115], v[218:221], v[24:27], v[112:115]
	v_mfma_f32_16x16x32_bf16 v[138:141], v[214:217], v[52:55], v[16:19]
	v_mfma_f32_16x16x32_bf16 v[138:141], v[218:221], v[56:59], v[138:141]
	v_mfma_f32_16x16x32_bf16 v[142:145], v[214:217], v[84:87], v[242:245]
	ds_read_b128 v[198:201], v130 offset:288
	ds_read_b128 v[214:217], v130 offset:864
	ds_read_b128 v[202:205], v131 offset:288
	ds_read_b128 v[218:221], v131 offset:864
	s_waitcnt lgkmcnt(4)
	v_mfma_f32_16x16x32_bf16 v[100:103], v[206:209], v[28:31], v[100:103]
	v_mfma_f32_16x16x32_bf16 v[100:103], v[210:213], v[32:35], v[100:103]
	v_mfma_f32_16x16x32_bf16 v[104:107], v[210:213], v[64:67], v[104:107]
	v_mfma_f32_16x16x32_bf16 v[104:107], v[206:209], v[60:63], v[104:107]
	v_mfma_f32_16x16x32_bf16 v[108:111], v[206:209], v[88:91], v[108:111]
	v_mfma_f32_16x16x32_bf16 v[112:115], v[222:225], v[28:31], v[112:115]
	v_mfma_f32_16x16x32_bf16 v[112:115], v[226:229], v[32:35], v[112:115]
	v_mfma_f32_16x16x32_bf16 v[138:141], v[226:229], v[64:67], v[138:141]
	v_mfma_f32_16x16x32_bf16 v[138:141], v[222:225], v[60:63], v[138:141]
	v_mfma_f32_16x16x32_bf16 v[142:145], v[222:225], v[88:91], v[142:145]
	ds_read_b128 v[206:209], v130 offset:432
	ds_read_b128 v[222:225], v130 offset:1008
	ds_read_b128 v[210:213], v131 offset:432
	ds_read_b128 v[226:229], v131 offset:1008
	s_waitcnt lgkmcnt(4)
	v_mfma_f32_16x16x32_bf16 v[100:103], v[198:201], v[36:39], v[100:103]
	v_mfma_f32_16x16x32_bf16 v[100:103], v[202:205], v[40:43], v[100:103]
	v_mfma_f32_16x16x32_bf16 v[104:107], v[202:205], v[72:75], v[104:107]
	v_mfma_f32_16x16x32_bf16 v[104:107], v[198:201], v[68:71], v[104:107]
	v_mfma_f32_16x16x32_bf16 v[108:111], v[198:201], v[92:95], v[108:111]
	v_mfma_f32_16x16x32_bf16 v[112:115], v[214:217], v[36:39], v[112:115]
	v_mfma_f32_16x16x32_bf16 v[112:115], v[218:221], v[40:43], v[112:115]
	v_mfma_f32_16x16x32_bf16 v[138:141], v[218:221], v[72:75], v[138:141]
	v_mfma_f32_16x16x32_bf16 v[138:141], v[214:217], v[68:71], v[138:141]
	v_mfma_f32_16x16x32_bf16 v[142:145], v[214:217], v[92:95], v[142:145]
	s_waitcnt lgkmcnt(0)
	v_mfma_f32_16x16x32_bf16 v[100:103], v[206:209], v[44:47], v[100:103]
	v_mfma_f32_16x16x32_bf16 v[100:103], v[210:213], v[48:51], v[100:103]
	v_mfma_f32_16x16x32_bf16 v[104:107], v[210:213], v[80:83], v[104:107]
	v_mfma_f32_16x16x32_bf16 v[104:107], v[206:209], v[76:79], v[104:107]
	v_mfma_f32_16x16x32_bf16 v[108:111], v[206:209], v[96:99], v[108:111]
	v_mfma_f32_16x16x32_bf16 v[112:115], v[222:225], v[44:47], v[112:115]
	v_mfma_f32_16x16x32_bf16 v[112:115], v[226:229], v[48:51], v[112:115]
	v_mfma_f32_16x16x32_bf16 v[138:141], v[226:229], v[80:83], v[138:141]
	v_mfma_f32_16x16x32_bf16 v[138:141], v[222:225], v[76:79], v[138:141]
	v_mfma_f32_16x16x32_bf16 v[142:145], v[222:225], v[96:99], v[142:145]
	s_waitcnt lgkmcnt(0)
	s_barrier
	s_waitcnt vmcnt(4)
	ds_write_b128 v134, v[230:233]
	ds_write_b128 v134, v[234:237] offset:4608
	ds_write_b128 v135, v[238:241]
	s_add_i32 s64, s4, 0
	s_sub_i32 s64, 31, s64
	s_mul_i32 s71, s64, 0x30000
	s_add_u32 s38, s60, s71
	s_addc_u32 s39, s61, 0
	s_lshl_b32 s64, s64, 12
	v_add_u32_e32 v136, s64, v195
	ds_read_b128 v[116:119], v136
	s_waitcnt vmcnt(3)
	s_waitcnt lgkmcnt(0)
	v_lshlrev_b32_e32 v136, 16, v116
	v_lshlrev_b32_e32 v137, 16, v8
	v_and_b32_e32 v168, 0xffff0000, v116
	v_and_b32_e32 v169, 0xffff0000, v8
	v_mul_f32_e32 v136, v136, v137
	v_mul_f32_e32 v168, v168, v169
	v_cvt_pk_bf16_f32 v116, v136, v168
	v_lshlrev_b32_e32 v136, 16, v117
	v_lshlrev_b32_e32 v137, 16, v9
	v_and_b32_e32 v168, 0xffff0000, v117
	v_and_b32_e32 v169, 0xffff0000, v9
	v_mul_f32_e32 v136, v136, v137
	v_mul_f32_e32 v168, v168, v169
	v_cvt_pk_bf16_f32 v117, v136, v168
	v_lshlrev_b32_e32 v136, 16, v118
	v_lshlrev_b32_e32 v137, 16, v10
	v_and_b32_e32 v168, 0xffff0000, v118
	v_and_b32_e32 v169, 0xffff0000, v10
	v_mul_f32_e32 v136, v136, v137
	v_mul_f32_e32 v168, v168, v169
	v_cvt_pk_bf16_f32 v118, v136, v168
	v_lshlrev_b32_e32 v136, 16, v119
	v_lshlrev_b32_e32 v137, 16, v11
	v_and_b32_e32 v168, 0xffff0000, v119
	v_and_b32_e32 v169, 0xffff0000, v11
	v_mul_f32_e32 v136, v136, v137
	v_mul_f32_e32 v168, v168, v169
	v_cvt_pk_bf16_f32 v119, v136, v168
	global_store_dwordx4 v255, v[116:119], s[38:39]
	s_add_i32 s64, s4, 1
	s_sub_i32 s64, 31, s64
	s_mul_i32 s71, s64, 0x30000
	s_add_u32 s38, s60, s71
	s_addc_u32 s39, s61, 0
	s_lshl_b32 s64, s64, 12
	global_load_dwordx4 v[8:11], v255, s[38:39]
	s_add_i32 s52, s4, 4
	s_min_u32 s52, s52, 31
	s_sub_i32 s52, 31, s52
	s_lshl_b32 s52, s52, 13
	s_add_u32 s26, s50, s52
	s_addc_u32 s27, s51, 0
	global_load_dwordx4 v[230:233], v154, s[26:27]
	global_load_dwordx4 v[234:237], v155, s[26:27]
	global_load_dwordx4 v[238:241], v159, s[26:27]
	v_exp_f32_e32 v198, v100
	v_exp_f32_e32 v199, v101
	v_exp_f32_e32 v200, v102
	v_exp_f32_e32 v201, v103
	v_exp_f32_e32 v202, v112
	v_exp_f32_e32 v203, v113
	v_exp_f32_e32 v204, v114
	v_exp_f32_e32 v205, v115
	v_exp_f32_e32 v214, v104
	v_add_f32_e32 v198, 1.0, v198
	v_exp_f32_e32 v215, v105
	v_add_f32_e32 v199, 1.0, v199
	v_exp_f32_e32 v216, v106
	v_add_f32_e32 v200, 1.0, v200
	v_exp_f32_e32 v217, v107
	v_add_f32_e32 v201, 1.0, v201
	v_exp_f32_e32 v218, v138
	v_add_f32_e32 v202, 1.0, v202
	v_exp_f32_e32 v219, v139
	v_add_f32_e32 v203, 1.0, v203
	v_exp_f32_e32 v220, v140
	v_add_f32_e32 v204, 1.0, v204
	v_exp_f32_e32 v221, v141
	v_add_f32_e32 v205, 1.0, v205
	v_rcp_f32_e32 v198, v198
	v_add_f32_e32 v214, 1.0, v214
	v_rcp_f32_e32 v199, v199
	v_add_f32_e32 v215, 1.0, v215
	v_rcp_f32_e32 v200, v200
	v_add_f32_e32 v216, 1.0, v216
	v_rcp_f32_e32 v201, v201
	v_add_f32_e32 v217, 1.0, v217
	v_rcp_f32_e32 v202, v202
	v_add_f32_e32 v218, 1.0, v218
	v_rcp_f32_e32 v203, v203
	v_add_f32_e32 v219, 1.0, v219
	v_rcp_f32_e32 v204, v204
	v_add_f32_e32 v220, 1.0, v220
	v_rcp_f32_e32 v205, v205
	v_add_f32_e32 v221, 1.0, v221
	v_mul_f32_e32 v198, v179, v198
	v_mul_f32_e32 v199, v179, v199
	v_mul_f32_e32 v200, v179, v200
	v_mul_f32_e32 v201, v179, v201
	v_mul_f32_e32 v202, v179, v202
	v_mul_f32_e32 v203, v179, v203
	v_mul_f32_e32 v204, v179, v204
	v_mul_f32_e32 v205, v179, v205
	v_exp_f32_e32 v120, v198
	v_exp_f32_e32 v121, v199
	v_exp_f32_e32 v122, v200
	v_exp_f32_e32 v123, v201
	v_exp_f32_e32 v124, v202
	v_exp_f32_e32 v125, v203
	v_exp_f32_e32 v126, v204
	v_exp_f32_e32 v127, v205
	v_fma_f32 v206, -v120, v120, 1.0
	v_fma_f32 v207, -v121, v121, 1.0
	v_fma_f32 v208, -v122, v122, 1.0
	v_fma_f32 v209, -v123, v123, 1.0
	v_fma_f32 v210, -v124, v124, 1.0
	v_fma_f32 v211, -v125, v125, 1.0
	v_fma_f32 v212, -v126, v126, 1.0
	v_fma_f32 v213, -v127, v127, 1.0
	v_max_f32_e32 v206, 0xda24260, v206
	v_max_f32_e32 v207, 0xda24260, v207
	v_max_f32_e32 v208, 0xda24260, v208
	v_max_f32_e32 v209, 0xda24260, v209
	v_max_f32_e32 v210, 0xda24260, v210
	v_max_f32_e32 v211, 0xda24260, v211
	v_max_f32_e32 v212, 0xda24260, v212
	v_max_f32_e32 v213, 0xda24260, v213
	v_mul_f32_e32 v198, v214, v206
	v_mul_f32_e32 v199, v215, v207
	v_mul_f32_e32 v200, v216, v208
	v_mul_f32_e32 v201, v217, v209
	v_mul_f32_e32 v202, v218, v210
	v_mul_f32_e32 v203, v219, v211
	v_mul_f32_e32 v204, v220, v212
	v_mul_f32_e32 v205, v221, v213
	v_mul_f32_e32 v214, v214, v198
	v_mul_f32_e32 v215, v215, v199
	v_mul_f32_e32 v216, v216, v200
	v_mul_f32_e32 v217, v217, v201
	v_mul_f32_e32 v218, v218, v202
	v_mul_f32_e32 v219, v219, v203
	v_mul_f32_e32 v220, v220, v204
	v_mul_f32_e32 v221, v221, v205
	v_rsq_f32_e32 v214, v214
	v_mul_f32_e32 v222, v108, v206
	v_rsq_f32_e32 v215, v215
	v_mul_f32_e32 v223, v109, v207
	v_rsq_f32_e32 v216, v216
	v_mul_f32_e32 v224, v110, v208
	v_rsq_f32_e32 v217, v217
	v_mul_f32_e32 v225, v111, v209
	v_rsq_f32_e32 v218, v218
	v_mul_f32_e32 v226, v142, v210
	v_rsq_f32_e32 v219, v219
	v_mul_f32_e32 v227, v143, v211
	v_rsq_f32_e32 v220, v220
	v_mul_f32_e32 v228, v144, v212
	v_rsq_f32_e32 v221, v221
	v_mul_f32_e32 v229, v145, v213
	v_mul_f32_e32 v170, v222, v214
	v_mul_f32_e32 v171, v223, v215
	v_mul_f32_e32 v172, v224, v216
	v_mul_f32_e32 v173, v225, v217
	v_mul_f32_e32 v174, v226, v218
	v_mul_f32_e32 v175, v227, v219
	v_mul_f32_e32 v176, v228, v220
	v_mul_f32_e32 v177, v229, v221
	v_mov_b32_e32 v198, v177
	v_mov_b32_e32 v199, v127
	v_fma_f32 v198, v126, v198, v176
	v_mul_f32_e32 v199, v199, v126
	v_fma_f32 v198, v125, v198, v175
	v_mul_f32_e32 v199, v199, v125
	v_fma_f32 v198, v124, v198, v174
	v_mul_f32_e32 v199, v199, v124
	v_fma_f32 v198, v123, v198, v173
	v_mul_f32_e32 v199, v199, v123
	v_fma_f32 v198, v122, v198, v172
	v_mul_f32_e32 v199, v199, v122
	v_fma_f32 v198, v121, v198, v171
	v_mul_f32_e32 v199, v199, v121
	v_fma_f32 v198, v120, v198, v170
	v_mul_f32_e32 v199, v199, v120
	ds_bpermute_b32 v164, v185, v199 offset:0
	ds_bpermute_b32 v246, v185, v198 offset:0
	ds_bpermute_b32 v165, v185, v199 offset:64
	ds_bpermute_b32 v247, v185, v198 offset:64
	ds_bpermute_b32 v166, v185, v199 offset:128
	ds_bpermute_b32 v248, v185, v198 offset:128
	ds_bpermute_b32 v167, v185, v199 offset:192
	ds_bpermute_b32 v249, v185, v198 offset:192
	s_waitcnt lgkmcnt(0)
	v_mov_b32_e32 v251, v249
	v_mov_b32_e32 v250, v167
	v_fma_f32 v251, v251, v166, v248
	v_mul_f32_e32 v250, v250, v166
	v_fma_f32 v251, v251, v165, v247
	v_mul_f32_e32 v250, v250, v165
	v_fma_f32 v251, v251, v164, v246
	v_mul_f32_e32 v250, v250, v164
	s_mov_b64 exec, s[10:11]
	ds_write_b64 v182, v[250:251] offset:1024
	s_mov_b64 exec, -1
	s_waitcnt lgkmcnt(0)
	s_barrier
	ds_read2_b64 v[4:7], v183 offset0:128 offset1:144
	s_add_i32 s52, s4, 1
	s_sub_i32 s52, 31, s52
	s_lshl_b32 s52, s52, 12
	v_add_u32_e32 v197, s52, v184
	s_waitcnt lgkmcnt(0)
	v_fma_f32 v198, v180, v6, v7
	v_cndmask_b32_e64 v199, v180, v198, s[24:25]
	v_fma_f32 v180, v198, v4, v5
	v_fma_f32 v200, v199, v167, v249
	v_cndmask_b32_e64 v199, v199, v200, s[16:17]
	v_fma_f32 v200, v199, v166, v248
	v_cndmask_b32_e64 v199, v199, v200, s[20:21]
	v_fma_f32 v200, v199, v165, v247
	v_cndmask_b32_e64 v199, v199, v200, s[22:23]
	v_fma_f32 v221, v127, v199, v177
	v_fma_f32 v220, v126, v221, v176
	v_fma_f32 v219, v125, v220, v175
	v_fma_f32 v218, v124, v219, v174
	v_fma_f32 v217, v123, v218, v173
	v_fma_f32 v216, v122, v217, v172
	v_fma_f32 v215, v121, v216, v171
	v_fma_f32 v214, v120, v215, v170
	ds_read_u16 v206, v197 offset:0
	ds_read_u16 v207, v197 offset:64
	ds_read_u16 v208, v197 offset:128
	ds_read_u16 v209, v197 offset:192
	ds_read_u16 v210, v197 offset:256
	ds_read_u16 v211, v197 offset:320
	ds_read_u16 v212, v197 offset:384
	ds_read_u16 v213, v197 offset:448
	s_waitcnt lgkmcnt(0)
	v_lshlrev_b32_e32 v206, 16, v206
	v_lshlrev_b32_e32 v207, 16, v207
	v_lshlrev_b32_e32 v208, 16, v208
	v_lshlrev_b32_e32 v209, 16, v209
	v_lshlrev_b32_e32 v210, 16, v210
	v_lshlrev_b32_e32 v211, 16, v211
	v_lshlrev_b32_e32 v212, 16, v212
	v_lshlrev_b32_e32 v213, 16, v213
	v_add_f32_e32 v214, v214, v206
	v_add_f32_e32 v215, v215, v207
	v_add_f32_e32 v216, v216, v208
	v_add_f32_e32 v217, v217, v209
	v_add_f32_e32 v218, v218, v210
	v_add_f32_e32 v219, v219, v211
	v_add_f32_e32 v220, v220, v212
	v_add_f32_e32 v221, v221, v213
	v_cvt_pk_bf16_f32 v206, v214, v215
	v_cvt_pk_bf16_f32 v208, v216, v217
	v_cvt_pk_bf16_f32 v210, v218, v219
	v_cvt_pk_bf16_f32 v212, v220, v221
	ds_write_b16 v197, v206 offset:0
	ds_write_b16_d16_hi v197, v206 offset:64
	ds_write_b16 v197, v208 offset:128
	ds_write_b16_d16_hi v197, v208 offset:192
	ds_write_b16 v197, v210 offset:256
	ds_write_b16_d16_hi v197, v210 offset:320
	ds_write_b16 v197, v212 offset:384
	ds_write_b16_d16_hi v197, v212 offset:448
	s_add_i32 s4, s4, 2
.Lrec2_loopB_d1:
	ds_read_b128 v[198:201], v130 offset:0
	ds_read_b128 v[214:217], v130 offset:576
	ds_read_b128 v[202:205], v131 offset:0
	ds_read_b128 v[218:221], v131 offset:576
	ds_read_b128 v[206:209], v130 offset:144
	ds_read_b128 v[222:225], v130 offset:720
	ds_read_b128 v[210:213], v131 offset:144
	s_waitcnt lgkmcnt(14)
	ds_read_b128 v[226:229], v131 offset:720
	s_waitcnt lgkmcnt(4)
	v_mfma_f32_16x16x32_bf16 v[100:103], v[198:201], v[20:23], v[12:15]
	v_mfma_f32_16x16x32_bf16 v[100:103], v[202:205], v[24:27], v[100:103]
	v_mfma_f32_16x16x32_bf16 v[104:107], v[198:201], v[52:55], v[16:19]
	v_mfma_f32_16x16x32_bf16 v[104:107], v[202:205], v[56:59], v[104:107]
	v_mfma_f32_16x16x32_bf16 v[108:111], v[198:201], v[84:87], v[242:245]
	v_mfma_f32_16x16x32_bf16 v[112:115], v[214:217], v[20:23], v[12:15]
	v_mfma_f32_16x16x32_bf16 v[112:115], v[218:221], v[24:27], v[112:115]
	v_mfma_f32_16x16x32_bf16 v[138:141], v[214:217], v[52:55], v[16:19]
	v_mfma_f32_16x16x32_bf16 v[138:141], v[218:221], v[56:59], v[138:141]
	v_mfma_f32_16x16x32_bf16 v[142:145], v[214:217], v[84:87], v[242:245]
	ds_read_b128 v[198:201], v130 offset:288
	ds_read_b128 v[214:217], v130 offset:864
	ds_read_b128 v[202:205], v131 offset:288
	ds_read_b128 v[218:221], v131 offset:864
	s_waitcnt lgkmcnt(4)
	v_mfma_f32_16x16x32_bf16 v[100:103], v[206:209], v[28:31], v[100:103]
	v_mfma_f32_16x16x32_bf16 v[100:103], v[210:213], v[32:35], v[100:103]
	v_mfma_f32_16x16x32_bf16 v[104:107], v[210:213], v[64:67], v[104:107]
	v_mfma_f32_16x16x32_bf16 v[104:107], v[206:209], v[60:63], v[104:107]
	v_mfma_f32_16x16x32_bf16 v[108:111], v[206:209], v[88:91], v[108:111]
	v_mfma_f32_16x16x32_bf16 v[112:115], v[222:225], v[28:31], v[112:115]
	v_mfma_f32_16x16x32_bf16 v[112:115], v[226:229], v[32:35], v[112:115]
	v_mfma_f32_16x16x32_bf16 v[138:141], v[226:229], v[64:67], v[138:141]
	v_mfma_f32_16x16x32_bf16 v[138:141], v[222:225], v[60:63], v[138:141]
	v_mfma_f32_16x16x32_bf16 v[142:145], v[222:225], v[88:91], v[142:145]
	ds_read_b128 v[206:209], v130 offset:432
	ds_read_b128 v[222:225], v130 offset:1008
	ds_read_b128 v[210:213], v131 offset:432
	ds_read_b128 v[226:229], v131 offset:1008
	s_waitcnt lgkmcnt(4)
	v_mfma_f32_16x16x32_bf16 v[100:103], v[198:201], v[36:39], v[100:103]
	v_mfma_f32_16x16x32_bf16 v[100:103], v[202:205], v[40:43], v[100:103]
	v_mfma_f32_16x16x32_bf16 v[104:107], v[202:205], v[72:75], v[104:107]
	v_mfma_f32_16x16x32_bf16 v[104:107], v[198:201], v[68:71], v[104:107]
	v_mfma_f32_16x16x32_bf16 v[108:111], v[198:201], v[92:95], v[108:111]
	v_mfma_f32_16x16x32_bf16 v[112:115], v[214:217], v[36:39], v[112:115]
	v_mfma_f32_16x16x32_bf16 v[112:115], v[218:221], v[40:43], v[112:115]
	v_mfma_f32_16x16x32_bf16 v[138:141], v[218:221], v[72:75], v[138:141]
	v_mfma_f32_16x16x32_bf16 v[138:141], v[214:217], v[68:71], v[138:141]
	v_mfma_f32_16x16x32_bf16 v[142:145], v[214:217], v[92:95], v[142:145]
	s_waitcnt lgkmcnt(0)
	v_mfma_f32_16x16x32_bf16 v[100:103], v[206:209], v[44:47], v[100:103]
	v_mfma_f32_16x16x32_bf16 v[100:103], v[210:213], v[48:51], v[100:103]
	v_mfma_f32_16x16x32_bf16 v[104:107], v[210:213], v[80:83], v[104:107]
	v_mfma_f32_16x16x32_bf16 v[104:107], v[206:209], v[76:79], v[104:107]
	v_mfma_f32_16x16x32_bf16 v[108:111], v[206:209], v[96:99], v[108:111]
	v_mfma_f32_16x16x32_bf16 v[112:115], v[222:225], v[44:47], v[112:115]
	v_mfma_f32_16x16x32_bf16 v[112:115], v[226:229], v[48:51], v[112:115]
	v_mfma_f32_16x16x32_bf16 v[138:141], v[226:229], v[80:83], v[138:141]
	v_mfma_f32_16x16x32_bf16 v[138:141], v[222:225], v[76:79], v[138:141]
	v_mfma_f32_16x16x32_bf16 v[142:145], v[222:225], v[96:99], v[142:145]
	s_waitcnt lgkmcnt(0)
	s_barrier
	s_waitcnt vmcnt(5)
	ds_write_b128 v134, v[146:149]
	ds_write_b128 v134, v[150:153] offset:4608
	ds_write_b128 v135, v[160:163]
	s_add_i32 s64, s4, -1
	s_sub_i32 s64, 31, s64
	s_mul_i32 s71, s64, 0x30000
	s_add_u32 s38, s60, s71
	s_addc_u32 s39, s61, 0
	s_lshl_b32 s64, s64, 12
	v_add_u32_e32 v136, s64, v195
	ds_read_b128 v[116:119], v136
	s_waitcnt vmcnt(3)
	s_waitcnt lgkmcnt(0)
	v_lshlrev_b32_e32 v136, 16, v116
	v_lshlrev_b32_e32 v137, 16, v8
	v_and_b32_e32 v168, 0xffff0000, v116
	v_and_b32_e32 v169, 0xffff0000, v8
	v_mul_f32_e32 v136, v136, v137
	v_mul_f32_e32 v168, v168, v169
	v_cvt_pk_bf16_f32 v116, v136, v168
	v_lshlrev_b32_e32 v136, 16, v117
	v_lshlrev_b32_e32 v137, 16, v9
	v_and_b32_e32 v168, 0xffff0000, v117
	v_and_b32_e32 v169, 0xffff0000, v9
	v_mul_f32_e32 v136, v136, v137
	v_mul_f32_e32 v168, v168, v169
	v_cvt_pk_bf16_f32 v117, v136, v168
	v_lshlrev_b32_e32 v136, 16, v118
	v_lshlrev_b32_e32 v137, 16, v10
	v_and_b32_e32 v168, 0xffff0000, v118
	v_and_b32_e32 v169, 0xffff0000, v10
	v_mul_f32_e32 v136, v136, v137
	v_mul_f32_e32 v168, v168, v169
	v_cvt_pk_bf16_f32 v118, v136, v168
	v_lshlrev_b32_e32 v136, 16, v119
	v_lshlrev_b32_e32 v137, 16, v11
	v_and_b32_e32 v168, 0xffff0000, v119
	v_and_b32_e32 v169, 0xffff0000, v11
	v_mul_f32_e32 v136, v136, v137
	v_mul_f32_e32 v168, v168, v169
	v_cvt_pk_bf16_f32 v119, v136, v168
	global_store_dwordx4 v255, v[116:119], s[38:39]
	s_add_i32 s64, s4, 0
	s_sub_i32 s64, 31, s64
	s_mul_i32 s71, s64, 0x30000
	s_add_u32 s38, s60, s71
	s_addc_u32 s39, s61, 0
	s_lshl_b32 s64, s64, 12
	global_load_dwordx4 v[8:11], v255, s[38:39]
	s_add_i32 s52, s4, 3
	s_min_u32 s52, s52, 31
	s_sub_i32 s52, 31, s52
	s_lshl_b32 s52, s52, 13
	s_add_u32 s26, s50, s52
	s_addc_u32 s27, s51, 0
	global_load_dwordx4 v[146:149], v154, s[26:27]
	global_load_dwordx4 v[150:153], v155, s[26:27]
	global_load_dwordx4 v[160:163], v159, s[26:27]
	v_exp_f32_e32 v198, v100
	v_exp_f32_e32 v199, v101
	v_exp_f32_e32 v200, v102
	v_exp_f32_e32 v201, v103
	v_exp_f32_e32 v202, v112
	v_exp_f32_e32 v203, v113
	v_exp_f32_e32 v204, v114
	v_exp_f32_e32 v205, v115
	v_exp_f32_e32 v214, v104
	v_add_f32_e32 v198, 1.0, v198
	v_exp_f32_e32 v215, v105
	v_add_f32_e32 v199, 1.0, v199
	v_exp_f32_e32 v216, v106
	v_add_f32_e32 v200, 1.0, v200
	v_exp_f32_e32 v217, v107
	v_add_f32_e32 v201, 1.0, v201
	v_exp_f32_e32 v218, v138
	v_add_f32_e32 v202, 1.0, v202
	v_exp_f32_e32 v219, v139
	v_add_f32_e32 v203, 1.0, v203
	v_exp_f32_e32 v220, v140
	v_add_f32_e32 v204, 1.0, v204
	v_exp_f32_e32 v221, v141
	v_add_f32_e32 v205, 1.0, v205
	v_rcp_f32_e32 v198, v198
	v_add_f32_e32 v214, 1.0, v214
	v_rcp_f32_e32 v199, v199
	v_add_f32_e32 v215, 1.0, v215
	v_rcp_f32_e32 v200, v200
	v_add_f32_e32 v216, 1.0, v216
	v_rcp_f32_e32 v201, v201
	v_add_f32_e32 v217, 1.0, v217
	v_rcp_f32_e32 v202, v202
	v_add_f32_e32 v218, 1.0, v218
	v_rcp_f32_e32 v203, v203
	v_add_f32_e32 v219, 1.0, v219
	v_rcp_f32_e32 v204, v204
	v_add_f32_e32 v220, 1.0, v220
	v_rcp_f32_e32 v205, v205
	v_add_f32_e32 v221, 1.0, v221
	v_mul_f32_e32 v198, v179, v198
	v_mul_f32_e32 v199, v179, v199
	v_mul_f32_e32 v200, v179, v200
	v_mul_f32_e32 v201, v179, v201
	v_mul_f32_e32 v202, v179, v202
	v_mul_f32_e32 v203, v179, v203
	v_mul_f32_e32 v204, v179, v204
	v_mul_f32_e32 v205, v179, v205
	v_exp_f32_e32 v120, v198
	v_exp_f32_e32 v121, v199
	v_exp_f32_e32 v122, v200
	v_exp_f32_e32 v123, v201
	v_exp_f32_e32 v124, v202
	v_exp_f32_e32 v125, v203
	v_exp_f32_e32 v126, v204
	v_exp_f32_e32 v127, v205
	v_fma_f32 v206, -v120, v120, 1.0
	v_fma_f32 v207, -v121, v121, 1.0
	v_fma_f32 v208, -v122, v122, 1.0
	v_fma_f32 v209, -v123, v123, 1.0
	v_fma_f32 v210, -v124, v124, 1.0
	v_fma_f32 v211, -v125, v125, 1.0
	v_fma_f32 v212, -v126, v126, 1.0
	v_fma_f32 v213, -v127, v127, 1.0
	v_max_f32_e32 v206, 0xda24260, v206
	v_max_f32_e32 v207, 0xda24260, v207
	v_max_f32_e32 v208, 0xda24260, v208
	v_max_f32_e32 v209, 0xda24260, v209
	v_max_f32_e32 v210, 0xda24260, v210
	v_max_f32_e32 v211, 0xda24260, v211
	v_max_f32_e32 v212, 0xda24260, v212
	v_max_f32_e32 v213, 0xda24260, v213
	v_mul_f32_e32 v198, v214, v206
	v_mul_f32_e32 v199, v215, v207
	v_mul_f32_e32 v200, v216, v208
	v_mul_f32_e32 v201, v217, v209
	v_mul_f32_e32 v202, v218, v210
	v_mul_f32_e32 v203, v219, v211
	v_mul_f32_e32 v204, v220, v212
	v_mul_f32_e32 v205, v221, v213
	v_mul_f32_e32 v214, v214, v198
	v_mul_f32_e32 v215, v215, v199
	v_mul_f32_e32 v216, v216, v200
	v_mul_f32_e32 v217, v217, v201
	v_mul_f32_e32 v218, v218, v202
	v_mul_f32_e32 v219, v219, v203
	v_mul_f32_e32 v220, v220, v204
	v_mul_f32_e32 v221, v221, v205
	v_rsq_f32_e32 v214, v214
	v_mul_f32_e32 v222, v108, v206
	v_rsq_f32_e32 v215, v215
	v_mul_f32_e32 v223, v109, v207
	v_rsq_f32_e32 v216, v216
	v_mul_f32_e32 v224, v110, v208
	v_rsq_f32_e32 v217, v217
	v_mul_f32_e32 v225, v111, v209
	v_rsq_f32_e32 v218, v218
	v_mul_f32_e32 v226, v142, v210
	v_rsq_f32_e32 v219, v219
	v_mul_f32_e32 v227, v143, v211
	v_rsq_f32_e32 v220, v220
	v_mul_f32_e32 v228, v144, v212
	v_rsq_f32_e32 v221, v221
	v_mul_f32_e32 v229, v145, v213
	v_mul_f32_e32 v170, v222, v214
	v_mul_f32_e32 v171, v223, v215
	v_mul_f32_e32 v172, v224, v216
	v_mul_f32_e32 v173, v225, v217
	v_mul_f32_e32 v174, v226, v218
	v_mul_f32_e32 v175, v227, v219
	v_mul_f32_e32 v176, v228, v220
	v_mul_f32_e32 v177, v229, v221
	v_mov_b32_e32 v198, v177
	v_mov_b32_e32 v199, v127
	v_fma_f32 v198, v126, v198, v176
	v_mul_f32_e32 v199, v199, v126
	v_fma_f32 v198, v125, v198, v175
	v_mul_f32_e32 v199, v199, v125
	v_fma_f32 v198, v124, v198, v174
	v_mul_f32_e32 v199, v199, v124
	v_fma_f32 v198, v123, v198, v173
	v_mul_f32_e32 v199, v199, v123
	v_fma_f32 v198, v122, v198, v172
	v_mul_f32_e32 v199, v199, v122
	v_fma_f32 v198, v121, v198, v171
	v_mul_f32_e32 v199, v199, v121
	v_fma_f32 v198, v120, v198, v170
	v_mul_f32_e32 v199, v199, v120
	ds_bpermute_b32 v164, v185, v199 offset:0
	ds_bpermute_b32 v246, v185, v198 offset:0
	ds_bpermute_b32 v165, v185, v199 offset:64
	ds_bpermute_b32 v247, v185, v198 offset:64
	ds_bpermute_b32 v166, v185, v199 offset:128
	ds_bpermute_b32 v248, v185, v198 offset:128
	ds_bpermute_b32 v167, v185, v199 offset:192
	ds_bpermute_b32 v249, v185, v198 offset:192
	s_waitcnt lgkmcnt(0)
	v_mov_b32_e32 v251, v249
	v_mov_b32_e32 v250, v167
	v_fma_f32 v251, v251, v166, v248
	v_mul_f32_e32 v250, v250, v166
	v_fma_f32 v251, v251, v165, v247
	v_mul_f32_e32 v250, v250, v165
	v_fma_f32 v251, v251, v164, v246
	v_mul_f32_e32 v250, v250, v164
	s_mov_b64 exec, s[10:11]
	ds_write_b64 v182, v[250:251] offset:0
	s_mov_b64 exec, -1
	s_waitcnt lgkmcnt(0)
	s_barrier
	ds_read2_b64 v[4:7], v183 offset0:0 offset1:16
	s_add_i32 s52, s4, 0
	s_sub_i32 s52, 31, s52
	s_lshl_b32 s52, s52, 12
	v_add_u32_e32 v197, s52, v184
	s_waitcnt lgkmcnt(0)
	v_fma_f32 v198, v180, v6, v7
	v_cndmask_b32_e64 v199, v180, v198, s[24:25]
	v_fma_f32 v180, v198, v4, v5
	v_fma_f32 v200, v199, v167, v249
	v_cndmask_b32_e64 v199, v199, v200, s[16:17]
	v_fma_f32 v200, v199, v166, v248
	v_cndmask_b32_e64 v199, v199, v200, s[20:21]
	v_fma_f32 v200, v199, v165, v247
	v_cndmask_b32_e64 v199, v199, v200, s[22:23]
	v_fma_f32 v221, v127, v199, v177
	v_fma_f32 v220, v126, v221, v176
	v_fma_f32 v219, v125, v220, v175
	v_fma_f32 v218, v124, v219, v174
	v_fma_f32 v217, v123, v218, v173
	v_fma_f32 v216, v122, v217, v172
	v_fma_f32 v215, v121, v216, v171
	v_fma_f32 v214, v120, v215, v170
	ds_read_u16 v206, v197 offset:0
	ds_read_u16 v207, v197 offset:64
	ds_read_u16 v208, v197 offset:128
	ds_read_u16 v209, v197 offset:192
	ds_read_u16 v210, v197 offset:256
	ds_read_u16 v211, v197 offset:320
	ds_read_u16 v212, v197 offset:384
	ds_read_u16 v213, v197 offset:448
	s_waitcnt lgkmcnt(0)
	v_lshlrev_b32_e32 v206, 16, v206
	v_lshlrev_b32_e32 v207, 16, v207
	v_lshlrev_b32_e32 v208, 16, v208
	v_lshlrev_b32_e32 v209, 16, v209
	v_lshlrev_b32_e32 v210, 16, v210
	v_lshlrev_b32_e32 v211, 16, v211
	v_lshlrev_b32_e32 v212, 16, v212
	v_lshlrev_b32_e32 v213, 16, v213
	v_add_f32_e32 v214, v214, v206
	v_add_f32_e32 v215, v215, v207
	v_add_f32_e32 v216, v216, v208
	v_add_f32_e32 v217, v217, v209
	v_add_f32_e32 v218, v218, v210
	v_add_f32_e32 v219, v219, v211
	v_add_f32_e32 v220, v220, v212
	v_add_f32_e32 v221, v221, v213
	v_cvt_pk_bf16_f32 v206, v214, v215
	v_cvt_pk_bf16_f32 v208, v216, v217
	v_cvt_pk_bf16_f32 v210, v218, v219
	v_cvt_pk_bf16_f32 v212, v220, v221
	ds_write_b16 v197, v206 offset:0
	ds_write_b16_d16_hi v197, v206 offset:64
	ds_write_b16 v197, v208 offset:128
	ds_write_b16_d16_hi v197, v208 offset:192
	ds_write_b16 v197, v210 offset:256
	ds_write_b16_d16_hi v197, v210 offset:320
	ds_write_b16 v197, v212 offset:384
	ds_write_b16_d16_hi v197, v212 offset:448
	ds_read_b128 v[198:201], v130 offset:0
	ds_read_b128 v[214:217], v130 offset:576
	ds_read_b128 v[202:205], v131 offset:0
	ds_read_b128 v[218:221], v131 offset:576
	ds_read_b128 v[206:209], v130 offset:144
	ds_read_b128 v[222:225], v130 offset:720
	ds_read_b128 v[210:213], v131 offset:144
	s_waitcnt lgkmcnt(14)
	ds_read_b128 v[226:229], v131 offset:720
	s_waitcnt lgkmcnt(4)
	v_mfma_f32_16x16x32_bf16 v[100:103], v[198:201], v[20:23], v[12:15]
	v_mfma_f32_16x16x32_bf16 v[100:103], v[202:205], v[24:27], v[100:103]
	v_mfma_f32_16x16x32_bf16 v[104:107], v[198:201], v[52:55], v[16:19]
	v_mfma_f32_16x16x32_bf16 v[104:107], v[202:205], v[56:59], v[104:107]
	v_mfma_f32_16x16x32_bf16 v[108:111], v[198:201], v[84:87], v[242:245]
	v_mfma_f32_16x16x32_bf16 v[112:115], v[214:217], v[20:23], v[12:15]
	v_mfma_f32_16x16x32_bf16 v[112:115], v[218:221], v[24:27], v[112:115]
	v_mfma_f32_16x16x32_bf16 v[138:141], v[214:217], v[52:55], v[16:19]
	v_mfma_f32_16x16x32_bf16 v[138:141], v[218:221], v[56:59], v[138:141]
	v_mfma_f32_16x16x32_bf16 v[142:145], v[214:217], v[84:87], v[242:245]
	ds_read_b128 v[198:201], v130 offset:288
	ds_read_b128 v[214:217], v130 offset:864
	ds_read_b128 v[202:205], v131 offset:288
	ds_read_b128 v[218:221], v131 offset:864
	s_waitcnt lgkmcnt(4)
	v_mfma_f32_16x16x32_bf16 v[100:103], v[206:209], v[28:31], v[100:103]
	v_mfma_f32_16x16x32_bf16 v[100:103], v[210:213], v[32:35], v[100:103]
	v_mfma_f32_16x16x32_bf16 v[104:107], v[210:213], v[64:67], v[104:107]
	v_mfma_f32_16x16x32_bf16 v[104:107], v[206:209], v[60:63], v[104:107]
	v_mfma_f32_16x16x32_bf16 v[108:111], v[206:209], v[88:91], v[108:111]
	v_mfma_f32_16x16x32_bf16 v[112:115], v[222:225], v[28:31], v[112:115]
	v_mfma_f32_16x16x32_bf16 v[112:115], v[226:229], v[32:35], v[112:115]
	v_mfma_f32_16x16x32_bf16 v[138:141], v[226:229], v[64:67], v[138:141]
	v_mfma_f32_16x16x32_bf16 v[138:141], v[222:225], v[60:63], v[138:141]
	v_mfma_f32_16x16x32_bf16 v[142:145], v[222:225], v[88:91], v[142:145]
	ds_read_b128 v[206:209], v130 offset:432
	ds_read_b128 v[222:225], v130 offset:1008
	ds_read_b128 v[210:213], v131 offset:432
	ds_read_b128 v[226:229], v131 offset:1008
	s_waitcnt lgkmcnt(4)
	v_mfma_f32_16x16x32_bf16 v[100:103], v[198:201], v[36:39], v[100:103]
	v_mfma_f32_16x16x32_bf16 v[100:103], v[202:205], v[40:43], v[100:103]
	v_mfma_f32_16x16x32_bf16 v[104:107], v[202:205], v[72:75], v[104:107]
	v_mfma_f32_16x16x32_bf16 v[104:107], v[198:201], v[68:71], v[104:107]
	v_mfma_f32_16x16x32_bf16 v[108:111], v[198:201], v[92:95], v[108:111]
	v_mfma_f32_16x16x32_bf16 v[112:115], v[214:217], v[36:39], v[112:115]
	v_mfma_f32_16x16x32_bf16 v[112:115], v[218:221], v[40:43], v[112:115]
	v_mfma_f32_16x16x32_bf16 v[138:141], v[218:221], v[72:75], v[138:141]
	v_mfma_f32_16x16x32_bf16 v[138:141], v[214:217], v[68:71], v[138:141]
	v_mfma_f32_16x16x32_bf16 v[142:145], v[214:217], v[92:95], v[142:145]
	s_waitcnt lgkmcnt(0)
	v_mfma_f32_16x16x32_bf16 v[100:103], v[206:209], v[44:47], v[100:103]
	v_mfma_f32_16x16x32_bf16 v[100:103], v[210:213], v[48:51], v[100:103]
	v_mfma_f32_16x16x32_bf16 v[104:107], v[210:213], v[80:83], v[104:107]
	v_mfma_f32_16x16x32_bf16 v[104:107], v[206:209], v[76:79], v[104:107]
	v_mfma_f32_16x16x32_bf16 v[108:111], v[206:209], v[96:99], v[108:111]
	v_mfma_f32_16x16x32_bf16 v[112:115], v[222:225], v[44:47], v[112:115]
	v_mfma_f32_16x16x32_bf16 v[112:115], v[226:229], v[48:51], v[112:115]
	v_mfma_f32_16x16x32_bf16 v[138:141], v[226:229], v[80:83], v[138:141]
	v_mfma_f32_16x16x32_bf16 v[138:141], v[222:225], v[76:79], v[138:141]
	v_mfma_f32_16x16x32_bf16 v[142:145], v[222:225], v[96:99], v[142:145]
	s_waitcnt lgkmcnt(0)
	s_barrier
	s_waitcnt vmcnt(5)
	ds_write_b128 v134, v[230:233]
	ds_write_b128 v134, v[234:237] offset:4608
	ds_write_b128 v135, v[238:241]
	s_add_i32 s64, s4, 0
	s_sub_i32 s64, 31, s64
	s_mul_i32 s71, s64, 0x30000
	s_add_u32 s38, s60, s71
	s_addc_u32 s39, s61, 0
	s_lshl_b32 s64, s64, 12
	v_add_u32_e32 v136, s64, v195
	ds_read_b128 v[116:119], v136
	s_waitcnt vmcnt(3)
	s_waitcnt lgkmcnt(0)
	v_lshlrev_b32_e32 v136, 16, v116
	v_lshlrev_b32_e32 v137, 16, v8
	v_and_b32_e32 v168, 0xffff0000, v116
	v_and_b32_e32 v169, 0xffff0000, v8
	v_mul_f32_e32 v136, v136, v137
	v_mul_f32_e32 v168, v168, v169
	v_cvt_pk_bf16_f32 v116, v136, v168
	v_lshlrev_b32_e32 v136, 16, v117
	v_lshlrev_b32_e32 v137, 16, v9
	v_and_b32_e32 v168, 0xffff0000, v117
	v_and_b32_e32 v169, 0xffff0000, v9
	v_mul_f32_e32 v136, v136, v137
	v_mul_f32_e32 v168, v168, v169
	v_cvt_pk_bf16_f32 v117, v136, v168
	v_lshlrev_b32_e32 v136, 16, v118
	v_lshlrev_b32_e32 v137, 16, v10
	v_and_b32_e32 v168, 0xffff0000, v118
	v_and_b32_e32 v169, 0xffff0000, v10
	v_mul_f32_e32 v136, v136, v137
	v_mul_f32_e32 v168, v168, v169
	v_cvt_pk_bf16_f32 v118, v136, v168
	v_lshlrev_b32_e32 v136, 16, v119
	v_lshlrev_b32_e32 v137, 16, v11
	v_and_b32_e32 v168, 0xffff0000, v119
	v_and_b32_e32 v169, 0xffff0000, v11
	v_mul_f32_e32 v136, v136, v137
	v_mul_f32_e32 v168, v168, v169
	v_cvt_pk_bf16_f32 v119, v136, v168
	global_store_dwordx4 v255, v[116:119], s[38:39]
	s_add_i32 s64, s4, 1
	s_sub_i32 s64, 31, s64
	s_mul_i32 s71, s64, 0x30000
	s_add_u32 s38, s60, s71
	s_addc_u32 s39, s61, 0
	s_lshl_b32 s64, s64, 12
	global_load_dwordx4 v[8:11], v255, s[38:39]
	s_add_i32 s52, s4, 4
	s_min_u32 s52, s52, 31
	s_sub_i32 s52, 31, s52
	s_lshl_b32 s52, s52, 13
	s_add_u32 s26, s50, s52
	s_addc_u32 s27, s51, 0
	global_load_dwordx4 v[230:233], v154, s[26:27]
	global_load_dwordx4 v[234:237], v155, s[26:27]
	global_load_dwordx4 v[238:241], v159, s[26:27]
	v_exp_f32_e32 v198, v100
	v_exp_f32_e32 v199, v101
	v_exp_f32_e32 v200, v102
	v_exp_f32_e32 v201, v103
	v_exp_f32_e32 v202, v112
	v_exp_f32_e32 v203, v113
	v_exp_f32_e32 v204, v114
	v_exp_f32_e32 v205, v115
	v_exp_f32_e32 v214, v104
	v_add_f32_e32 v198, 1.0, v198
	v_exp_f32_e32 v215, v105
	v_add_f32_e32 v199, 1.0, v199
	v_exp_f32_e32 v216, v106
	v_add_f32_e32 v200, 1.0, v200
	v_exp_f32_e32 v217, v107
	v_add_f32_e32 v201, 1.0, v201
	v_exp_f32_e32 v218, v138
	v_add_f32_e32 v202, 1.0, v202
	v_exp_f32_e32 v219, v139
	v_add_f32_e32 v203, 1.0, v203
	v_exp_f32_e32 v220, v140
	v_add_f32_e32 v204, 1.0, v204
	v_exp_f32_e32 v221, v141
	v_add_f32_e32 v205, 1.0, v205
	v_rcp_f32_e32 v198, v198
	v_add_f32_e32 v214, 1.0, v214
	v_rcp_f32_e32 v199, v199
	v_add_f32_e32 v215, 1.0, v215
	v_rcp_f32_e32 v200, v200
	v_add_f32_e32 v216, 1.0, v216
	v_rcp_f32_e32 v201, v201
	v_add_f32_e32 v217, 1.0, v217
	v_rcp_f32_e32 v202, v202
	v_add_f32_e32 v218, 1.0, v218
	v_rcp_f32_e32 v203, v203
	v_add_f32_e32 v219, 1.0, v219
	v_rcp_f32_e32 v204, v204
	v_add_f32_e32 v220, 1.0, v220
	v_rcp_f32_e32 v205, v205
	v_add_f32_e32 v221, 1.0, v221
	v_mul_f32_e32 v198, v179, v198
	v_mul_f32_e32 v199, v179, v199
	v_mul_f32_e32 v200, v179, v200
	v_mul_f32_e32 v201, v179, v201
	v_mul_f32_e32 v202, v179, v202
	v_mul_f32_e32 v203, v179, v203
	v_mul_f32_e32 v204, v179, v204
	v_mul_f32_e32 v205, v179, v205
	v_exp_f32_e32 v120, v198
	v_exp_f32_e32 v121, v199
	v_exp_f32_e32 v122, v200
	v_exp_f32_e32 v123, v201
	v_exp_f32_e32 v124, v202
	v_exp_f32_e32 v125, v203
	v_exp_f32_e32 v126, v204
	v_exp_f32_e32 v127, v205
	v_fma_f32 v206, -v120, v120, 1.0
	v_fma_f32 v207, -v121, v121, 1.0
	v_fma_f32 v208, -v122, v122, 1.0
	v_fma_f32 v209, -v123, v123, 1.0
	v_fma_f32 v210, -v124, v124, 1.0
	v_fma_f32 v211, -v125, v125, 1.0
	v_fma_f32 v212, -v126, v126, 1.0
	v_fma_f32 v213, -v127, v127, 1.0
	v_max_f32_e32 v206, 0xda24260, v206
	v_max_f32_e32 v207, 0xda24260, v207
	v_max_f32_e32 v208, 0xda24260, v208
	v_max_f32_e32 v209, 0xda24260, v209
	v_max_f32_e32 v210, 0xda24260, v210
	v_max_f32_e32 v211, 0xda24260, v211
	v_max_f32_e32 v212, 0xda24260, v212
	v_max_f32_e32 v213, 0xda24260, v213
	v_mul_f32_e32 v198, v214, v206
	v_mul_f32_e32 v199, v215, v207
	v_mul_f32_e32 v200, v216, v208
	v_mul_f32_e32 v201, v217, v209
	v_mul_f32_e32 v202, v218, v210
	v_mul_f32_e32 v203, v219, v211
	v_mul_f32_e32 v204, v220, v212
	v_mul_f32_e32 v205, v221, v213
	v_mul_f32_e32 v214, v214, v198
	v_mul_f32_e32 v215, v215, v199
	v_mul_f32_e32 v216, v216, v200
	v_mul_f32_e32 v217, v217, v201
	v_mul_f32_e32 v218, v218, v202
	v_mul_f32_e32 v219, v219, v203
	v_mul_f32_e32 v220, v220, v204
	v_mul_f32_e32 v221, v221, v205
	v_rsq_f32_e32 v214, v214
	v_mul_f32_e32 v222, v108, v206
	v_rsq_f32_e32 v215, v215
	v_mul_f32_e32 v223, v109, v207
	v_rsq_f32_e32 v216, v216
	v_mul_f32_e32 v224, v110, v208
	v_rsq_f32_e32 v217, v217
	v_mul_f32_e32 v225, v111, v209
	v_rsq_f32_e32 v218, v218
	v_mul_f32_e32 v226, v142, v210
	v_rsq_f32_e32 v219, v219
	v_mul_f32_e32 v227, v143, v211
	v_rsq_f32_e32 v220, v220
	v_mul_f32_e32 v228, v144, v212
	v_rsq_f32_e32 v221, v221
	v_mul_f32_e32 v229, v145, v213
	v_mul_f32_e32 v170, v222, v214
	v_mul_f32_e32 v171, v223, v215
	v_mul_f32_e32 v172, v224, v216
	v_mul_f32_e32 v173, v225, v217
	v_mul_f32_e32 v174, v226, v218
	v_mul_f32_e32 v175, v227, v219
	v_mul_f32_e32 v176, v228, v220
	v_mul_f32_e32 v177, v229, v221
	v_mov_b32_e32 v198, v177
	v_mov_b32_e32 v199, v127
	v_fma_f32 v198, v126, v198, v176
	v_mul_f32_e32 v199, v199, v126
	v_fma_f32 v198, v125, v198, v175
	v_mul_f32_e32 v199, v199, v125
	v_fma_f32 v198, v124, v198, v174
	v_mul_f32_e32 v199, v199, v124
	v_fma_f32 v198, v123, v198, v173
	v_mul_f32_e32 v199, v199, v123
	v_fma_f32 v198, v122, v198, v172
	v_mul_f32_e32 v199, v199, v122
	v_fma_f32 v198, v121, v198, v171
	v_mul_f32_e32 v199, v199, v121
	v_fma_f32 v198, v120, v198, v170
	v_mul_f32_e32 v199, v199, v120
	ds_bpermute_b32 v164, v185, v199 offset:0
	ds_bpermute_b32 v246, v185, v198 offset:0
	ds_bpermute_b32 v165, v185, v199 offset:64
	ds_bpermute_b32 v247, v185, v198 offset:64
	ds_bpermute_b32 v166, v185, v199 offset:128
	ds_bpermute_b32 v248, v185, v198 offset:128
	ds_bpermute_b32 v167, v185, v199 offset:192
	ds_bpermute_b32 v249, v185, v198 offset:192
	s_waitcnt lgkmcnt(0)
	v_mov_b32_e32 v251, v249
	v_mov_b32_e32 v250, v167
	v_fma_f32 v251, v251, v166, v248
	v_mul_f32_e32 v250, v250, v166
	v_fma_f32 v251, v251, v165, v247
	v_mul_f32_e32 v250, v250, v165
	v_fma_f32 v251, v251, v164, v246
	v_mul_f32_e32 v250, v250, v164
	s_mov_b64 exec, s[10:11]
	ds_write_b64 v182, v[250:251] offset:1024
	s_mov_b64 exec, -1
	s_waitcnt lgkmcnt(0)
	s_barrier
	ds_read2_b64 v[4:7], v183 offset0:128 offset1:144
	s_add_i32 s52, s4, 1
	s_sub_i32 s52, 31, s52
	s_lshl_b32 s52, s52, 12
	v_add_u32_e32 v197, s52, v184
	s_waitcnt lgkmcnt(0)
	v_fma_f32 v198, v180, v6, v7
	v_cndmask_b32_e64 v199, v180, v198, s[24:25]
	v_fma_f32 v180, v198, v4, v5
	v_fma_f32 v200, v199, v167, v249
	v_cndmask_b32_e64 v199, v199, v200, s[16:17]
	v_fma_f32 v200, v199, v166, v248
	v_cndmask_b32_e64 v199, v199, v200, s[20:21]
	v_fma_f32 v200, v199, v165, v247
	v_cndmask_b32_e64 v199, v199, v200, s[22:23]
	v_fma_f32 v221, v127, v199, v177
	v_fma_f32 v220, v126, v221, v176
	v_fma_f32 v219, v125, v220, v175
	v_fma_f32 v218, v124, v219, v174
	v_fma_f32 v217, v123, v218, v173
	v_fma_f32 v216, v122, v217, v172
	v_fma_f32 v215, v121, v216, v171
	v_fma_f32 v214, v120, v215, v170
	ds_read_u16 v206, v197 offset:0
	ds_read_u16 v207, v197 offset:64
	ds_read_u16 v208, v197 offset:128
	ds_read_u16 v209, v197 offset:192
	ds_read_u16 v210, v197 offset:256
	ds_read_u16 v211, v197 offset:320
	ds_read_u16 v212, v197 offset:384
	ds_read_u16 v213, v197 offset:448
	s_waitcnt lgkmcnt(0)
	v_lshlrev_b32_e32 v206, 16, v206
	v_lshlrev_b32_e32 v207, 16, v207
	v_lshlrev_b32_e32 v208, 16, v208
	v_lshlrev_b32_e32 v209, 16, v209
	v_lshlrev_b32_e32 v210, 16, v210
	v_lshlrev_b32_e32 v211, 16, v211
	v_lshlrev_b32_e32 v212, 16, v212
	v_lshlrev_b32_e32 v213, 16, v213
	v_add_f32_e32 v214, v214, v206
	v_add_f32_e32 v215, v215, v207
	v_add_f32_e32 v216, v216, v208
	v_add_f32_e32 v217, v217, v209
	v_add_f32_e32 v218, v218, v210
	v_add_f32_e32 v219, v219, v211
	v_add_f32_e32 v220, v220, v212
	v_add_f32_e32 v221, v221, v213
	v_cvt_pk_bf16_f32 v206, v214, v215
	v_cvt_pk_bf16_f32 v208, v216, v217
	v_cvt_pk_bf16_f32 v210, v218, v219
	v_cvt_pk_bf16_f32 v212, v220, v221
	ds_write_b16 v197, v206 offset:0
	ds_write_b16_d16_hi v197, v206 offset:64
	ds_write_b16 v197, v208 offset:128
	ds_write_b16_d16_hi v197, v208 offset:192
	ds_write_b16 v197, v210 offset:256
	ds_write_b16_d16_hi v197, v210 offset:320
	ds_write_b16 v197, v212 offset:384
	ds_write_b16_d16_hi v197, v212 offset:448
	s_add_i32 s4, s4, 2
	s_cmp_lt_u32 s4, 32
	s_cbranch_scc1 .Lrec2_loopB_d1
	s_waitcnt lgkmcnt(0)
	s_barrier
	s_add_i32 s64, s4, -1
	s_sub_i32 s64, 31, s64
	s_mul_i32 s71, s64, 0x30000
	s_add_u32 s38, s60, s71
	s_addc_u32 s39, s61, 0
	s_lshl_b32 s64, s64, 12
	v_add_u32_e32 v136, s64, v195
	ds_read_b128 v[116:119], v136
	s_waitcnt vmcnt(3)
	s_waitcnt lgkmcnt(0)
	v_lshlrev_b32_e32 v136, 16, v116
	v_lshlrev_b32_e32 v137, 16, v8
	v_and_b32_e32 v168, 0xffff0000, v116
	v_and_b32_e32 v169, 0xffff0000, v8
	v_mul_f32_e32 v136, v136, v137
	v_mul_f32_e32 v168, v168, v169
	v_cvt_pk_bf16_f32 v116, v136, v168
	v_lshlrev_b32_e32 v136, 16, v117
	v_lshlrev_b32_e32 v137, 16, v9
	v_and_b32_e32 v168, 0xffff0000, v117
	v_and_b32_e32 v169, 0xffff0000, v9
	v_mul_f32_e32 v136, v136, v137
	v_mul_f32_e32 v168, v168, v169
	v_cvt_pk_bf16_f32 v117, v136, v168
	v_lshlrev_b32_e32 v136, 16, v118
	v_lshlrev_b32_e32 v137, 16, v10
	v_and_b32_e32 v168, 0xffff0000, v118
	v_and_b32_e32 v169, 0xffff0000, v10
	v_mul_f32_e32 v136, v136, v137
	v_mul_f32_e32 v168, v168, v169
	v_cvt_pk_bf16_f32 v118, v136, v168
	v_lshlrev_b32_e32 v136, 16, v119
	v_lshlrev_b32_e32 v137, 16, v11
	v_and_b32_e32 v168, 0xffff0000, v119
	v_and_b32_e32 v169, 0xffff0000, v11
	v_mul_f32_e32 v136, v136, v137
	v_mul_f32_e32 v168, v168, v169
	v_cvt_pk_bf16_f32 v119, v136, v168
	global_store_dwordx4 v255, v[116:119], s[38:39]
